# GEMM loops: accumulate-chain MFMA pairs ordered so four consecutive pairs share the same srcA fragment
# speedup vs baseline: 1.0387x; 1.0036x over previous
.LBB0_252:
	s_add_u32 s0, s0, 0x80
	s_addc_u32 s1, s1, 0
	s_add_u32 s47, s4, 0x100
	s_addc_u32 s48, s5, 0
	s_mov_b32 s4, 0
	s_waitcnt lgkmcnt(0)
	s_waitcnt vmcnt(0)
	s_add_i32 s49, s4, 2
	s_add_u32 s16, s0, 0x80
	s_addc_u32 s5, s1, 0
	s_add_i32 s65, 0, 0x10000
	ds_read_b128 v[148:151], v248
	ds_read_b128 v[152:155], v248 offset:1024
	ds_read_b128 v[156:159], v248 offset:2048
	ds_read_b128 v[160:163], v248 offset:3072
	s_cmp_eq_u32 s41, s4
	s_cselect_b32 s4, s10, s16
	s_cselect_b32 s5, s11, s5
	s_cselect_b32 s17, s13, s48
	s_cselect_b32 s16, s12, s47
	s_add_i32 m0, s26, 0xc000
	ds_read_b128 v[164:167], v146
	ds_read_b128 v[168:171], v146 offset:1024
	ds_read_b128 v[172:175], v146 offset:2048
	ds_read_b128 v[176:179], v146 offset:3072
	ds_read_b128 v[180:183], v146 offset:4096
	ds_read_b128 v[204:207], v146 offset:5120
	ds_read_b128 v[208:211], v146 offset:6144
	ds_read_b128 v[212:215], v146 offset:7168
	global_load_lds_dwordx4 v138, s[0:1]
	s_add_i32 m0, s26, 0xe000
	s_nop 0
	global_load_lds_dwordx4 v140, s[0:1]
	s_waitcnt lgkmcnt(8)
	s_barrier
	s_waitcnt lgkmcnt(0)
	v_mfma_f32_16x16x32_bf16 v[126:129], v[148:151], v[164:167], 0
	v_mfma_f32_16x16x32_bf16 v[126:129], v[152:155], v[168:171], v[126:129]
	v_mfma_f32_16x16x32_bf16 v[110:113], v[148:151], v[172:175], 0
	v_mfma_f32_16x16x32_bf16 v[110:113], v[152:155], v[176:179], v[110:113]
	v_mfma_f32_16x16x32_bf16 v[94:97], v[148:151], v[180:183], 0
	v_mfma_f32_16x16x32_bf16 v[94:97], v[152:155], v[204:207], v[94:97]
	v_mfma_f32_16x16x32_bf16 v[78:81], v[148:151], v[208:211], 0
	v_mfma_f32_16x16x32_bf16 v[78:81], v[152:155], v[212:215], v[78:81]
	v_mfma_f32_16x16x32_bf16 v[122:125], v[156:159], v[164:167], 0
	v_mfma_f32_16x16x32_bf16 v[122:125], v[160:163], v[168:171], v[122:125]
	v_mfma_f32_16x16x32_bf16 v[106:109], v[156:159], v[172:175], 0
	v_mfma_f32_16x16x32_bf16 v[106:109], v[160:163], v[176:179], v[106:109]
	v_mfma_f32_16x16x32_bf16 v[90:93], v[156:159], v[180:183], 0
	v_mfma_f32_16x16x32_bf16 v[90:93], v[160:163], v[204:207], v[90:93]
	v_mfma_f32_16x16x32_bf16 v[74:77], v[156:159], v[208:211], 0
	v_mfma_f32_16x16x32_bf16 v[74:77], v[160:163], v[212:215], v[74:77]
	s_barrier
	s_add_i32 s66, 0, 0x14000
	s_add_i32 s65, s65, s24
	ds_read_b128 v[216:219], v248 offset:16384
	ds_read_b128 v[220:223], v248 offset:17408
	ds_read_b128 v[224:227], v248 offset:18432
	ds_read_b128 v[228:231], v248 offset:19456
	s_add_u32 s70, s16, s6
	s_addc_u32 s71, s17, s7
	s_mov_b32 m0, s65
	s_nop 0
	global_load_lds_dwordx4 v132, s[16:17]
	s_add_i32 m0, s65, 0x2000
	s_nop 0
	global_load_lds_dwordx4 v136, s[16:17]
	s_barrier
	s_waitcnt lgkmcnt(0)
	v_mfma_f32_16x16x32_bf16 v[114:117], v[216:219], v[164:167], 0
	v_mfma_f32_16x16x32_bf16 v[114:117], v[220:223], v[168:171], v[114:117]
	v_mfma_f32_16x16x32_bf16 v[98:101], v[216:219], v[172:175], 0
	v_mfma_f32_16x16x32_bf16 v[98:101], v[220:223], v[176:179], v[98:101]
	v_mfma_f32_16x16x32_bf16 v[82:85], v[216:219], v[180:183], 0
	v_mfma_f32_16x16x32_bf16 v[82:85], v[220:223], v[204:207], v[82:85]
	v_mfma_f32_16x16x32_bf16 v[66:69], v[216:219], v[208:211], 0
	v_mfma_f32_16x16x32_bf16 v[66:69], v[220:223], v[212:215], v[66:69]
	v_mfma_f32_16x16x32_bf16 v[118:121], v[224:227], v[164:167], 0
	v_mfma_f32_16x16x32_bf16 v[118:121], v[228:231], v[168:171], v[118:121]
	v_mfma_f32_16x16x32_bf16 v[102:105], v[224:227], v[172:175], 0
	v_mfma_f32_16x16x32_bf16 v[102:105], v[228:231], v[176:179], v[102:105]
	v_mfma_f32_16x16x32_bf16 v[86:89], v[224:227], v[180:183], 0
	v_mfma_f32_16x16x32_bf16 v[86:89], v[228:231], v[204:207], v[86:89]
	v_mfma_f32_16x16x32_bf16 v[70:73], v[224:227], v[208:211], 0
	v_mfma_f32_16x16x32_bf16 v[70:73], v[228:231], v[212:215], v[70:73]
	s_barrier
	s_mov_b32 m0, s26
	s_add_u32 s72, s4, s6
	s_addc_u32 s73, s5, s7
	ds_read_b128 v[164:167], v146 offset:16384
	ds_read_b128 v[168:171], v146 offset:17408
	ds_read_b128 v[172:175], v146 offset:18432
	ds_read_b128 v[176:179], v146 offset:19456
	ds_read_b128 v[180:183], v146 offset:20480
	ds_read_b128 v[204:207], v146 offset:21504
	ds_read_b128 v[208:211], v146 offset:22528
	ds_read_b128 v[212:215], v146 offset:23552
	global_load_lds_dwordx4 v130, s[4:5]
	s_mov_b32 m0, s27
	s_nop 0
	global_load_lds_dwordx4 v134, s[4:5]
	s_barrier
	s_waitcnt lgkmcnt(0)
	v_mfma_f32_16x16x32_bf16 v[62:65], v[148:151], v[164:167], 0
	v_mfma_f32_16x16x32_bf16 v[62:65], v[152:155], v[168:171], v[62:65]
	v_mfma_f32_16x16x32_bf16 v[46:49], v[148:151], v[172:175], 0
	v_mfma_f32_16x16x32_bf16 v[46:49], v[152:155], v[176:179], v[46:49]
	v_mfma_f32_16x16x32_bf16 v[30:33], v[148:151], v[180:183], 0
	v_mfma_f32_16x16x32_bf16 v[30:33], v[152:155], v[204:207], v[30:33]
	v_mfma_f32_16x16x32_bf16 v[14:17], v[148:151], v[208:211], 0
	v_mfma_f32_16x16x32_bf16 v[14:17], v[152:155], v[212:215], v[14:17]
	v_mfma_f32_16x16x32_bf16 v[58:61], v[156:159], v[164:167], 0
	v_mfma_f32_16x16x32_bf16 v[58:61], v[160:163], v[168:171], v[58:61]
	v_mfma_f32_16x16x32_bf16 v[42:45], v[156:159], v[172:175], 0
	v_mfma_f32_16x16x32_bf16 v[42:45], v[160:163], v[176:179], v[42:45]
	v_mfma_f32_16x16x32_bf16 v[26:29], v[156:159], v[180:183], 0
	v_mfma_f32_16x16x32_bf16 v[26:29], v[160:163], v[204:207], v[26:29]
	v_mfma_f32_16x16x32_bf16 v[10:13], v[156:159], v[208:211], 0
	v_mfma_f32_16x16x32_bf16 v[10:13], v[160:163], v[212:215], v[10:13]
	s_barrier
	s_add_u32 s16, s16, s92
	s_addc_u32 s17, s17, 0
	s_add_i32 s65, s66, s24
	s_add_u32 s76, s16, s6
	s_addc_u32 s77, s17, s7
	s_mov_b32 m0, s65
	s_nop 0
	global_load_lds_dwordx4 v132, s[16:17]
	s_add_i32 m0, s65, 0x2000
	s_nop 0
	global_load_lds_dwordx4 v136, s[16:17]
	s_waitcnt vmcnt(6)
	s_barrier
	v_mfma_f32_16x16x32_bf16 v[50:53], v[216:219], v[164:167], 0
	v_mfma_f32_16x16x32_bf16 v[50:53], v[220:223], v[168:171], v[50:53]
	v_mfma_f32_16x16x32_bf16 v[34:37], v[216:219], v[172:175], 0
	v_mfma_f32_16x16x32_bf16 v[34:37], v[220:223], v[176:179], v[34:37]
	v_mfma_f32_16x16x32_bf16 v[18:21], v[216:219], v[180:183], 0
	v_mfma_f32_16x16x32_bf16 v[18:21], v[220:223], v[204:207], v[18:21]
	v_mfma_f32_16x16x32_bf16 v[6:9], v[216:219], v[208:211], 0
	v_mfma_f32_16x16x32_bf16 v[6:9], v[220:223], v[212:215], v[6:9]
	v_mfma_f32_16x16x32_bf16 v[54:57], v[224:227], v[164:167], 0
	v_mfma_f32_16x16x32_bf16 v[54:57], v[228:231], v[168:171], v[54:57]
	v_mfma_f32_16x16x32_bf16 v[38:41], v[224:227], v[172:175], 0
	v_mfma_f32_16x16x32_bf16 v[38:41], v[228:231], v[176:179], v[38:41]
	v_mfma_f32_16x16x32_bf16 v[22:25], v[224:227], v[180:183], 0
	v_mfma_f32_16x16x32_bf16 v[22:25], v[228:231], v[204:207], v[22:25]
	v_mfma_f32_16x16x32_bf16 v[2:5], v[224:227], v[208:211], 0
	v_mfma_f32_16x16x32_bf16 v[2:5], v[228:231], v[212:215], v[2:5]
	s_barrier
	s_add_i32 s16, 0, 0x18000
	ds_read_b128 v[148:151], v248 offset:32768
	ds_read_b128 v[152:155], v248 offset:33792
	ds_read_b128 v[156:159], v248 offset:34816
	ds_read_b128 v[160:163], v248 offset:35840
	s_add_u32 s4, s4, s92
	s_addc_u32 s5, s5, 0
	s_mov_b32 m0, s28
	ds_read_b128 v[164:167], v146 offset:32768
	ds_read_b128 v[168:171], v146 offset:33792
	ds_read_b128 v[172:175], v146 offset:34816
	ds_read_b128 v[176:179], v146 offset:35840
	ds_read_b128 v[180:183], v146 offset:36864
	ds_read_b128 v[204:207], v146 offset:37888
	ds_read_b128 v[208:211], v146 offset:38912
	ds_read_b128 v[212:215], v146 offset:39936
	global_load_lds_dwordx4 v130, s[4:5]
	s_mov_b32 m0, s29
	s_nop 0
	global_load_lds_dwordx4 v134, s[4:5]
	s_waitcnt lgkmcnt(8)
	s_barrier
	s_waitcnt lgkmcnt(0)
	v_mfma_f32_16x16x32_bf16 v[126:129], v[148:151], v[164:167], v[126:129]
	v_mfma_f32_16x16x32_bf16 v[126:129], v[152:155], v[168:171], v[126:129]
	v_mfma_f32_16x16x32_bf16 v[110:113], v[148:151], v[172:175], v[110:113]
	v_mfma_f32_16x16x32_bf16 v[110:113], v[152:155], v[176:179], v[110:113]
	v_mfma_f32_16x16x32_bf16 v[94:97], v[148:151], v[180:183], v[94:97]
	v_mfma_f32_16x16x32_bf16 v[94:97], v[152:155], v[204:207], v[94:97]
	v_mfma_f32_16x16x32_bf16 v[78:81], v[148:151], v[208:211], v[78:81]
	v_mfma_f32_16x16x32_bf16 v[78:81], v[152:155], v[212:215], v[78:81]
	v_mfma_f32_16x16x32_bf16 v[122:125], v[156:159], v[164:167], v[122:125]
	v_mfma_f32_16x16x32_bf16 v[122:125], v[160:163], v[168:171], v[122:125]
	v_mfma_f32_16x16x32_bf16 v[106:109], v[156:159], v[172:175], v[106:109]
	v_mfma_f32_16x16x32_bf16 v[106:109], v[160:163], v[176:179], v[106:109]
	v_mfma_f32_16x16x32_bf16 v[90:93], v[156:159], v[180:183], v[90:93]
	v_mfma_f32_16x16x32_bf16 v[90:93], v[160:163], v[204:207], v[90:93]
	v_mfma_f32_16x16x32_bf16 v[74:77], v[156:159], v[208:211], v[74:77]
	v_mfma_f32_16x16x32_bf16 v[74:77], v[160:163], v[212:215], v[74:77]
	s_barrier
	s_add_i32 s4, 0, 0x1c000
	s_add_i32 s5, s16, s24
	s_mov_b32 m0, s5
	ds_read_b128 v[216:219], v248 offset:49152
	ds_read_b128 v[220:223], v248 offset:50176
	ds_read_b128 v[224:227], v248 offset:51200
	ds_read_b128 v[228:231], v248 offset:52224
	global_load_lds_dwordx4 v132, s[70:71]
	s_add_i32 m0, s5, 0x2000
	s_nop 0
	global_load_lds_dwordx4 v136, s[70:71]
	s_barrier
	s_waitcnt lgkmcnt(0)
	v_mfma_f32_16x16x32_bf16 v[114:117], v[216:219], v[164:167], v[114:117]
	v_mfma_f32_16x16x32_bf16 v[114:117], v[220:223], v[168:171], v[114:117]
	v_mfma_f32_16x16x32_bf16 v[98:101], v[216:219], v[172:175], v[98:101]
	v_mfma_f32_16x16x32_bf16 v[98:101], v[220:223], v[176:179], v[98:101]
	v_mfma_f32_16x16x32_bf16 v[82:85], v[216:219], v[180:183], v[82:85]
	v_mfma_f32_16x16x32_bf16 v[82:85], v[220:223], v[204:207], v[82:85]
	v_mfma_f32_16x16x32_bf16 v[66:69], v[216:219], v[208:211], v[66:69]
	v_mfma_f32_16x16x32_bf16 v[66:69], v[220:223], v[212:215], v[66:69]
	v_mfma_f32_16x16x32_bf16 v[118:121], v[224:227], v[164:167], v[118:121]
	v_mfma_f32_16x16x32_bf16 v[118:121], v[228:231], v[168:171], v[118:121]
	v_mfma_f32_16x16x32_bf16 v[102:105], v[224:227], v[172:175], v[102:105]
	v_mfma_f32_16x16x32_bf16 v[102:105], v[228:231], v[176:179], v[102:105]
	v_mfma_f32_16x16x32_bf16 v[86:89], v[224:227], v[180:183], v[86:89]
	v_mfma_f32_16x16x32_bf16 v[86:89], v[228:231], v[204:207], v[86:89]
	v_mfma_f32_16x16x32_bf16 v[70:73], v[224:227], v[208:211], v[70:73]
	v_mfma_f32_16x16x32_bf16 v[70:73], v[228:231], v[212:215], v[70:73]
	s_barrier
	s_mov_b32 m0, s35
	ds_read_b128 v[164:167], v146 offset:49152
	ds_read_b128 v[168:171], v146 offset:50176
	ds_read_b128 v[172:175], v146 offset:51200
	ds_read_b128 v[176:179], v146 offset:52224
	ds_read_b128 v[180:183], v146 offset:53248
	ds_read_b128 v[204:207], v146 offset:54272
	ds_read_b128 v[208:211], v146 offset:55296
	ds_read_b128 v[212:215], v146 offset:56320
	global_load_lds_dwordx4 v130, s[72:73]
	s_mov_b32 m0, s40
	s_nop 0
	global_load_lds_dwordx4 v134, s[72:73]
	s_barrier
	s_waitcnt lgkmcnt(0)
	v_mfma_f32_16x16x32_bf16 v[62:65], v[148:151], v[164:167], v[62:65]
	v_mfma_f32_16x16x32_bf16 v[62:65], v[152:155], v[168:171], v[62:65]
	v_mfma_f32_16x16x32_bf16 v[46:49], v[148:151], v[172:175], v[46:49]
	v_mfma_f32_16x16x32_bf16 v[46:49], v[152:155], v[176:179], v[46:49]
	v_mfma_f32_16x16x32_bf16 v[30:33], v[148:151], v[180:183], v[30:33]
	v_mfma_f32_16x16x32_bf16 v[30:33], v[152:155], v[204:207], v[30:33]
	v_mfma_f32_16x16x32_bf16 v[14:17], v[148:151], v[208:211], v[14:17]
	v_mfma_f32_16x16x32_bf16 v[14:17], v[152:155], v[212:215], v[14:17]
	v_mfma_f32_16x16x32_bf16 v[58:61], v[156:159], v[164:167], v[58:61]
	v_mfma_f32_16x16x32_bf16 v[58:61], v[160:163], v[168:171], v[58:61]
	v_mfma_f32_16x16x32_bf16 v[42:45], v[156:159], v[172:175], v[42:45]
	v_mfma_f32_16x16x32_bf16 v[42:45], v[160:163], v[176:179], v[42:45]
	v_mfma_f32_16x16x32_bf16 v[26:29], v[156:159], v[180:183], v[26:29]
	v_mfma_f32_16x16x32_bf16 v[26:29], v[160:163], v[204:207], v[26:29]
	v_mfma_f32_16x16x32_bf16 v[10:13], v[156:159], v[208:211], v[10:13]
	v_mfma_f32_16x16x32_bf16 v[10:13], v[160:163], v[212:215], v[10:13]
	s_barrier
	s_add_i32 s4, s4, s24
	s_mov_b32 m0, s4
	s_nop 0
	global_load_lds_dwordx4 v132, s[76:77]
	s_add_i32 m0, s4, 0x2000
	s_nop 0
	global_load_lds_dwordx4 v136, s[76:77]
	s_add_u32 s0, s0, 0x100
	s_addc_u32 s1, s1, 0
	s_add_u32 s47, s47, 0x100
	s_addc_u32 s48, s48, 0
	s_cmp_ge_u32 s49, s30
	s_mov_b32 s4, s49
	s_waitcnt vmcnt(6)
	s_barrier
	v_mfma_f32_16x16x32_bf16 v[50:53], v[216:219], v[164:167], v[50:53]
	v_mfma_f32_16x16x32_bf16 v[50:53], v[220:223], v[168:171], v[50:53]
	v_mfma_f32_16x16x32_bf16 v[34:37], v[216:219], v[172:175], v[34:37]
	v_mfma_f32_16x16x32_bf16 v[34:37], v[220:223], v[176:179], v[34:37]
	v_mfma_f32_16x16x32_bf16 v[18:21], v[216:219], v[180:183], v[18:21]
	v_mfma_f32_16x16x32_bf16 v[18:21], v[220:223], v[204:207], v[18:21]
	v_mfma_f32_16x16x32_bf16 v[6:9], v[216:219], v[208:211], v[6:9]
	v_mfma_f32_16x16x32_bf16 v[6:9], v[220:223], v[212:215], v[6:9]
	v_mfma_f32_16x16x32_bf16 v[54:57], v[224:227], v[164:167], v[54:57]
	v_mfma_f32_16x16x32_bf16 v[54:57], v[228:231], v[168:171], v[54:57]
	v_mfma_f32_16x16x32_bf16 v[38:41], v[224:227], v[172:175], v[38:41]
	v_mfma_f32_16x16x32_bf16 v[38:41], v[228:231], v[176:179], v[38:41]
	v_mfma_f32_16x16x32_bf16 v[22:25], v[224:227], v[180:183], v[22:25]
	v_mfma_f32_16x16x32_bf16 v[22:25], v[228:231], v[204:207], v[22:25]
	v_mfma_f32_16x16x32_bf16 v[2:5], v[224:227], v[208:211], v[2:5]
	v_mfma_f32_16x16x32_bf16 v[2:5], v[228:231], v[212:215], v[2:5]
	s_barrier
	s_cbranch_scc1 .Lkexit_253
.LBB0_253:
	s_add_i32 s49, s4, 2
	s_add_u32 s16, s0, 0x80
	s_addc_u32 s5, s1, 0
	s_add_i32 s65, 0, 0x10000
	ds_read_b128 v[148:151], v248
	ds_read_b128 v[152:155], v248 offset:1024
	ds_read_b128 v[156:159], v248 offset:2048
	ds_read_b128 v[160:163], v248 offset:3072
	s_cmp_eq_u32 s41, s4
	s_cselect_b32 s4, s10, s16
	s_cselect_b32 s5, s11, s5
	s_cselect_b32 s17, s13, s48
	s_cselect_b32 s16, s12, s47
	s_add_i32 m0, s26, 0xc000
	ds_read_b128 v[164:167], v146
	ds_read_b128 v[168:171], v146 offset:1024
	ds_read_b128 v[172:175], v146 offset:2048
	ds_read_b128 v[176:179], v146 offset:3072
	ds_read_b128 v[180:183], v146 offset:4096
	ds_read_b128 v[204:207], v146 offset:5120
	ds_read_b128 v[208:211], v146 offset:6144
	ds_read_b128 v[212:215], v146 offset:7168
	global_load_lds_dwordx4 v138, s[0:1]
	s_add_i32 m0, s26, 0xe000
	s_nop 0
	global_load_lds_dwordx4 v140, s[0:1]
	s_waitcnt lgkmcnt(8)
	s_barrier
	s_waitcnt lgkmcnt(0)
	v_mfma_f32_16x16x32_bf16 v[126:129], v[148:151], v[164:167], v[126:129]
	v_mfma_f32_16x16x32_bf16 v[126:129], v[152:155], v[168:171], v[126:129]
	v_mfma_f32_16x16x32_bf16 v[110:113], v[148:151], v[172:175], v[110:113]
	v_mfma_f32_16x16x32_bf16 v[110:113], v[152:155], v[176:179], v[110:113]
	v_mfma_f32_16x16x32_bf16 v[94:97], v[148:151], v[180:183], v[94:97]
	v_mfma_f32_16x16x32_bf16 v[94:97], v[152:155], v[204:207], v[94:97]
	v_mfma_f32_16x16x32_bf16 v[78:81], v[148:151], v[208:211], v[78:81]
	v_mfma_f32_16x16x32_bf16 v[78:81], v[152:155], v[212:215], v[78:81]
	v_mfma_f32_16x16x32_bf16 v[122:125], v[156:159], v[164:167], v[122:125]
	v_mfma_f32_16x16x32_bf16 v[122:125], v[160:163], v[168:171], v[122:125]
	v_mfma_f32_16x16x32_bf16 v[106:109], v[156:159], v[172:175], v[106:109]
	v_mfma_f32_16x16x32_bf16 v[106:109], v[160:163], v[176:179], v[106:109]
	v_mfma_f32_16x16x32_bf16 v[90:93], v[156:159], v[180:183], v[90:93]
	v_mfma_f32_16x16x32_bf16 v[90:93], v[160:163], v[204:207], v[90:93]
	v_mfma_f32_16x16x32_bf16 v[74:77], v[156:159], v[208:211], v[74:77]
	v_mfma_f32_16x16x32_bf16 v[74:77], v[160:163], v[212:215], v[74:77]
	s_barrier
	s_add_i32 s66, 0, 0x14000
	s_add_i32 s65, s65, s24
	ds_read_b128 v[216:219], v248 offset:16384
	ds_read_b128 v[220:223], v248 offset:17408
	ds_read_b128 v[224:227], v248 offset:18432
	ds_read_b128 v[228:231], v248 offset:19456
	s_add_u32 s70, s16, s6
	s_addc_u32 s71, s17, s7
	s_mov_b32 m0, s65
	s_nop 0
	global_load_lds_dwordx4 v132, s[16:17]
	s_add_i32 m0, s65, 0x2000
	s_nop 0
	global_load_lds_dwordx4 v136, s[16:17]
	s_barrier
	s_waitcnt lgkmcnt(0)
	v_mfma_f32_16x16x32_bf16 v[114:117], v[216:219], v[164:167], v[114:117]
	v_mfma_f32_16x16x32_bf16 v[114:117], v[220:223], v[168:171], v[114:117]
	v_mfma_f32_16x16x32_bf16 v[98:101], v[216:219], v[172:175], v[98:101]
	v_mfma_f32_16x16x32_bf16 v[98:101], v[220:223], v[176:179], v[98:101]
	v_mfma_f32_16x16x32_bf16 v[82:85], v[216:219], v[180:183], v[82:85]
	v_mfma_f32_16x16x32_bf16 v[82:85], v[220:223], v[204:207], v[82:85]
	v_mfma_f32_16x16x32_bf16 v[66:69], v[216:219], v[208:211], v[66:69]
	v_mfma_f32_16x16x32_bf16 v[66:69], v[220:223], v[212:215], v[66:69]
	v_mfma_f32_16x16x32_bf16 v[118:121], v[224:227], v[164:167], v[118:121]
	v_mfma_f32_16x16x32_bf16 v[118:121], v[228:231], v[168:171], v[118:121]
	v_mfma_f32_16x16x32_bf16 v[102:105], v[224:227], v[172:175], v[102:105]
	v_mfma_f32_16x16x32_bf16 v[102:105], v[228:231], v[176:179], v[102:105]
	v_mfma_f32_16x16x32_bf16 v[86:89], v[224:227], v[180:183], v[86:89]
	v_mfma_f32_16x16x32_bf16 v[86:89], v[228:231], v[204:207], v[86:89]
	v_mfma_f32_16x16x32_bf16 v[70:73], v[224:227], v[208:211], v[70:73]
	v_mfma_f32_16x16x32_bf16 v[70:73], v[228:231], v[212:215], v[70:73]
	s_barrier
	s_mov_b32 m0, s26
	s_add_u32 s72, s4, s6
	s_addc_u32 s73, s5, s7
	ds_read_b128 v[164:167], v146 offset:16384
	ds_read_b128 v[168:171], v146 offset:17408
	ds_read_b128 v[172:175], v146 offset:18432
	ds_read_b128 v[176:179], v146 offset:19456
	ds_read_b128 v[180:183], v146 offset:20480
	ds_read_b128 v[204:207], v146 offset:21504
	ds_read_b128 v[208:211], v146 offset:22528
	ds_read_b128 v[212:215], v146 offset:23552
	global_load_lds_dwordx4 v130, s[4:5]
	s_mov_b32 m0, s27
	s_nop 0
	global_load_lds_dwordx4 v134, s[4:5]
	s_barrier
	s_waitcnt lgkmcnt(0)
	v_mfma_f32_16x16x32_bf16 v[62:65], v[148:151], v[164:167], v[62:65]
	v_mfma_f32_16x16x32_bf16 v[62:65], v[152:155], v[168:171], v[62:65]
	v_mfma_f32_16x16x32_bf16 v[46:49], v[148:151], v[172:175], v[46:49]
	v_mfma_f32_16x16x32_bf16 v[46:49], v[152:155], v[176:179], v[46:49]
	v_mfma_f32_16x16x32_bf16 v[30:33], v[148:151], v[180:183], v[30:33]
	v_mfma_f32_16x16x32_bf16 v[30:33], v[152:155], v[204:207], v[30:33]
	v_mfma_f32_16x16x32_bf16 v[14:17], v[148:151], v[208:211], v[14:17]
	v_mfma_f32_16x16x32_bf16 v[14:17], v[152:155], v[212:215], v[14:17]
	v_mfma_f32_16x16x32_bf16 v[58:61], v[156:159], v[164:167], v[58:61]
	v_mfma_f32_16x16x32_bf16 v[58:61], v[160:163], v[168:171], v[58:61]
	v_mfma_f32_16x16x32_bf16 v[42:45], v[156:159], v[172:175], v[42:45]
	v_mfma_f32_16x16x32_bf16 v[42:45], v[160:163], v[176:179], v[42:45]
	v_mfma_f32_16x16x32_bf16 v[26:29], v[156:159], v[180:183], v[26:29]
	v_mfma_f32_16x16x32_bf16 v[26:29], v[160:163], v[204:207], v[26:29]
	v_mfma_f32_16x16x32_bf16 v[10:13], v[156:159], v[208:211], v[10:13]
	v_mfma_f32_16x16x32_bf16 v[10:13], v[160:163], v[212:215], v[10:13]
	s_barrier
	s_add_u32 s16, s16, s92
	s_addc_u32 s17, s17, 0
	s_add_i32 s65, s66, s24
	s_add_u32 s76, s16, s6
	s_addc_u32 s77, s17, s7
	s_mov_b32 m0, s65
	s_nop 0
	global_load_lds_dwordx4 v132, s[16:17]
	s_add_i32 m0, s65, 0x2000
	s_nop 0
	global_load_lds_dwordx4 v136, s[16:17]
	s_waitcnt vmcnt(6)
	s_barrier
	v_mfma_f32_16x16x32_bf16 v[50:53], v[216:219], v[164:167], v[50:53]
	v_mfma_f32_16x16x32_bf16 v[50:53], v[220:223], v[168:171], v[50:53]
	v_mfma_f32_16x16x32_bf16 v[34:37], v[216:219], v[172:175], v[34:37]
	v_mfma_f32_16x16x32_bf16 v[34:37], v[220:223], v[176:179], v[34:37]
	v_mfma_f32_16x16x32_bf16 v[18:21], v[216:219], v[180:183], v[18:21]
	v_mfma_f32_16x16x32_bf16 v[18:21], v[220:223], v[204:207], v[18:21]
	v_mfma_f32_16x16x32_bf16 v[6:9], v[216:219], v[208:211], v[6:9]
	v_mfma_f32_16x16x32_bf16 v[6:9], v[220:223], v[212:215], v[6:9]
	v_mfma_f32_16x16x32_bf16 v[54:57], v[224:227], v[164:167], v[54:57]
	v_mfma_f32_16x16x32_bf16 v[54:57], v[228:231], v[168:171], v[54:57]
	v_mfma_f32_16x16x32_bf16 v[38:41], v[224:227], v[172:175], v[38:41]
	v_mfma_f32_16x16x32_bf16 v[38:41], v[228:231], v[176:179], v[38:41]
	v_mfma_f32_16x16x32_bf16 v[22:25], v[224:227], v[180:183], v[22:25]
	v_mfma_f32_16x16x32_bf16 v[22:25], v[228:231], v[204:207], v[22:25]
	v_mfma_f32_16x16x32_bf16 v[2:5], v[224:227], v[208:211], v[2:5]
	v_mfma_f32_16x16x32_bf16 v[2:5], v[228:231], v[212:215], v[2:5]
	s_barrier
	s_add_i32 s16, 0, 0x18000
	ds_read_b128 v[148:151], v248 offset:32768
	ds_read_b128 v[152:155], v248 offset:33792
	ds_read_b128 v[156:159], v248 offset:34816
	ds_read_b128 v[160:163], v248 offset:35840
	s_add_u32 s4, s4, s92
	s_addc_u32 s5, s5, 0
	s_mov_b32 m0, s28
	ds_read_b128 v[164:167], v146 offset:32768
	ds_read_b128 v[168:171], v146 offset:33792
	ds_read_b128 v[172:175], v146 offset:34816
	ds_read_b128 v[176:179], v146 offset:35840
	ds_read_b128 v[180:183], v146 offset:36864
	ds_read_b128 v[204:207], v146 offset:37888
	ds_read_b128 v[208:211], v146 offset:38912
	ds_read_b128 v[212:215], v146 offset:39936
	global_load_lds_dwordx4 v130, s[4:5]
	s_mov_b32 m0, s29
	s_nop 0
	global_load_lds_dwordx4 v134, s[4:5]
	s_waitcnt lgkmcnt(8)
	s_barrier
	s_waitcnt lgkmcnt(0)
	v_mfma_f32_16x16x32_bf16 v[126:129], v[148:151], v[164:167], v[126:129]
	v_mfma_f32_16x16x32_bf16 v[126:129], v[152:155], v[168:171], v[126:129]
	v_mfma_f32_16x16x32_bf16 v[110:113], v[148:151], v[172:175], v[110:113]
	v_mfma_f32_16x16x32_bf16 v[110:113], v[152:155], v[176:179], v[110:113]
	v_mfma_f32_16x16x32_bf16 v[94:97], v[148:151], v[180:183], v[94:97]
	v_mfma_f32_16x16x32_bf16 v[94:97], v[152:155], v[204:207], v[94:97]
	v_mfma_f32_16x16x32_bf16 v[78:81], v[148:151], v[208:211], v[78:81]
	v_mfma_f32_16x16x32_bf16 v[78:81], v[152:155], v[212:215], v[78:81]
	v_mfma_f32_16x16x32_bf16 v[122:125], v[156:159], v[164:167], v[122:125]
	v_mfma_f32_16x16x32_bf16 v[122:125], v[160:163], v[168:171], v[122:125]
	v_mfma_f32_16x16x32_bf16 v[106:109], v[156:159], v[172:175], v[106:109]
	v_mfma_f32_16x16x32_bf16 v[106:109], v[160:163], v[176:179], v[106:109]
	v_mfma_f32_16x16x32_bf16 v[90:93], v[156:159], v[180:183], v[90:93]
	v_mfma_f32_16x16x32_bf16 v[90:93], v[160:163], v[204:207], v[90:93]
	v_mfma_f32_16x16x32_bf16 v[74:77], v[156:159], v[208:211], v[74:77]
	v_mfma_f32_16x16x32_bf16 v[74:77], v[160:163], v[212:215], v[74:77]
	s_barrier
	s_add_i32 s4, 0, 0x1c000
	s_add_i32 s5, s16, s24
	s_mov_b32 m0, s5
	ds_read_b128 v[216:219], v248 offset:49152
	ds_read_b128 v[220:223], v248 offset:50176
	ds_read_b128 v[224:227], v248 offset:51200
	ds_read_b128 v[228:231], v248 offset:52224
	global_load_lds_dwordx4 v132, s[70:71]
	s_add_i32 m0, s5, 0x2000
	s_nop 0
	global_load_lds_dwordx4 v136, s[70:71]
	s_barrier
	s_waitcnt lgkmcnt(0)
	v_mfma_f32_16x16x32_bf16 v[114:117], v[216:219], v[164:167], v[114:117]
	v_mfma_f32_16x16x32_bf16 v[114:117], v[220:223], v[168:171], v[114:117]
	v_mfma_f32_16x16x32_bf16 v[98:101], v[216:219], v[172:175], v[98:101]
	v_mfma_f32_16x16x32_bf16 v[98:101], v[220:223], v[176:179], v[98:101]
	v_mfma_f32_16x16x32_bf16 v[82:85], v[216:219], v[180:183], v[82:85]
	v_mfma_f32_16x16x32_bf16 v[82:85], v[220:223], v[204:207], v[82:85]
	v_mfma_f32_16x16x32_bf16 v[66:69], v[216:219], v[208:211], v[66:69]
	v_mfma_f32_16x16x32_bf16 v[66:69], v[220:223], v[212:215], v[66:69]
	v_mfma_f32_16x16x32_bf16 v[118:121], v[224:227], v[164:167], v[118:121]
	v_mfma_f32_16x16x32_bf16 v[118:121], v[228:231], v[168:171], v[118:121]
	v_mfma_f32_16x16x32_bf16 v[102:105], v[224:227], v[172:175], v[102:105]
	v_mfma_f32_16x16x32_bf16 v[102:105], v[228:231], v[176:179], v[102:105]
	v_mfma_f32_16x16x32_bf16 v[86:89], v[224:227], v[180:183], v[86:89]
	v_mfma_f32_16x16x32_bf16 v[86:89], v[228:231], v[204:207], v[86:89]
	v_mfma_f32_16x16x32_bf16 v[70:73], v[224:227], v[208:211], v[70:73]
	v_mfma_f32_16x16x32_bf16 v[70:73], v[228:231], v[212:215], v[70:73]
	s_barrier
	s_mov_b32 m0, s35
	ds_read_b128 v[164:167], v146 offset:49152
	ds_read_b128 v[168:171], v146 offset:50176
	ds_read_b128 v[172:175], v146 offset:51200
	ds_read_b128 v[176:179], v146 offset:52224
	ds_read_b128 v[180:183], v146 offset:53248
	ds_read_b128 v[204:207], v146 offset:54272
	ds_read_b128 v[208:211], v146 offset:55296
	ds_read_b128 v[212:215], v146 offset:56320
	global_load_lds_dwordx4 v130, s[72:73]
	s_mov_b32 m0, s40
	s_nop 0
	global_load_lds_dwordx4 v134, s[72:73]
	s_barrier
	s_waitcnt lgkmcnt(0)
	v_mfma_f32_16x16x32_bf16 v[62:65], v[148:151], v[164:167], v[62:65]
	v_mfma_f32_16x16x32_bf16 v[62:65], v[152:155], v[168:171], v[62:65]
	v_mfma_f32_16x16x32_bf16 v[46:49], v[148:151], v[172:175], v[46:49]
	v_mfma_f32_16x16x32_bf16 v[46:49], v[152:155], v[176:179], v[46:49]
	v_mfma_f32_16x16x32_bf16 v[30:33], v[148:151], v[180:183], v[30:33]
	v_mfma_f32_16x16x32_bf16 v[30:33], v[152:155], v[204:207], v[30:33]
	v_mfma_f32_16x16x32_bf16 v[14:17], v[148:151], v[208:211], v[14:17]
	v_mfma_f32_16x16x32_bf16 v[14:17], v[152:155], v[212:215], v[14:17]
	v_mfma_f32_16x16x32_bf16 v[58:61], v[156:159], v[164:167], v[58:61]
	v_mfma_f32_16x16x32_bf16 v[58:61], v[160:163], v[168:171], v[58:61]
	v_mfma_f32_16x16x32_bf16 v[42:45], v[156:159], v[172:175], v[42:45]
	v_mfma_f32_16x16x32_bf16 v[42:45], v[160:163], v[176:179], v[42:45]
	v_mfma_f32_16x16x32_bf16 v[26:29], v[156:159], v[180:183], v[26:29]
	v_mfma_f32_16x16x32_bf16 v[26:29], v[160:163], v[204:207], v[26:29]
	v_mfma_f32_16x16x32_bf16 v[10:13], v[156:159], v[208:211], v[10:13]
	v_mfma_f32_16x16x32_bf16 v[10:13], v[160:163], v[212:215], v[10:13]
	s_barrier
	s_add_i32 s4, s4, s24
	s_mov_b32 m0, s4
	s_nop 0
	global_load_lds_dwordx4 v132, s[76:77]
	s_add_i32 m0, s4, 0x2000
	s_nop 0
	global_load_lds_dwordx4 v136, s[76:77]
	s_add_u32 s0, s0, 0x100
	s_addc_u32 s1, s1, 0
	s_add_u32 s47, s47, 0x100
	s_addc_u32 s48, s48, 0
	s_cmp_ge_u32 s49, s30
	s_mov_b32 s4, s49
	s_waitcnt vmcnt(6)
	s_barrier
	v_mfma_f32_16x16x32_bf16 v[50:53], v[216:219], v[164:167], v[50:53]
	v_mfma_f32_16x16x32_bf16 v[50:53], v[220:223], v[168:171], v[50:53]
	v_mfma_f32_16x16x32_bf16 v[34:37], v[216:219], v[172:175], v[34:37]
	v_mfma_f32_16x16x32_bf16 v[34:37], v[220:223], v[176:179], v[34:37]
	v_mfma_f32_16x16x32_bf16 v[18:21], v[216:219], v[180:183], v[18:21]
	v_mfma_f32_16x16x32_bf16 v[18:21], v[220:223], v[204:207], v[18:21]
	v_mfma_f32_16x16x32_bf16 v[6:9], v[216:219], v[208:211], v[6:9]
	v_mfma_f32_16x16x32_bf16 v[6:9], v[220:223], v[212:215], v[6:9]
	v_mfma_f32_16x16x32_bf16 v[54:57], v[224:227], v[164:167], v[54:57]
	v_mfma_f32_16x16x32_bf16 v[54:57], v[228:231], v[168:171], v[54:57]
	v_mfma_f32_16x16x32_bf16 v[38:41], v[224:227], v[172:175], v[38:41]
	v_mfma_f32_16x16x32_bf16 v[38:41], v[228:231], v[176:179], v[38:41]
	v_mfma_f32_16x16x32_bf16 v[22:25], v[224:227], v[180:183], v[22:25]
	v_mfma_f32_16x16x32_bf16 v[22:25], v[228:231], v[204:207], v[22:25]
	v_mfma_f32_16x16x32_bf16 v[2:5], v[224:227], v[208:211], v[2:5]
	v_mfma_f32_16x16x32_bf16 v[2:5], v[228:231], v[212:215], v[2:5]
	s_barrier
	s_cbranch_scc0 .LBB0_253

.LBB0_281:
	s_add_u32 s0, s0, 0x80
	s_addc_u32 s1, s1, 0
	s_add_u32 s20, s4, 0x100
	s_addc_u32 s21, s5, 0
	s_mov_b32 s4, 0
	s_waitcnt lgkmcnt(0)
	s_add_i32 s22, s4, 2
	s_add_u32 s10, s0, 0x80
	s_addc_u32 s5, s1, 0
	s_add_i32 s23, 0, 0x10000
	ds_read_b128 v[142:145], v248
	ds_read_b128 v[146:149], v248 offset:1024
	ds_read_b128 v[150:153], v248 offset:2048
	ds_read_b128 v[154:157], v248 offset:3072
	s_cmp_eq_u32 s44, s4
	s_cselect_b32 s4, s16, s10
	s_cselect_b32 s5, s17, s5
	s_cselect_b32 s11, s13, s21
	s_cselect_b32 s10, s12, s20
	s_add_i32 m0, s29, 0xc000
	ds_read_b128 v[158:161], v166
	ds_read_b128 v[168:171], v166 offset:1024
	ds_read_b128 v[172:175], v166 offset:2048
	ds_read_b128 v[176:179], v166 offset:3072
	ds_read_b128 v[180:183], v166 offset:4096
	ds_read_b128 v[204:207], v166 offset:5120
	ds_read_b128 v[208:211], v166 offset:6144
	ds_read_b128 v[212:215], v166 offset:7168
	global_load_lds_dwordx4 v138, s[0:1]
	s_add_i32 m0, s29, 0xe000
	s_nop 0
	global_load_lds_dwordx4 v140, s[0:1]
	s_waitcnt lgkmcnt(8)
	s_barrier
	s_waitcnt lgkmcnt(0)
	v_mfma_f32_16x16x32_bf16 v[126:129], v[142:145], v[158:161], 0
	v_mfma_f32_16x16x32_bf16 v[126:129], v[146:149], v[168:171], v[126:129]
	v_mfma_f32_16x16x32_bf16 v[110:113], v[142:145], v[172:175], 0
	v_mfma_f32_16x16x32_bf16 v[110:113], v[146:149], v[176:179], v[110:113]
	v_mfma_f32_16x16x32_bf16 v[94:97], v[142:145], v[180:183], 0
	v_mfma_f32_16x16x32_bf16 v[94:97], v[146:149], v[204:207], v[94:97]
	v_mfma_f32_16x16x32_bf16 v[78:81], v[142:145], v[208:211], 0
	v_mfma_f32_16x16x32_bf16 v[78:81], v[146:149], v[212:215], v[78:81]
	v_mfma_f32_16x16x32_bf16 v[122:125], v[150:153], v[158:161], 0
	v_mfma_f32_16x16x32_bf16 v[122:125], v[154:157], v[168:171], v[122:125]
	v_mfma_f32_16x16x32_bf16 v[106:109], v[150:153], v[172:175], 0
	v_mfma_f32_16x16x32_bf16 v[106:109], v[154:157], v[176:179], v[106:109]
	v_mfma_f32_16x16x32_bf16 v[90:93], v[150:153], v[180:183], 0
	v_mfma_f32_16x16x32_bf16 v[90:93], v[154:157], v[204:207], v[90:93]
	v_mfma_f32_16x16x32_bf16 v[74:77], v[150:153], v[208:211], 0
	v_mfma_f32_16x16x32_bf16 v[74:77], v[154:157], v[212:215], v[74:77]
	s_barrier
	s_add_i32 s24, 0, 0x14000
	s_add_i32 s23, s23, s28
	ds_read_b128 v[216:219], v248 offset:16384
	ds_read_b128 v[220:223], v248 offset:17408
	ds_read_b128 v[224:227], v248 offset:18432
	ds_read_b128 v[228:231], v248 offset:19456
	s_add_u32 s70, s10, s6
	s_addc_u32 s71, s11, s7
	s_mov_b32 m0, s23
	s_nop 0
	global_load_lds_dwordx4 v132, s[10:11]
	s_add_i32 m0, s23, 0x2000
	s_nop 0
	global_load_lds_dwordx4 v136, s[10:11]
	s_barrier
	s_waitcnt lgkmcnt(0)
	v_mfma_f32_16x16x32_bf16 v[118:121], v[216:219], v[158:161], 0
	v_mfma_f32_16x16x32_bf16 v[118:121], v[220:223], v[168:171], v[118:121]
	v_mfma_f32_16x16x32_bf16 v[102:105], v[216:219], v[172:175], 0
	v_mfma_f32_16x16x32_bf16 v[102:105], v[220:223], v[176:179], v[102:105]
	v_mfma_f32_16x16x32_bf16 v[86:89], v[216:219], v[180:183], 0
	v_mfma_f32_16x16x32_bf16 v[86:89], v[220:223], v[204:207], v[86:89]
	v_mfma_f32_16x16x32_bf16 v[70:73], v[216:219], v[208:211], 0
	v_mfma_f32_16x16x32_bf16 v[70:73], v[220:223], v[212:215], v[70:73]
	v_mfma_f32_16x16x32_bf16 v[114:117], v[224:227], v[158:161], 0
	v_mfma_f32_16x16x32_bf16 v[114:117], v[228:231], v[168:171], v[114:117]
	v_mfma_f32_16x16x32_bf16 v[98:101], v[224:227], v[172:175], 0
	v_mfma_f32_16x16x32_bf16 v[98:101], v[228:231], v[176:179], v[98:101]
	v_mfma_f32_16x16x32_bf16 v[82:85], v[224:227], v[180:183], 0
	v_mfma_f32_16x16x32_bf16 v[82:85], v[228:231], v[204:207], v[82:85]
	v_mfma_f32_16x16x32_bf16 v[66:69], v[224:227], v[208:211], 0
	v_mfma_f32_16x16x32_bf16 v[66:69], v[228:231], v[212:215], v[66:69]
	s_barrier
	s_mov_b32 m0, s29
	s_add_u32 s72, s4, s6
	s_addc_u32 s73, s5, s7
	ds_read_b128 v[158:161], v166 offset:16384
	ds_read_b128 v[168:171], v166 offset:17408
	ds_read_b128 v[172:175], v166 offset:18432
	ds_read_b128 v[176:179], v166 offset:19456
	ds_read_b128 v[180:183], v166 offset:20480
	ds_read_b128 v[204:207], v166 offset:21504
	ds_read_b128 v[208:211], v166 offset:22528
	ds_read_b128 v[212:215], v166 offset:23552
	global_load_lds_dwordx4 v130, s[4:5]
	s_mov_b32 m0, s30
	s_nop 0
	global_load_lds_dwordx4 v134, s[4:5]
	s_barrier
	s_waitcnt lgkmcnt(0)
	v_mfma_f32_16x16x32_bf16 v[62:65], v[142:145], v[158:161], 0
	v_mfma_f32_16x16x32_bf16 v[62:65], v[146:149], v[168:171], v[62:65]
	v_mfma_f32_16x16x32_bf16 v[46:49], v[142:145], v[172:175], 0
	v_mfma_f32_16x16x32_bf16 v[46:49], v[146:149], v[176:179], v[46:49]
	v_mfma_f32_16x16x32_bf16 v[30:33], v[142:145], v[180:183], 0
	v_mfma_f32_16x16x32_bf16 v[30:33], v[146:149], v[204:207], v[30:33]
	v_mfma_f32_16x16x32_bf16 v[14:17], v[142:145], v[208:211], 0
	v_mfma_f32_16x16x32_bf16 v[14:17], v[146:149], v[212:215], v[14:17]
	v_mfma_f32_16x16x32_bf16 v[58:61], v[150:153], v[158:161], 0
	v_mfma_f32_16x16x32_bf16 v[58:61], v[154:157], v[168:171], v[58:61]
	v_mfma_f32_16x16x32_bf16 v[42:45], v[150:153], v[172:175], 0
	v_mfma_f32_16x16x32_bf16 v[42:45], v[154:157], v[176:179], v[42:45]
	v_mfma_f32_16x16x32_bf16 v[26:29], v[150:153], v[180:183], 0
	v_mfma_f32_16x16x32_bf16 v[26:29], v[154:157], v[204:207], v[26:29]
	v_mfma_f32_16x16x32_bf16 v[10:13], v[150:153], v[208:211], 0
	v_mfma_f32_16x16x32_bf16 v[10:13], v[154:157], v[212:215], v[10:13]
	s_barrier
	s_add_u32 s10, s10, s92
	s_addc_u32 s11, s11, 0
	s_add_i32 s23, s24, s28
	s_add_u32 s80, s10, s6
	s_addc_u32 s81, s11, s7
	s_mov_b32 m0, s23
	s_nop 0
	global_load_lds_dwordx4 v132, s[10:11]
	s_add_i32 m0, s23, 0x2000
	s_nop 0
	global_load_lds_dwordx4 v136, s[10:11]
	s_waitcnt vmcnt(6)
	s_barrier
	v_mfma_f32_16x16x32_bf16 v[54:57], v[216:219], v[158:161], 0
	v_mfma_f32_16x16x32_bf16 v[54:57], v[220:223], v[168:171], v[54:57]
	v_mfma_f32_16x16x32_bf16 v[38:41], v[216:219], v[172:175], 0
	v_mfma_f32_16x16x32_bf16 v[38:41], v[220:223], v[176:179], v[38:41]
	v_mfma_f32_16x16x32_bf16 v[22:25], v[216:219], v[180:183], 0
	v_mfma_f32_16x16x32_bf16 v[22:25], v[220:223], v[204:207], v[22:25]
	v_mfma_f32_16x16x32_bf16 v[6:9], v[216:219], v[208:211], 0
	v_mfma_f32_16x16x32_bf16 v[6:9], v[220:223], v[212:215], v[6:9]
	v_mfma_f32_16x16x32_bf16 v[50:53], v[224:227], v[158:161], 0
	v_mfma_f32_16x16x32_bf16 v[50:53], v[228:231], v[168:171], v[50:53]
	v_mfma_f32_16x16x32_bf16 v[34:37], v[224:227], v[172:175], 0
	v_mfma_f32_16x16x32_bf16 v[34:37], v[228:231], v[176:179], v[34:37]
	v_mfma_f32_16x16x32_bf16 v[18:21], v[224:227], v[180:183], 0
	v_mfma_f32_16x16x32_bf16 v[18:21], v[228:231], v[204:207], v[18:21]
	v_mfma_f32_16x16x32_bf16 v[2:5], v[224:227], v[208:211], 0
	v_mfma_f32_16x16x32_bf16 v[2:5], v[228:231], v[212:215], v[2:5]
	s_barrier
	s_add_i32 s10, 0, 0x18000
	ds_read_b128 v[142:145], v248 offset:32768
	ds_read_b128 v[146:149], v248 offset:33792
	ds_read_b128 v[150:153], v248 offset:34816
	ds_read_b128 v[154:157], v248 offset:35840
	s_add_u32 s4, s4, s92
	s_addc_u32 s5, s5, 0
	s_mov_b32 m0, s31
	ds_read_b128 v[158:161], v166 offset:32768
	ds_read_b128 v[168:171], v166 offset:33792
	ds_read_b128 v[172:175], v166 offset:34816
	ds_read_b128 v[176:179], v166 offset:35840
	ds_read_b128 v[180:183], v166 offset:36864
	ds_read_b128 v[204:207], v166 offset:37888
	ds_read_b128 v[208:211], v166 offset:38912
	ds_read_b128 v[212:215], v166 offset:39936
	global_load_lds_dwordx4 v130, s[4:5]
	s_mov_b32 m0, s34
	s_nop 0
	global_load_lds_dwordx4 v134, s[4:5]
	s_waitcnt lgkmcnt(8)
	s_barrier
	s_waitcnt lgkmcnt(0)
	v_mfma_f32_16x16x32_bf16 v[126:129], v[142:145], v[158:161], v[126:129]
	v_mfma_f32_16x16x32_bf16 v[126:129], v[146:149], v[168:171], v[126:129]
	v_mfma_f32_16x16x32_bf16 v[110:113], v[142:145], v[172:175], v[110:113]
	v_mfma_f32_16x16x32_bf16 v[110:113], v[146:149], v[176:179], v[110:113]
	v_mfma_f32_16x16x32_bf16 v[94:97], v[142:145], v[180:183], v[94:97]
	v_mfma_f32_16x16x32_bf16 v[94:97], v[146:149], v[204:207], v[94:97]
	v_mfma_f32_16x16x32_bf16 v[78:81], v[142:145], v[208:211], v[78:81]
	v_mfma_f32_16x16x32_bf16 v[78:81], v[146:149], v[212:215], v[78:81]
	v_mfma_f32_16x16x32_bf16 v[122:125], v[150:153], v[158:161], v[122:125]
	v_mfma_f32_16x16x32_bf16 v[122:125], v[154:157], v[168:171], v[122:125]
	v_mfma_f32_16x16x32_bf16 v[106:109], v[150:153], v[172:175], v[106:109]
	v_mfma_f32_16x16x32_bf16 v[106:109], v[154:157], v[176:179], v[106:109]
	v_mfma_f32_16x16x32_bf16 v[90:93], v[150:153], v[180:183], v[90:93]
	v_mfma_f32_16x16x32_bf16 v[90:93], v[154:157], v[204:207], v[90:93]
	v_mfma_f32_16x16x32_bf16 v[74:77], v[150:153], v[208:211], v[74:77]
	v_mfma_f32_16x16x32_bf16 v[74:77], v[154:157], v[212:215], v[74:77]
	s_barrier
	s_add_i32 s4, 0, 0x1c000
	s_add_i32 s5, s10, s28
	s_mov_b32 m0, s5
	ds_read_b128 v[216:219], v248 offset:49152
	ds_read_b128 v[220:223], v248 offset:50176
	ds_read_b128 v[224:227], v248 offset:51200
	ds_read_b128 v[228:231], v248 offset:52224
	global_load_lds_dwordx4 v132, s[70:71]
	s_add_i32 m0, s5, 0x2000
	s_nop 0
	global_load_lds_dwordx4 v136, s[70:71]
	s_barrier
	s_waitcnt lgkmcnt(0)
	v_mfma_f32_16x16x32_bf16 v[118:121], v[216:219], v[158:161], v[118:121]
	v_mfma_f32_16x16x32_bf16 v[118:121], v[220:223], v[168:171], v[118:121]
	v_mfma_f32_16x16x32_bf16 v[102:105], v[216:219], v[172:175], v[102:105]
	v_mfma_f32_16x16x32_bf16 v[102:105], v[220:223], v[176:179], v[102:105]
	v_mfma_f32_16x16x32_bf16 v[86:89], v[216:219], v[180:183], v[86:89]
	v_mfma_f32_16x16x32_bf16 v[86:89], v[220:223], v[204:207], v[86:89]
	v_mfma_f32_16x16x32_bf16 v[70:73], v[216:219], v[208:211], v[70:73]
	v_mfma_f32_16x16x32_bf16 v[70:73], v[220:223], v[212:215], v[70:73]
	v_mfma_f32_16x16x32_bf16 v[114:117], v[224:227], v[158:161], v[114:117]
	v_mfma_f32_16x16x32_bf16 v[114:117], v[228:231], v[168:171], v[114:117]
	v_mfma_f32_16x16x32_bf16 v[98:101], v[224:227], v[172:175], v[98:101]
	v_mfma_f32_16x16x32_bf16 v[98:101], v[228:231], v[176:179], v[98:101]
	v_mfma_f32_16x16x32_bf16 v[82:85], v[224:227], v[180:183], v[82:85]
	v_mfma_f32_16x16x32_bf16 v[82:85], v[228:231], v[204:207], v[82:85]
	v_mfma_f32_16x16x32_bf16 v[66:69], v[224:227], v[208:211], v[66:69]
	v_mfma_f32_16x16x32_bf16 v[66:69], v[228:231], v[212:215], v[66:69]
	s_barrier
	s_mov_b32 m0, s42
	ds_read_b128 v[158:161], v166 offset:49152
	ds_read_b128 v[168:171], v166 offset:50176
	ds_read_b128 v[172:175], v166 offset:51200
	ds_read_b128 v[176:179], v166 offset:52224
	ds_read_b128 v[180:183], v166 offset:53248
	ds_read_b128 v[204:207], v166 offset:54272
	ds_read_b128 v[208:211], v166 offset:55296
	ds_read_b128 v[212:215], v166 offset:56320
	global_load_lds_dwordx4 v130, s[72:73]
	s_mov_b32 m0, s43
	s_nop 0
	global_load_lds_dwordx4 v134, s[72:73]
	s_barrier
	s_waitcnt lgkmcnt(0)
	v_mfma_f32_16x16x32_bf16 v[62:65], v[142:145], v[158:161], v[62:65]
	v_mfma_f32_16x16x32_bf16 v[62:65], v[146:149], v[168:171], v[62:65]
	v_mfma_f32_16x16x32_bf16 v[46:49], v[142:145], v[172:175], v[46:49]
	v_mfma_f32_16x16x32_bf16 v[46:49], v[146:149], v[176:179], v[46:49]
	v_mfma_f32_16x16x32_bf16 v[30:33], v[142:145], v[180:183], v[30:33]
	v_mfma_f32_16x16x32_bf16 v[30:33], v[146:149], v[204:207], v[30:33]
	v_mfma_f32_16x16x32_bf16 v[14:17], v[142:145], v[208:211], v[14:17]
	v_mfma_f32_16x16x32_bf16 v[14:17], v[146:149], v[212:215], v[14:17]
	v_mfma_f32_16x16x32_bf16 v[58:61], v[150:153], v[158:161], v[58:61]
	v_mfma_f32_16x16x32_bf16 v[58:61], v[154:157], v[168:171], v[58:61]
	v_mfma_f32_16x16x32_bf16 v[42:45], v[150:153], v[172:175], v[42:45]
	v_mfma_f32_16x16x32_bf16 v[42:45], v[154:157], v[176:179], v[42:45]
	v_mfma_f32_16x16x32_bf16 v[26:29], v[150:153], v[180:183], v[26:29]
	v_mfma_f32_16x16x32_bf16 v[26:29], v[154:157], v[204:207], v[26:29]
	v_mfma_f32_16x16x32_bf16 v[10:13], v[150:153], v[208:211], v[10:13]
	v_mfma_f32_16x16x32_bf16 v[10:13], v[154:157], v[212:215], v[10:13]
	s_barrier
	s_add_i32 s4, s4, s28
	s_mov_b32 m0, s4
	s_nop 0
	global_load_lds_dwordx4 v132, s[80:81]
	s_add_i32 m0, s4, 0x2000
	s_nop 0
	global_load_lds_dwordx4 v136, s[80:81]
	s_add_u32 s0, s0, 0x100
	s_addc_u32 s1, s1, 0
	s_add_u32 s20, s20, 0x100
	s_addc_u32 s21, s21, 0
	s_cmp_ge_u32 s22, s35
	s_mov_b32 s4, s22
	s_waitcnt vmcnt(6)
	s_barrier
	v_mfma_f32_16x16x32_bf16 v[54:57], v[216:219], v[158:161], v[54:57]
	v_mfma_f32_16x16x32_bf16 v[54:57], v[220:223], v[168:171], v[54:57]
	v_mfma_f32_16x16x32_bf16 v[38:41], v[216:219], v[172:175], v[38:41]
	v_mfma_f32_16x16x32_bf16 v[38:41], v[220:223], v[176:179], v[38:41]
	v_mfma_f32_16x16x32_bf16 v[22:25], v[216:219], v[180:183], v[22:25]
	v_mfma_f32_16x16x32_bf16 v[22:25], v[220:223], v[204:207], v[22:25]
	v_mfma_f32_16x16x32_bf16 v[6:9], v[216:219], v[208:211], v[6:9]
	v_mfma_f32_16x16x32_bf16 v[6:9], v[220:223], v[212:215], v[6:9]
	v_mfma_f32_16x16x32_bf16 v[50:53], v[224:227], v[158:161], v[50:53]
	v_mfma_f32_16x16x32_bf16 v[50:53], v[228:231], v[168:171], v[50:53]
	v_mfma_f32_16x16x32_bf16 v[34:37], v[224:227], v[172:175], v[34:37]
	v_mfma_f32_16x16x32_bf16 v[34:37], v[228:231], v[176:179], v[34:37]
	v_mfma_f32_16x16x32_bf16 v[18:21], v[224:227], v[180:183], v[18:21]
	v_mfma_f32_16x16x32_bf16 v[18:21], v[228:231], v[204:207], v[18:21]
	v_mfma_f32_16x16x32_bf16 v[2:5], v[224:227], v[208:211], v[2:5]
	v_mfma_f32_16x16x32_bf16 v[2:5], v[228:231], v[212:215], v[2:5]
	s_barrier
	s_cbranch_scc1 .Lkexit_282
.LBB0_282:
	s_add_i32 s22, s4, 2
	s_add_u32 s10, s0, 0x80
	s_addc_u32 s5, s1, 0
	s_add_i32 s23, 0, 0x10000
	ds_read_b128 v[142:145], v248
	ds_read_b128 v[146:149], v248 offset:1024
	ds_read_b128 v[150:153], v248 offset:2048
	ds_read_b128 v[154:157], v248 offset:3072
	s_cmp_eq_u32 s44, s4
	s_cselect_b32 s4, s16, s10
	s_cselect_b32 s5, s17, s5
	s_cselect_b32 s11, s13, s21
	s_cselect_b32 s10, s12, s20
	s_add_i32 m0, s29, 0xc000
	ds_read_b128 v[158:161], v166
	ds_read_b128 v[168:171], v166 offset:1024
	ds_read_b128 v[172:175], v166 offset:2048
	ds_read_b128 v[176:179], v166 offset:3072
	ds_read_b128 v[180:183], v166 offset:4096
	ds_read_b128 v[204:207], v166 offset:5120
	ds_read_b128 v[208:211], v166 offset:6144
	ds_read_b128 v[212:215], v166 offset:7168
	global_load_lds_dwordx4 v138, s[0:1]
	s_add_i32 m0, s29, 0xe000
	s_nop 0
	global_load_lds_dwordx4 v140, s[0:1]
	s_waitcnt lgkmcnt(8)
	s_barrier
	s_waitcnt lgkmcnt(0)
	v_mfma_f32_16x16x32_bf16 v[126:129], v[142:145], v[158:161], v[126:129]
	v_mfma_f32_16x16x32_bf16 v[126:129], v[146:149], v[168:171], v[126:129]
	v_mfma_f32_16x16x32_bf16 v[110:113], v[142:145], v[172:175], v[110:113]
	v_mfma_f32_16x16x32_bf16 v[110:113], v[146:149], v[176:179], v[110:113]
	v_mfma_f32_16x16x32_bf16 v[94:97], v[142:145], v[180:183], v[94:97]
	v_mfma_f32_16x16x32_bf16 v[94:97], v[146:149], v[204:207], v[94:97]
	v_mfma_f32_16x16x32_bf16 v[78:81], v[142:145], v[208:211], v[78:81]
	v_mfma_f32_16x16x32_bf16 v[78:81], v[146:149], v[212:215], v[78:81]
	v_mfma_f32_16x16x32_bf16 v[122:125], v[150:153], v[158:161], v[122:125]
	v_mfma_f32_16x16x32_bf16 v[122:125], v[154:157], v[168:171], v[122:125]
	v_mfma_f32_16x16x32_bf16 v[106:109], v[150:153], v[172:175], v[106:109]
	v_mfma_f32_16x16x32_bf16 v[106:109], v[154:157], v[176:179], v[106:109]
	v_mfma_f32_16x16x32_bf16 v[90:93], v[150:153], v[180:183], v[90:93]
	v_mfma_f32_16x16x32_bf16 v[90:93], v[154:157], v[204:207], v[90:93]
	v_mfma_f32_16x16x32_bf16 v[74:77], v[150:153], v[208:211], v[74:77]
	v_mfma_f32_16x16x32_bf16 v[74:77], v[154:157], v[212:215], v[74:77]
	s_barrier
	s_add_i32 s24, 0, 0x14000
	s_add_i32 s23, s23, s28
	ds_read_b128 v[216:219], v248 offset:16384
	ds_read_b128 v[220:223], v248 offset:17408
	ds_read_b128 v[224:227], v248 offset:18432
	ds_read_b128 v[228:231], v248 offset:19456
	s_add_u32 s70, s10, s6
	s_addc_u32 s71, s11, s7
	s_mov_b32 m0, s23
	s_nop 0
	global_load_lds_dwordx4 v132, s[10:11]
	s_add_i32 m0, s23, 0x2000
	s_nop 0
	global_load_lds_dwordx4 v136, s[10:11]
	s_barrier
	s_waitcnt lgkmcnt(0)
	v_mfma_f32_16x16x32_bf16 v[118:121], v[216:219], v[158:161], v[118:121]
	v_mfma_f32_16x16x32_bf16 v[118:121], v[220:223], v[168:171], v[118:121]
	v_mfma_f32_16x16x32_bf16 v[102:105], v[216:219], v[172:175], v[102:105]
	v_mfma_f32_16x16x32_bf16 v[102:105], v[220:223], v[176:179], v[102:105]
	v_mfma_f32_16x16x32_bf16 v[86:89], v[216:219], v[180:183], v[86:89]
	v_mfma_f32_16x16x32_bf16 v[86:89], v[220:223], v[204:207], v[86:89]
	v_mfma_f32_16x16x32_bf16 v[70:73], v[216:219], v[208:211], v[70:73]
	v_mfma_f32_16x16x32_bf16 v[70:73], v[220:223], v[212:215], v[70:73]
	v_mfma_f32_16x16x32_bf16 v[114:117], v[224:227], v[158:161], v[114:117]
	v_mfma_f32_16x16x32_bf16 v[114:117], v[228:231], v[168:171], v[114:117]
	v_mfma_f32_16x16x32_bf16 v[98:101], v[224:227], v[172:175], v[98:101]
	v_mfma_f32_16x16x32_bf16 v[98:101], v[228:231], v[176:179], v[98:101]
	v_mfma_f32_16x16x32_bf16 v[82:85], v[224:227], v[180:183], v[82:85]
	v_mfma_f32_16x16x32_bf16 v[82:85], v[228:231], v[204:207], v[82:85]
	v_mfma_f32_16x16x32_bf16 v[66:69], v[224:227], v[208:211], v[66:69]
	v_mfma_f32_16x16x32_bf16 v[66:69], v[228:231], v[212:215], v[66:69]
	s_barrier
	s_mov_b32 m0, s29
	s_add_u32 s72, s4, s6
	s_addc_u32 s73, s5, s7
	ds_read_b128 v[158:161], v166 offset:16384
	ds_read_b128 v[168:171], v166 offset:17408
	ds_read_b128 v[172:175], v166 offset:18432
	ds_read_b128 v[176:179], v166 offset:19456
	ds_read_b128 v[180:183], v166 offset:20480
	ds_read_b128 v[204:207], v166 offset:21504
	ds_read_b128 v[208:211], v166 offset:22528
	ds_read_b128 v[212:215], v166 offset:23552
	global_load_lds_dwordx4 v130, s[4:5]
	s_mov_b32 m0, s30
	s_nop 0
	global_load_lds_dwordx4 v134, s[4:5]
	s_barrier
	s_waitcnt lgkmcnt(0)
	v_mfma_f32_16x16x32_bf16 v[62:65], v[142:145], v[158:161], v[62:65]
	v_mfma_f32_16x16x32_bf16 v[62:65], v[146:149], v[168:171], v[62:65]
	v_mfma_f32_16x16x32_bf16 v[46:49], v[142:145], v[172:175], v[46:49]
	v_mfma_f32_16x16x32_bf16 v[46:49], v[146:149], v[176:179], v[46:49]
	v_mfma_f32_16x16x32_bf16 v[30:33], v[142:145], v[180:183], v[30:33]
	v_mfma_f32_16x16x32_bf16 v[30:33], v[146:149], v[204:207], v[30:33]
	v_mfma_f32_16x16x32_bf16 v[14:17], v[142:145], v[208:211], v[14:17]
	v_mfma_f32_16x16x32_bf16 v[14:17], v[146:149], v[212:215], v[14:17]
	v_mfma_f32_16x16x32_bf16 v[58:61], v[150:153], v[158:161], v[58:61]
	v_mfma_f32_16x16x32_bf16 v[58:61], v[154:157], v[168:171], v[58:61]
	v_mfma_f32_16x16x32_bf16 v[42:45], v[150:153], v[172:175], v[42:45]
	v_mfma_f32_16x16x32_bf16 v[42:45], v[154:157], v[176:179], v[42:45]
	v_mfma_f32_16x16x32_bf16 v[26:29], v[150:153], v[180:183], v[26:29]
	v_mfma_f32_16x16x32_bf16 v[26:29], v[154:157], v[204:207], v[26:29]
	v_mfma_f32_16x16x32_bf16 v[10:13], v[150:153], v[208:211], v[10:13]
	v_mfma_f32_16x16x32_bf16 v[10:13], v[154:157], v[212:215], v[10:13]
	s_barrier
	s_add_u32 s10, s10, s92
	s_addc_u32 s11, s11, 0
	s_add_i32 s23, s24, s28
	s_add_u32 s80, s10, s6
	s_addc_u32 s81, s11, s7
	s_mov_b32 m0, s23
	s_nop 0
	global_load_lds_dwordx4 v132, s[10:11]
	s_add_i32 m0, s23, 0x2000
	s_nop 0
	global_load_lds_dwordx4 v136, s[10:11]
	s_waitcnt vmcnt(6)
	s_barrier
	v_mfma_f32_16x16x32_bf16 v[54:57], v[216:219], v[158:161], v[54:57]
	v_mfma_f32_16x16x32_bf16 v[54:57], v[220:223], v[168:171], v[54:57]
	v_mfma_f32_16x16x32_bf16 v[38:41], v[216:219], v[172:175], v[38:41]
	v_mfma_f32_16x16x32_bf16 v[38:41], v[220:223], v[176:179], v[38:41]
	v_mfma_f32_16x16x32_bf16 v[22:25], v[216:219], v[180:183], v[22:25]
	v_mfma_f32_16x16x32_bf16 v[22:25], v[220:223], v[204:207], v[22:25]
	v_mfma_f32_16x16x32_bf16 v[6:9], v[216:219], v[208:211], v[6:9]
	v_mfma_f32_16x16x32_bf16 v[6:9], v[220:223], v[212:215], v[6:9]
	v_mfma_f32_16x16x32_bf16 v[50:53], v[224:227], v[158:161], v[50:53]
	v_mfma_f32_16x16x32_bf16 v[50:53], v[228:231], v[168:171], v[50:53]
	v_mfma_f32_16x16x32_bf16 v[34:37], v[224:227], v[172:175], v[34:37]
	v_mfma_f32_16x16x32_bf16 v[34:37], v[228:231], v[176:179], v[34:37]
	v_mfma_f32_16x16x32_bf16 v[18:21], v[224:227], v[180:183], v[18:21]
	v_mfma_f32_16x16x32_bf16 v[18:21], v[228:231], v[204:207], v[18:21]
	v_mfma_f32_16x16x32_bf16 v[2:5], v[224:227], v[208:211], v[2:5]
	v_mfma_f32_16x16x32_bf16 v[2:5], v[228:231], v[212:215], v[2:5]
	s_barrier
	s_add_i32 s10, 0, 0x18000
	ds_read_b128 v[142:145], v248 offset:32768
	ds_read_b128 v[146:149], v248 offset:33792
	ds_read_b128 v[150:153], v248 offset:34816
	ds_read_b128 v[154:157], v248 offset:35840
	s_add_u32 s4, s4, s92
	s_addc_u32 s5, s5, 0
	s_mov_b32 m0, s31
	ds_read_b128 v[158:161], v166 offset:32768
	ds_read_b128 v[168:171], v166 offset:33792
	ds_read_b128 v[172:175], v166 offset:34816
	ds_read_b128 v[176:179], v166 offset:35840
	ds_read_b128 v[180:183], v166 offset:36864
	ds_read_b128 v[204:207], v166 offset:37888
	ds_read_b128 v[208:211], v166 offset:38912
	ds_read_b128 v[212:215], v166 offset:39936
	global_load_lds_dwordx4 v130, s[4:5]
	s_mov_b32 m0, s34
	s_nop 0
	global_load_lds_dwordx4 v134, s[4:5]
	s_waitcnt lgkmcnt(8)
	s_barrier
	s_waitcnt lgkmcnt(0)
	v_mfma_f32_16x16x32_bf16 v[126:129], v[142:145], v[158:161], v[126:129]
	v_mfma_f32_16x16x32_bf16 v[126:129], v[146:149], v[168:171], v[126:129]
	v_mfma_f32_16x16x32_bf16 v[110:113], v[142:145], v[172:175], v[110:113]
	v_mfma_f32_16x16x32_bf16 v[110:113], v[146:149], v[176:179], v[110:113]
	v_mfma_f32_16x16x32_bf16 v[94:97], v[142:145], v[180:183], v[94:97]
	v_mfma_f32_16x16x32_bf16 v[94:97], v[146:149], v[204:207], v[94:97]
	v_mfma_f32_16x16x32_bf16 v[78:81], v[142:145], v[208:211], v[78:81]
	v_mfma_f32_16x16x32_bf16 v[78:81], v[146:149], v[212:215], v[78:81]
	v_mfma_f32_16x16x32_bf16 v[122:125], v[150:153], v[158:161], v[122:125]
	v_mfma_f32_16x16x32_bf16 v[122:125], v[154:157], v[168:171], v[122:125]
	v_mfma_f32_16x16x32_bf16 v[106:109], v[150:153], v[172:175], v[106:109]
	v_mfma_f32_16x16x32_bf16 v[106:109], v[154:157], v[176:179], v[106:109]
	v_mfma_f32_16x16x32_bf16 v[90:93], v[150:153], v[180:183], v[90:93]
	v_mfma_f32_16x16x32_bf16 v[90:93], v[154:157], v[204:207], v[90:93]
	v_mfma_f32_16x16x32_bf16 v[74:77], v[150:153], v[208:211], v[74:77]
	v_mfma_f32_16x16x32_bf16 v[74:77], v[154:157], v[212:215], v[74:77]
	s_barrier
	s_add_i32 s4, 0, 0x1c000
	s_add_i32 s5, s10, s28
	s_mov_b32 m0, s5
	ds_read_b128 v[216:219], v248 offset:49152
	ds_read_b128 v[220:223], v248 offset:50176
	ds_read_b128 v[224:227], v248 offset:51200
	ds_read_b128 v[228:231], v248 offset:52224
	global_load_lds_dwordx4 v132, s[70:71]
	s_add_i32 m0, s5, 0x2000
	s_nop 0
	global_load_lds_dwordx4 v136, s[70:71]
	s_barrier
	s_waitcnt lgkmcnt(0)
	v_mfma_f32_16x16x32_bf16 v[118:121], v[216:219], v[158:161], v[118:121]
	v_mfma_f32_16x16x32_bf16 v[118:121], v[220:223], v[168:171], v[118:121]
	v_mfma_f32_16x16x32_bf16 v[102:105], v[216:219], v[172:175], v[102:105]
	v_mfma_f32_16x16x32_bf16 v[102:105], v[220:223], v[176:179], v[102:105]
	v_mfma_f32_16x16x32_bf16 v[86:89], v[216:219], v[180:183], v[86:89]
	v_mfma_f32_16x16x32_bf16 v[86:89], v[220:223], v[204:207], v[86:89]
	v_mfma_f32_16x16x32_bf16 v[70:73], v[216:219], v[208:211], v[70:73]
	v_mfma_f32_16x16x32_bf16 v[70:73], v[220:223], v[212:215], v[70:73]
	v_mfma_f32_16x16x32_bf16 v[114:117], v[224:227], v[158:161], v[114:117]
	v_mfma_f32_16x16x32_bf16 v[114:117], v[228:231], v[168:171], v[114:117]
	v_mfma_f32_16x16x32_bf16 v[98:101], v[224:227], v[172:175], v[98:101]
	v_mfma_f32_16x16x32_bf16 v[98:101], v[228:231], v[176:179], v[98:101]
	v_mfma_f32_16x16x32_bf16 v[82:85], v[224:227], v[180:183], v[82:85]
	v_mfma_f32_16x16x32_bf16 v[82:85], v[228:231], v[204:207], v[82:85]
	v_mfma_f32_16x16x32_bf16 v[66:69], v[224:227], v[208:211], v[66:69]
	v_mfma_f32_16x16x32_bf16 v[66:69], v[228:231], v[212:215], v[66:69]
	s_barrier
	s_mov_b32 m0, s42
	ds_read_b128 v[158:161], v166 offset:49152
	ds_read_b128 v[168:171], v166 offset:50176
	ds_read_b128 v[172:175], v166 offset:51200
	ds_read_b128 v[176:179], v166 offset:52224
	ds_read_b128 v[180:183], v166 offset:53248
	ds_read_b128 v[204:207], v166 offset:54272
	ds_read_b128 v[208:211], v166 offset:55296
	ds_read_b128 v[212:215], v166 offset:56320
	global_load_lds_dwordx4 v130, s[72:73]
	s_mov_b32 m0, s43
	s_nop 0
	global_load_lds_dwordx4 v134, s[72:73]
	s_barrier
	s_waitcnt lgkmcnt(0)
	v_mfma_f32_16x16x32_bf16 v[62:65], v[142:145], v[158:161], v[62:65]
	v_mfma_f32_16x16x32_bf16 v[62:65], v[146:149], v[168:171], v[62:65]
	v_mfma_f32_16x16x32_bf16 v[46:49], v[142:145], v[172:175], v[46:49]
	v_mfma_f32_16x16x32_bf16 v[46:49], v[146:149], v[176:179], v[46:49]
	v_mfma_f32_16x16x32_bf16 v[30:33], v[142:145], v[180:183], v[30:33]
	v_mfma_f32_16x16x32_bf16 v[30:33], v[146:149], v[204:207], v[30:33]
	v_mfma_f32_16x16x32_bf16 v[14:17], v[142:145], v[208:211], v[14:17]
	v_mfma_f32_16x16x32_bf16 v[14:17], v[146:149], v[212:215], v[14:17]
	v_mfma_f32_16x16x32_bf16 v[58:61], v[150:153], v[158:161], v[58:61]
	v_mfma_f32_16x16x32_bf16 v[58:61], v[154:157], v[168:171], v[58:61]
	v_mfma_f32_16x16x32_bf16 v[42:45], v[150:153], v[172:175], v[42:45]
	v_mfma_f32_16x16x32_bf16 v[42:45], v[154:157], v[176:179], v[42:45]
	v_mfma_f32_16x16x32_bf16 v[26:29], v[150:153], v[180:183], v[26:29]
	v_mfma_f32_16x16x32_bf16 v[26:29], v[154:157], v[204:207], v[26:29]
	v_mfma_f32_16x16x32_bf16 v[10:13], v[150:153], v[208:211], v[10:13]
	v_mfma_f32_16x16x32_bf16 v[10:13], v[154:157], v[212:215], v[10:13]
	s_barrier
	s_add_i32 s4, s4, s28
	s_mov_b32 m0, s4
	s_nop 0
	global_load_lds_dwordx4 v132, s[80:81]
	s_add_i32 m0, s4, 0x2000
	s_nop 0
	global_load_lds_dwordx4 v136, s[80:81]
	s_add_u32 s0, s0, 0x100
	s_addc_u32 s1, s1, 0
	s_add_u32 s20, s20, 0x100
	s_addc_u32 s21, s21, 0
	s_cmp_ge_u32 s22, s35
	s_mov_b32 s4, s22
	s_waitcnt vmcnt(6)
	s_barrier
	v_mfma_f32_16x16x32_bf16 v[54:57], v[216:219], v[158:161], v[54:57]
	v_mfma_f32_16x16x32_bf16 v[54:57], v[220:223], v[168:171], v[54:57]
	v_mfma_f32_16x16x32_bf16 v[38:41], v[216:219], v[172:175], v[38:41]
	v_mfma_f32_16x16x32_bf16 v[38:41], v[220:223], v[176:179], v[38:41]
	v_mfma_f32_16x16x32_bf16 v[22:25], v[216:219], v[180:183], v[22:25]
	v_mfma_f32_16x16x32_bf16 v[22:25], v[220:223], v[204:207], v[22:25]
	v_mfma_f32_16x16x32_bf16 v[6:9], v[216:219], v[208:211], v[6:9]
	v_mfma_f32_16x16x32_bf16 v[6:9], v[220:223], v[212:215], v[6:9]
	v_mfma_f32_16x16x32_bf16 v[50:53], v[224:227], v[158:161], v[50:53]
	v_mfma_f32_16x16x32_bf16 v[50:53], v[228:231], v[168:171], v[50:53]
	v_mfma_f32_16x16x32_bf16 v[34:37], v[224:227], v[172:175], v[34:37]
	v_mfma_f32_16x16x32_bf16 v[34:37], v[228:231], v[176:179], v[34:37]
	v_mfma_f32_16x16x32_bf16 v[18:21], v[224:227], v[180:183], v[18:21]
	v_mfma_f32_16x16x32_bf16 v[18:21], v[228:231], v[204:207], v[18:21]
	v_mfma_f32_16x16x32_bf16 v[2:5], v[224:227], v[208:211], v[2:5]
	v_mfma_f32_16x16x32_bf16 v[2:5], v[228:231], v[212:215], v[2:5]
	s_barrier
	s_cbranch_scc0 .LBB0_282

.LBB0_346:
	s_add_u32 s0, s0, 0x80
	s_addc_u32 s1, s1, 0
	s_add_u32 s12, s4, 0x100
	s_addc_u32 s13, s5, 0
	s_mov_b32 s4, 0
	s_waitcnt lgkmcnt(0)
	s_waitcnt vmcnt(0)
	s_add_i32 s15, s4, 2
	s_add_u32 s10, s0, 0x80
	s_addc_u32 s5, s1, 0
	s_add_i32 s16, 0, 0x10000
	ds_read_b128 v[130:133], v248
	ds_read_b128 v[134:137], v248 offset:1024
	ds_read_b128 v[138:141], v248 offset:2048
	ds_read_b128 v[142:145], v248 offset:3072
	s_cmp_eq_u32 s79, s4
	s_cselect_b32 s4, s44, s10
	s_cselect_b32 s5, s45, s5
	s_cselect_b32 s11, s47, s13
	s_cselect_b32 s10, s46, s12
	s_add_i32 m0, s71, 0xc000
	ds_read_b128 v[158:161], v206
	ds_read_b128 v[162:165], v206 offset:1024
	ds_read_b128 v[166:169], v206 offset:2048
	ds_read_b128 v[170:173], v206 offset:3072
	ds_read_b128 v[174:177], v206 offset:4096
	ds_read_b128 v[178:181], v206 offset:5120
	ds_read_b128 v[182:185], v206 offset:6144
	ds_read_b128 v[208:211], v206 offset:7168
	global_load_lds_dwordx4 v154, s[0:1]
	s_add_i32 m0, s71, 0xe000
	s_nop 0
	global_load_lds_dwordx4 v156, s[0:1]
	s_waitcnt lgkmcnt(8)
	s_barrier
	s_waitcnt lgkmcnt(0)
	v_mfma_f32_16x16x32_bf16 v[126:129], v[130:133], v[158:161], 0
	v_mfma_f32_16x16x32_bf16 v[126:129], v[134:137], v[162:165], v[126:129]
	v_mfma_f32_16x16x32_bf16 v[110:113], v[130:133], v[166:169], 0
	v_mfma_f32_16x16x32_bf16 v[110:113], v[134:137], v[170:173], v[110:113]
	v_mfma_f32_16x16x32_bf16 v[94:97], v[130:133], v[174:177], 0
	v_mfma_f32_16x16x32_bf16 v[94:97], v[134:137], v[178:181], v[94:97]
	v_mfma_f32_16x16x32_bf16 v[78:81], v[130:133], v[182:185], 0
	v_mfma_f32_16x16x32_bf16 v[78:81], v[134:137], v[208:211], v[78:81]
	v_mfma_f32_16x16x32_bf16 v[122:125], v[138:141], v[158:161], 0
	v_mfma_f32_16x16x32_bf16 v[122:125], v[142:145], v[162:165], v[122:125]
	v_mfma_f32_16x16x32_bf16 v[106:109], v[138:141], v[166:169], 0
	v_mfma_f32_16x16x32_bf16 v[106:109], v[142:145], v[170:173], v[106:109]
	v_mfma_f32_16x16x32_bf16 v[90:93], v[138:141], v[174:177], 0
	v_mfma_f32_16x16x32_bf16 v[90:93], v[142:145], v[178:181], v[90:93]
	v_mfma_f32_16x16x32_bf16 v[74:77], v[138:141], v[182:185], 0
	v_mfma_f32_16x16x32_bf16 v[74:77], v[142:145], v[208:211], v[74:77]
	s_barrier
	s_add_i32 s17, 0, 0x14000
	s_add_i32 s16, s16, s70
	s_add_u32 s2, s10, s6
	s_addc_u32 s3, s11, s7
	s_mov_b32 m0, s16
	ds_read_b128 v[212:215], v248 offset:16384
	ds_read_b128 v[216:219], v248 offset:17408
	ds_read_b128 v[220:223], v248 offset:18432
	ds_read_b128 v[224:227], v248 offset:19456
	global_load_lds_dwordx4 v148, s[10:11]
	s_add_i32 m0, s16, 0x2000
	s_nop 0
	global_load_lds_dwordx4 v152, s[10:11]
	s_barrier
	s_waitcnt lgkmcnt(0)
	v_mfma_f32_16x16x32_bf16 v[118:121], v[212:215], v[158:161], 0
	v_mfma_f32_16x16x32_bf16 v[118:121], v[216:219], v[162:165], v[118:121]
	v_mfma_f32_16x16x32_bf16 v[102:105], v[212:215], v[166:169], 0
	v_mfma_f32_16x16x32_bf16 v[102:105], v[216:219], v[170:173], v[102:105]
	v_mfma_f32_16x16x32_bf16 v[86:89], v[212:215], v[174:177], 0
	v_mfma_f32_16x16x32_bf16 v[86:89], v[216:219], v[178:181], v[86:89]
	v_mfma_f32_16x16x32_bf16 v[70:73], v[212:215], v[182:185], 0
	v_mfma_f32_16x16x32_bf16 v[70:73], v[216:219], v[208:211], v[70:73]
	v_mfma_f32_16x16x32_bf16 v[114:117], v[220:223], v[158:161], 0
	v_mfma_f32_16x16x32_bf16 v[114:117], v[224:227], v[162:165], v[114:117]
	v_mfma_f32_16x16x32_bf16 v[98:101], v[220:223], v[166:169], 0
	v_mfma_f32_16x16x32_bf16 v[98:101], v[224:227], v[170:173], v[98:101]
	v_mfma_f32_16x16x32_bf16 v[82:85], v[220:223], v[174:177], 0
	v_mfma_f32_16x16x32_bf16 v[82:85], v[224:227], v[178:181], v[82:85]
	v_mfma_f32_16x16x32_bf16 v[66:69], v[220:223], v[182:185], 0
	v_mfma_f32_16x16x32_bf16 v[66:69], v[224:227], v[208:211], v[66:69]
	s_barrier
	s_mov_b32 m0, s71
	s_add_u32 s98, s4, s6
	s_addc_u32 s99, s5, s7
	ds_read_b128 v[158:161], v206 offset:16384
	ds_read_b128 v[162:165], v206 offset:17408
	ds_read_b128 v[166:169], v206 offset:18432
	ds_read_b128 v[170:173], v206 offset:19456
	ds_read_b128 v[174:177], v206 offset:20480
	ds_read_b128 v[178:181], v206 offset:21504
	ds_read_b128 v[182:185], v206 offset:22528
	ds_read_b128 v[208:211], v206 offset:23552
	global_load_lds_dwordx4 v146, s[4:5]
	s_mov_b32 m0, s72
	s_nop 0
	global_load_lds_dwordx4 v150, s[4:5]
	s_barrier
	s_waitcnt lgkmcnt(0)
	v_mfma_f32_16x16x32_bf16 v[62:65], v[130:133], v[158:161], 0
	v_mfma_f32_16x16x32_bf16 v[62:65], v[134:137], v[162:165], v[62:65]
	v_mfma_f32_16x16x32_bf16 v[46:49], v[130:133], v[166:169], 0
	v_mfma_f32_16x16x32_bf16 v[46:49], v[134:137], v[170:173], v[46:49]
	v_mfma_f32_16x16x32_bf16 v[30:33], v[130:133], v[174:177], 0
	v_mfma_f32_16x16x32_bf16 v[30:33], v[134:137], v[178:181], v[30:33]
	v_mfma_f32_16x16x32_bf16 v[14:17], v[130:133], v[182:185], 0
	v_mfma_f32_16x16x32_bf16 v[14:17], v[134:137], v[208:211], v[14:17]
	v_mfma_f32_16x16x32_bf16 v[58:61], v[138:141], v[158:161], 0
	v_mfma_f32_16x16x32_bf16 v[58:61], v[142:145], v[162:165], v[58:61]
	v_mfma_f32_16x16x32_bf16 v[42:45], v[138:141], v[166:169], 0
	v_mfma_f32_16x16x32_bf16 v[42:45], v[142:145], v[170:173], v[42:45]
	v_mfma_f32_16x16x32_bf16 v[26:29], v[138:141], v[174:177], 0
	v_mfma_f32_16x16x32_bf16 v[26:29], v[142:145], v[178:181], v[26:29]
	v_mfma_f32_16x16x32_bf16 v[10:13], v[138:141], v[182:185], 0
	v_mfma_f32_16x16x32_bf16 v[10:13], v[142:145], v[208:211], v[10:13]
	s_barrier
	s_add_u32 s10, s10, s92
	s_addc_u32 s11, s11, 0
	s_add_i32 s16, s17, s70
	v_lshl_add_u64 v[236:237], s[10:11], 0, v[148:149]
	s_mov_b32 m0, s16
	v_lshl_add_u64 v[238:239], s[10:11], 0, v[152:153]
	global_load_lds_dwordx4 v[236:237], off
	s_add_i32 m0, s16, 0x2000
	s_nop 0
	global_load_lds_dwordx4 v[238:239], off
	s_waitcnt vmcnt(6)
	s_barrier
	v_mfma_f32_16x16x32_bf16 v[54:57], v[212:215], v[158:161], 0
	v_mfma_f32_16x16x32_bf16 v[54:57], v[216:219], v[162:165], v[54:57]
	v_mfma_f32_16x16x32_bf16 v[38:41], v[212:215], v[166:169], 0
	v_mfma_f32_16x16x32_bf16 v[38:41], v[216:219], v[170:173], v[38:41]
	v_mfma_f32_16x16x32_bf16 v[22:25], v[212:215], v[174:177], 0
	v_mfma_f32_16x16x32_bf16 v[22:25], v[216:219], v[178:181], v[22:25]
	v_mfma_f32_16x16x32_bf16 v[6:9], v[212:215], v[182:185], 0
	v_mfma_f32_16x16x32_bf16 v[6:9], v[216:219], v[208:211], v[6:9]
	v_mfma_f32_16x16x32_bf16 v[50:53], v[220:223], v[158:161], 0
	v_mfma_f32_16x16x32_bf16 v[50:53], v[224:227], v[162:165], v[50:53]
	v_mfma_f32_16x16x32_bf16 v[34:37], v[220:223], v[166:169], 0
	v_mfma_f32_16x16x32_bf16 v[34:37], v[224:227], v[170:173], v[34:37]
	v_mfma_f32_16x16x32_bf16 v[18:21], v[220:223], v[174:177], 0
	v_mfma_f32_16x16x32_bf16 v[18:21], v[224:227], v[178:181], v[18:21]
	v_mfma_f32_16x16x32_bf16 v[2:5], v[220:223], v[182:185], 0
	v_mfma_f32_16x16x32_bf16 v[2:5], v[224:227], v[208:211], v[2:5]
	s_barrier
	s_add_i32 s10, 0, 0x18000
	ds_read_b128 v[130:133], v248 offset:32768
	ds_read_b128 v[134:137], v248 offset:33792
	ds_read_b128 v[138:141], v248 offset:34816
	ds_read_b128 v[142:145], v248 offset:35840
	s_add_u32 s4, s4, s92
	s_addc_u32 s5, s5, 0
	s_mov_b32 m0, s73
	ds_read_b128 v[158:161], v206 offset:32768
	ds_read_b128 v[162:165], v206 offset:33792
	ds_read_b128 v[166:169], v206 offset:34816
	ds_read_b128 v[170:173], v206 offset:35840
	ds_read_b128 v[174:177], v206 offset:36864
	ds_read_b128 v[178:181], v206 offset:37888
	ds_read_b128 v[182:185], v206 offset:38912
	ds_read_b128 v[208:211], v206 offset:39936
	global_load_lds_dwordx4 v146, s[4:5]
	s_mov_b32 m0, s74
	s_nop 0
	global_load_lds_dwordx4 v150, s[4:5]
	s_waitcnt lgkmcnt(8)
	s_barrier
	s_waitcnt lgkmcnt(0)
	v_mfma_f32_16x16x32_bf16 v[126:129], v[130:133], v[158:161], v[126:129]
	v_mfma_f32_16x16x32_bf16 v[126:129], v[134:137], v[162:165], v[126:129]
	v_mfma_f32_16x16x32_bf16 v[110:113], v[130:133], v[166:169], v[110:113]
	v_mfma_f32_16x16x32_bf16 v[110:113], v[134:137], v[170:173], v[110:113]
	v_mfma_f32_16x16x32_bf16 v[94:97], v[130:133], v[174:177], v[94:97]
	v_mfma_f32_16x16x32_bf16 v[94:97], v[134:137], v[178:181], v[94:97]
	v_mfma_f32_16x16x32_bf16 v[78:81], v[130:133], v[182:185], v[78:81]
	v_mfma_f32_16x16x32_bf16 v[78:81], v[134:137], v[208:211], v[78:81]
	v_mfma_f32_16x16x32_bf16 v[122:125], v[138:141], v[158:161], v[122:125]
	v_mfma_f32_16x16x32_bf16 v[122:125], v[142:145], v[162:165], v[122:125]
	v_mfma_f32_16x16x32_bf16 v[106:109], v[138:141], v[166:169], v[106:109]
	v_mfma_f32_16x16x32_bf16 v[106:109], v[142:145], v[170:173], v[106:109]
	v_mfma_f32_16x16x32_bf16 v[90:93], v[138:141], v[174:177], v[90:93]
	v_mfma_f32_16x16x32_bf16 v[90:93], v[142:145], v[178:181], v[90:93]
	v_mfma_f32_16x16x32_bf16 v[74:77], v[138:141], v[182:185], v[74:77]
	v_mfma_f32_16x16x32_bf16 v[74:77], v[142:145], v[208:211], v[74:77]
	s_barrier
	s_add_i32 s4, 0, 0x1c000
	s_add_i32 s5, s10, s70
	s_mov_b32 m0, s5
	ds_read_b128 v[212:215], v248 offset:49152
	ds_read_b128 v[216:219], v248 offset:50176
	ds_read_b128 v[220:223], v248 offset:51200
	ds_read_b128 v[224:227], v248 offset:52224
	global_load_lds_dwordx4 v148, s[2:3]
	s_add_i32 m0, s5, 0x2000
	s_nop 0
	global_load_lds_dwordx4 v152, s[2:3]
	s_barrier
	s_waitcnt lgkmcnt(0)
	v_mfma_f32_16x16x32_bf16 v[118:121], v[212:215], v[158:161], v[118:121]
	v_mfma_f32_16x16x32_bf16 v[118:121], v[216:219], v[162:165], v[118:121]
	v_mfma_f32_16x16x32_bf16 v[102:105], v[212:215], v[166:169], v[102:105]
	v_mfma_f32_16x16x32_bf16 v[102:105], v[216:219], v[170:173], v[102:105]
	v_mfma_f32_16x16x32_bf16 v[86:89], v[212:215], v[174:177], v[86:89]
	v_mfma_f32_16x16x32_bf16 v[86:89], v[216:219], v[178:181], v[86:89]
	v_mfma_f32_16x16x32_bf16 v[70:73], v[212:215], v[182:185], v[70:73]
	v_mfma_f32_16x16x32_bf16 v[70:73], v[216:219], v[208:211], v[70:73]
	v_mfma_f32_16x16x32_bf16 v[114:117], v[220:223], v[158:161], v[114:117]
	v_mfma_f32_16x16x32_bf16 v[114:117], v[224:227], v[162:165], v[114:117]
	v_mfma_f32_16x16x32_bf16 v[98:101], v[220:223], v[166:169], v[98:101]
	v_mfma_f32_16x16x32_bf16 v[98:101], v[224:227], v[170:173], v[98:101]
	v_mfma_f32_16x16x32_bf16 v[82:85], v[220:223], v[174:177], v[82:85]
	v_mfma_f32_16x16x32_bf16 v[82:85], v[224:227], v[178:181], v[82:85]
	v_mfma_f32_16x16x32_bf16 v[66:69], v[220:223], v[182:185], v[66:69]
	v_mfma_f32_16x16x32_bf16 v[66:69], v[224:227], v[208:211], v[66:69]
	s_barrier
	s_mov_b32 m0, s77
	ds_read_b128 v[158:161], v206 offset:49152
	ds_read_b128 v[162:165], v206 offset:50176
	ds_read_b128 v[166:169], v206 offset:51200
	ds_read_b128 v[170:173], v206 offset:52224
	ds_read_b128 v[174:177], v206 offset:53248
	ds_read_b128 v[178:181], v206 offset:54272
	ds_read_b128 v[182:185], v206 offset:55296
	ds_read_b128 v[208:211], v206 offset:56320
	global_load_lds_dwordx4 v146, s[98:99]
	s_mov_b32 m0, s78
	s_nop 0
	global_load_lds_dwordx4 v150, s[98:99]
	s_barrier
	s_waitcnt lgkmcnt(0)
	v_mfma_f32_16x16x32_bf16 v[62:65], v[130:133], v[158:161], v[62:65]
	v_mfma_f32_16x16x32_bf16 v[62:65], v[134:137], v[162:165], v[62:65]
	v_mfma_f32_16x16x32_bf16 v[46:49], v[130:133], v[166:169], v[46:49]
	v_mfma_f32_16x16x32_bf16 v[46:49], v[134:137], v[170:173], v[46:49]
	v_mfma_f32_16x16x32_bf16 v[30:33], v[130:133], v[174:177], v[30:33]
	v_mfma_f32_16x16x32_bf16 v[30:33], v[134:137], v[178:181], v[30:33]
	v_mfma_f32_16x16x32_bf16 v[14:17], v[130:133], v[182:185], v[14:17]
	v_mfma_f32_16x16x32_bf16 v[14:17], v[134:137], v[208:211], v[14:17]
	v_mfma_f32_16x16x32_bf16 v[58:61], v[138:141], v[158:161], v[58:61]
	v_mfma_f32_16x16x32_bf16 v[58:61], v[142:145], v[162:165], v[58:61]
	v_mfma_f32_16x16x32_bf16 v[42:45], v[138:141], v[166:169], v[42:45]
	v_mfma_f32_16x16x32_bf16 v[42:45], v[142:145], v[170:173], v[42:45]
	v_mfma_f32_16x16x32_bf16 v[26:29], v[138:141], v[174:177], v[26:29]
	v_mfma_f32_16x16x32_bf16 v[26:29], v[142:145], v[178:181], v[26:29]
	v_mfma_f32_16x16x32_bf16 v[10:13], v[138:141], v[182:185], v[10:13]
	v_mfma_f32_16x16x32_bf16 v[10:13], v[142:145], v[208:211], v[10:13]
	s_barrier
	s_add_i32 s4, s4, s70
	v_lshl_add_u64 v[130:131], v[236:237], 0, s[6:7]
	s_mov_b32 m0, s4
	s_nop 0
	global_load_lds_dwordx4 v[130:131], off
	v_lshl_add_u64 v[130:131], v[238:239], 0, s[6:7]
	s_add_i32 m0, s4, 0x2000
	s_nop 0
	global_load_lds_dwordx4 v[130:131], off
	s_add_u32 s0, s0, 0x100
	s_addc_u32 s1, s1, 0
	s_add_u32 s12, s12, 0x100
	s_addc_u32 s13, s13, 0
	s_cmp_ge_u32 s15, s75
	s_mov_b32 s4, s15
	s_waitcnt vmcnt(6)
	s_barrier
	v_mfma_f32_16x16x32_bf16 v[54:57], v[212:215], v[158:161], v[54:57]
	v_mfma_f32_16x16x32_bf16 v[54:57], v[216:219], v[162:165], v[54:57]
	v_mfma_f32_16x16x32_bf16 v[38:41], v[212:215], v[166:169], v[38:41]
	v_mfma_f32_16x16x32_bf16 v[38:41], v[216:219], v[170:173], v[38:41]
	v_mfma_f32_16x16x32_bf16 v[22:25], v[212:215], v[174:177], v[22:25]
	v_mfma_f32_16x16x32_bf16 v[22:25], v[216:219], v[178:181], v[22:25]
	v_mfma_f32_16x16x32_bf16 v[6:9], v[212:215], v[182:185], v[6:9]
	v_mfma_f32_16x16x32_bf16 v[6:9], v[216:219], v[208:211], v[6:9]
	v_mfma_f32_16x16x32_bf16 v[50:53], v[220:223], v[158:161], v[50:53]
	v_mfma_f32_16x16x32_bf16 v[50:53], v[224:227], v[162:165], v[50:53]
	v_mfma_f32_16x16x32_bf16 v[34:37], v[220:223], v[166:169], v[34:37]
	v_mfma_f32_16x16x32_bf16 v[34:37], v[224:227], v[170:173], v[34:37]
	v_mfma_f32_16x16x32_bf16 v[18:21], v[220:223], v[174:177], v[18:21]
	v_mfma_f32_16x16x32_bf16 v[18:21], v[224:227], v[178:181], v[18:21]
	v_mfma_f32_16x16x32_bf16 v[2:5], v[220:223], v[182:185], v[2:5]
	v_mfma_f32_16x16x32_bf16 v[2:5], v[224:227], v[208:211], v[2:5]
	s_barrier
	s_cbranch_scc1 .Lkexit_347
.LBB0_347:
	s_add_i32 s15, s4, 2
	s_add_u32 s10, s0, 0x80
	s_addc_u32 s5, s1, 0
	s_add_i32 s16, 0, 0x10000
	ds_read_b128 v[130:133], v248
	ds_read_b128 v[134:137], v248 offset:1024
	ds_read_b128 v[138:141], v248 offset:2048
	ds_read_b128 v[142:145], v248 offset:3072
	s_cmp_eq_u32 s79, s4
	s_cselect_b32 s4, s44, s10
	s_cselect_b32 s5, s45, s5
	s_cselect_b32 s11, s47, s13
	s_cselect_b32 s10, s46, s12
	s_add_i32 m0, s71, 0xc000
	ds_read_b128 v[158:161], v206
	ds_read_b128 v[162:165], v206 offset:1024
	ds_read_b128 v[166:169], v206 offset:2048
	ds_read_b128 v[170:173], v206 offset:3072
	ds_read_b128 v[174:177], v206 offset:4096
	ds_read_b128 v[178:181], v206 offset:5120
	ds_read_b128 v[182:185], v206 offset:6144
	ds_read_b128 v[208:211], v206 offset:7168
	global_load_lds_dwordx4 v154, s[0:1]
	s_add_i32 m0, s71, 0xe000
	s_nop 0
	global_load_lds_dwordx4 v156, s[0:1]
	s_waitcnt lgkmcnt(8)
	s_barrier
	s_waitcnt lgkmcnt(0)
	v_mfma_f32_16x16x32_bf16 v[126:129], v[130:133], v[158:161], v[126:129]
	v_mfma_f32_16x16x32_bf16 v[126:129], v[134:137], v[162:165], v[126:129]
	v_mfma_f32_16x16x32_bf16 v[110:113], v[130:133], v[166:169], v[110:113]
	v_mfma_f32_16x16x32_bf16 v[110:113], v[134:137], v[170:173], v[110:113]
	v_mfma_f32_16x16x32_bf16 v[94:97], v[130:133], v[174:177], v[94:97]
	v_mfma_f32_16x16x32_bf16 v[94:97], v[134:137], v[178:181], v[94:97]
	v_mfma_f32_16x16x32_bf16 v[78:81], v[130:133], v[182:185], v[78:81]
	v_mfma_f32_16x16x32_bf16 v[78:81], v[134:137], v[208:211], v[78:81]
	v_mfma_f32_16x16x32_bf16 v[122:125], v[138:141], v[158:161], v[122:125]
	v_mfma_f32_16x16x32_bf16 v[122:125], v[142:145], v[162:165], v[122:125]
	v_mfma_f32_16x16x32_bf16 v[106:109], v[138:141], v[166:169], v[106:109]
	v_mfma_f32_16x16x32_bf16 v[106:109], v[142:145], v[170:173], v[106:109]
	v_mfma_f32_16x16x32_bf16 v[90:93], v[138:141], v[174:177], v[90:93]
	v_mfma_f32_16x16x32_bf16 v[90:93], v[142:145], v[178:181], v[90:93]
	v_mfma_f32_16x16x32_bf16 v[74:77], v[138:141], v[182:185], v[74:77]
	v_mfma_f32_16x16x32_bf16 v[74:77], v[142:145], v[208:211], v[74:77]
	s_barrier
	s_add_i32 s17, 0, 0x14000
	s_add_i32 s16, s16, s70
	s_add_u32 s2, s10, s6
	s_addc_u32 s3, s11, s7
	s_mov_b32 m0, s16
	ds_read_b128 v[212:215], v248 offset:16384
	ds_read_b128 v[216:219], v248 offset:17408
	ds_read_b128 v[220:223], v248 offset:18432
	ds_read_b128 v[224:227], v248 offset:19456
	global_load_lds_dwordx4 v148, s[10:11]
	s_add_i32 m0, s16, 0x2000
	s_nop 0
	global_load_lds_dwordx4 v152, s[10:11]
	s_barrier
	s_waitcnt lgkmcnt(0)
	v_mfma_f32_16x16x32_bf16 v[118:121], v[212:215], v[158:161], v[118:121]
	v_mfma_f32_16x16x32_bf16 v[118:121], v[216:219], v[162:165], v[118:121]
	v_mfma_f32_16x16x32_bf16 v[102:105], v[212:215], v[166:169], v[102:105]
	v_mfma_f32_16x16x32_bf16 v[102:105], v[216:219], v[170:173], v[102:105]
	v_mfma_f32_16x16x32_bf16 v[86:89], v[212:215], v[174:177], v[86:89]
	v_mfma_f32_16x16x32_bf16 v[86:89], v[216:219], v[178:181], v[86:89]
	v_mfma_f32_16x16x32_bf16 v[70:73], v[212:215], v[182:185], v[70:73]
	v_mfma_f32_16x16x32_bf16 v[70:73], v[216:219], v[208:211], v[70:73]
	v_mfma_f32_16x16x32_bf16 v[114:117], v[220:223], v[158:161], v[114:117]
	v_mfma_f32_16x16x32_bf16 v[114:117], v[224:227], v[162:165], v[114:117]
	v_mfma_f32_16x16x32_bf16 v[98:101], v[220:223], v[166:169], v[98:101]
	v_mfma_f32_16x16x32_bf16 v[98:101], v[224:227], v[170:173], v[98:101]
	v_mfma_f32_16x16x32_bf16 v[82:85], v[220:223], v[174:177], v[82:85]
	v_mfma_f32_16x16x32_bf16 v[82:85], v[224:227], v[178:181], v[82:85]
	v_mfma_f32_16x16x32_bf16 v[66:69], v[220:223], v[182:185], v[66:69]
	v_mfma_f32_16x16x32_bf16 v[66:69], v[224:227], v[208:211], v[66:69]
	s_barrier
	s_mov_b32 m0, s71
	s_add_u32 s98, s4, s6
	s_addc_u32 s99, s5, s7
	ds_read_b128 v[158:161], v206 offset:16384
	ds_read_b128 v[162:165], v206 offset:17408
	ds_read_b128 v[166:169], v206 offset:18432
	ds_read_b128 v[170:173], v206 offset:19456
	ds_read_b128 v[174:177], v206 offset:20480
	ds_read_b128 v[178:181], v206 offset:21504
	ds_read_b128 v[182:185], v206 offset:22528
	ds_read_b128 v[208:211], v206 offset:23552
	global_load_lds_dwordx4 v146, s[4:5]
	s_mov_b32 m0, s72
	s_nop 0
	global_load_lds_dwordx4 v150, s[4:5]
	s_barrier
	s_waitcnt lgkmcnt(0)
	v_mfma_f32_16x16x32_bf16 v[62:65], v[130:133], v[158:161], v[62:65]
	v_mfma_f32_16x16x32_bf16 v[62:65], v[134:137], v[162:165], v[62:65]
	v_mfma_f32_16x16x32_bf16 v[46:49], v[130:133], v[166:169], v[46:49]
	v_mfma_f32_16x16x32_bf16 v[46:49], v[134:137], v[170:173], v[46:49]
	v_mfma_f32_16x16x32_bf16 v[30:33], v[130:133], v[174:177], v[30:33]
	v_mfma_f32_16x16x32_bf16 v[30:33], v[134:137], v[178:181], v[30:33]
	v_mfma_f32_16x16x32_bf16 v[14:17], v[130:133], v[182:185], v[14:17]
	v_mfma_f32_16x16x32_bf16 v[14:17], v[134:137], v[208:211], v[14:17]
	v_mfma_f32_16x16x32_bf16 v[58:61], v[138:141], v[158:161], v[58:61]
	v_mfma_f32_16x16x32_bf16 v[58:61], v[142:145], v[162:165], v[58:61]
	v_mfma_f32_16x16x32_bf16 v[42:45], v[138:141], v[166:169], v[42:45]
	v_mfma_f32_16x16x32_bf16 v[42:45], v[142:145], v[170:173], v[42:45]
	v_mfma_f32_16x16x32_bf16 v[26:29], v[138:141], v[174:177], v[26:29]
	v_mfma_f32_16x16x32_bf16 v[26:29], v[142:145], v[178:181], v[26:29]
	v_mfma_f32_16x16x32_bf16 v[10:13], v[138:141], v[182:185], v[10:13]
	v_mfma_f32_16x16x32_bf16 v[10:13], v[142:145], v[208:211], v[10:13]
	s_barrier
	s_add_u32 s10, s10, s92
	s_addc_u32 s11, s11, 0
	s_add_i32 s16, s17, s70
	v_lshl_add_u64 v[236:237], s[10:11], 0, v[148:149]
	s_mov_b32 m0, s16
	v_lshl_add_u64 v[238:239], s[10:11], 0, v[152:153]
	global_load_lds_dwordx4 v[236:237], off
	s_add_i32 m0, s16, 0x2000
	s_nop 0
	global_load_lds_dwordx4 v[238:239], off
	s_waitcnt vmcnt(6)
	s_barrier
	v_mfma_f32_16x16x32_bf16 v[54:57], v[212:215], v[158:161], v[54:57]
	v_mfma_f32_16x16x32_bf16 v[54:57], v[216:219], v[162:165], v[54:57]
	v_mfma_f32_16x16x32_bf16 v[38:41], v[212:215], v[166:169], v[38:41]
	v_mfma_f32_16x16x32_bf16 v[38:41], v[216:219], v[170:173], v[38:41]
	v_mfma_f32_16x16x32_bf16 v[22:25], v[212:215], v[174:177], v[22:25]
	v_mfma_f32_16x16x32_bf16 v[22:25], v[216:219], v[178:181], v[22:25]
	v_mfma_f32_16x16x32_bf16 v[6:9], v[212:215], v[182:185], v[6:9]
	v_mfma_f32_16x16x32_bf16 v[6:9], v[216:219], v[208:211], v[6:9]
	v_mfma_f32_16x16x32_bf16 v[50:53], v[220:223], v[158:161], v[50:53]
	v_mfma_f32_16x16x32_bf16 v[50:53], v[224:227], v[162:165], v[50:53]
	v_mfma_f32_16x16x32_bf16 v[34:37], v[220:223], v[166:169], v[34:37]
	v_mfma_f32_16x16x32_bf16 v[34:37], v[224:227], v[170:173], v[34:37]
	v_mfma_f32_16x16x32_bf16 v[18:21], v[220:223], v[174:177], v[18:21]
	v_mfma_f32_16x16x32_bf16 v[18:21], v[224:227], v[178:181], v[18:21]
	v_mfma_f32_16x16x32_bf16 v[2:5], v[220:223], v[182:185], v[2:5]
	v_mfma_f32_16x16x32_bf16 v[2:5], v[224:227], v[208:211], v[2:5]
	s_barrier
	s_add_i32 s10, 0, 0x18000
	ds_read_b128 v[130:133], v248 offset:32768
	ds_read_b128 v[134:137], v248 offset:33792
	ds_read_b128 v[138:141], v248 offset:34816
	ds_read_b128 v[142:145], v248 offset:35840
	s_add_u32 s4, s4, s92
	s_addc_u32 s5, s5, 0
	s_mov_b32 m0, s73
	ds_read_b128 v[158:161], v206 offset:32768
	ds_read_b128 v[162:165], v206 offset:33792
	ds_read_b128 v[166:169], v206 offset:34816
	ds_read_b128 v[170:173], v206 offset:35840
	ds_read_b128 v[174:177], v206 offset:36864
	ds_read_b128 v[178:181], v206 offset:37888
	ds_read_b128 v[182:185], v206 offset:38912
	ds_read_b128 v[208:211], v206 offset:39936
	global_load_lds_dwordx4 v146, s[4:5]
	s_mov_b32 m0, s74
	s_nop 0
	global_load_lds_dwordx4 v150, s[4:5]
	s_waitcnt lgkmcnt(8)
	s_barrier
	s_waitcnt lgkmcnt(0)
	v_mfma_f32_16x16x32_bf16 v[126:129], v[130:133], v[158:161], v[126:129]
	v_mfma_f32_16x16x32_bf16 v[126:129], v[134:137], v[162:165], v[126:129]
	v_mfma_f32_16x16x32_bf16 v[110:113], v[130:133], v[166:169], v[110:113]
	v_mfma_f32_16x16x32_bf16 v[110:113], v[134:137], v[170:173], v[110:113]
	v_mfma_f32_16x16x32_bf16 v[94:97], v[130:133], v[174:177], v[94:97]
	v_mfma_f32_16x16x32_bf16 v[94:97], v[134:137], v[178:181], v[94:97]
	v_mfma_f32_16x16x32_bf16 v[78:81], v[130:133], v[182:185], v[78:81]
	v_mfma_f32_16x16x32_bf16 v[78:81], v[134:137], v[208:211], v[78:81]
	v_mfma_f32_16x16x32_bf16 v[122:125], v[138:141], v[158:161], v[122:125]
	v_mfma_f32_16x16x32_bf16 v[122:125], v[142:145], v[162:165], v[122:125]
	v_mfma_f32_16x16x32_bf16 v[106:109], v[138:141], v[166:169], v[106:109]
	v_mfma_f32_16x16x32_bf16 v[106:109], v[142:145], v[170:173], v[106:109]
	v_mfma_f32_16x16x32_bf16 v[90:93], v[138:141], v[174:177], v[90:93]
	v_mfma_f32_16x16x32_bf16 v[90:93], v[142:145], v[178:181], v[90:93]
	v_mfma_f32_16x16x32_bf16 v[74:77], v[138:141], v[182:185], v[74:77]
	v_mfma_f32_16x16x32_bf16 v[74:77], v[142:145], v[208:211], v[74:77]
	s_barrier
	s_add_i32 s4, 0, 0x1c000
	s_add_i32 s5, s10, s70
	s_mov_b32 m0, s5
	ds_read_b128 v[212:215], v248 offset:49152
	ds_read_b128 v[216:219], v248 offset:50176
	ds_read_b128 v[220:223], v248 offset:51200
	ds_read_b128 v[224:227], v248 offset:52224
	global_load_lds_dwordx4 v148, s[2:3]
	s_add_i32 m0, s5, 0x2000
	s_nop 0
	global_load_lds_dwordx4 v152, s[2:3]
	s_barrier
	s_waitcnt lgkmcnt(0)
	v_mfma_f32_16x16x32_bf16 v[118:121], v[212:215], v[158:161], v[118:121]
	v_mfma_f32_16x16x32_bf16 v[118:121], v[216:219], v[162:165], v[118:121]
	v_mfma_f32_16x16x32_bf16 v[102:105], v[212:215], v[166:169], v[102:105]
	v_mfma_f32_16x16x32_bf16 v[102:105], v[216:219], v[170:173], v[102:105]
	v_mfma_f32_16x16x32_bf16 v[86:89], v[212:215], v[174:177], v[86:89]
	v_mfma_f32_16x16x32_bf16 v[86:89], v[216:219], v[178:181], v[86:89]
	v_mfma_f32_16x16x32_bf16 v[70:73], v[212:215], v[182:185], v[70:73]
	v_mfma_f32_16x16x32_bf16 v[70:73], v[216:219], v[208:211], v[70:73]
	v_mfma_f32_16x16x32_bf16 v[114:117], v[220:223], v[158:161], v[114:117]
	v_mfma_f32_16x16x32_bf16 v[114:117], v[224:227], v[162:165], v[114:117]
	v_mfma_f32_16x16x32_bf16 v[98:101], v[220:223], v[166:169], v[98:101]
	v_mfma_f32_16x16x32_bf16 v[98:101], v[224:227], v[170:173], v[98:101]
	v_mfma_f32_16x16x32_bf16 v[82:85], v[220:223], v[174:177], v[82:85]
	v_mfma_f32_16x16x32_bf16 v[82:85], v[224:227], v[178:181], v[82:85]
	v_mfma_f32_16x16x32_bf16 v[66:69], v[220:223], v[182:185], v[66:69]
	v_mfma_f32_16x16x32_bf16 v[66:69], v[224:227], v[208:211], v[66:69]
	s_barrier
	s_mov_b32 m0, s77
	ds_read_b128 v[158:161], v206 offset:49152
	ds_read_b128 v[162:165], v206 offset:50176
	ds_read_b128 v[166:169], v206 offset:51200
	ds_read_b128 v[170:173], v206 offset:52224
	ds_read_b128 v[174:177], v206 offset:53248
	ds_read_b128 v[178:181], v206 offset:54272
	ds_read_b128 v[182:185], v206 offset:55296
	ds_read_b128 v[208:211], v206 offset:56320
	global_load_lds_dwordx4 v146, s[98:99]
	s_mov_b32 m0, s78
	s_nop 0
	global_load_lds_dwordx4 v150, s[98:99]
	s_barrier
	s_waitcnt lgkmcnt(0)
	v_mfma_f32_16x16x32_bf16 v[62:65], v[130:133], v[158:161], v[62:65]
	v_mfma_f32_16x16x32_bf16 v[62:65], v[134:137], v[162:165], v[62:65]
	v_mfma_f32_16x16x32_bf16 v[46:49], v[130:133], v[166:169], v[46:49]
	v_mfma_f32_16x16x32_bf16 v[46:49], v[134:137], v[170:173], v[46:49]
	v_mfma_f32_16x16x32_bf16 v[30:33], v[130:133], v[174:177], v[30:33]
	v_mfma_f32_16x16x32_bf16 v[30:33], v[134:137], v[178:181], v[30:33]
	v_mfma_f32_16x16x32_bf16 v[14:17], v[130:133], v[182:185], v[14:17]
	v_mfma_f32_16x16x32_bf16 v[14:17], v[134:137], v[208:211], v[14:17]
	v_mfma_f32_16x16x32_bf16 v[58:61], v[138:141], v[158:161], v[58:61]
	v_mfma_f32_16x16x32_bf16 v[58:61], v[142:145], v[162:165], v[58:61]
	v_mfma_f32_16x16x32_bf16 v[42:45], v[138:141], v[166:169], v[42:45]
	v_mfma_f32_16x16x32_bf16 v[42:45], v[142:145], v[170:173], v[42:45]
	v_mfma_f32_16x16x32_bf16 v[26:29], v[138:141], v[174:177], v[26:29]
	v_mfma_f32_16x16x32_bf16 v[26:29], v[142:145], v[178:181], v[26:29]
	v_mfma_f32_16x16x32_bf16 v[10:13], v[138:141], v[182:185], v[10:13]
	v_mfma_f32_16x16x32_bf16 v[10:13], v[142:145], v[208:211], v[10:13]
	s_barrier
	s_add_i32 s4, s4, s70
	v_lshl_add_u64 v[130:131], v[236:237], 0, s[6:7]
	s_mov_b32 m0, s4
	s_nop 0
	global_load_lds_dwordx4 v[130:131], off
	v_lshl_add_u64 v[130:131], v[238:239], 0, s[6:7]
	s_add_i32 m0, s4, 0x2000
	s_nop 0
	global_load_lds_dwordx4 v[130:131], off
	s_add_u32 s0, s0, 0x100
	s_addc_u32 s1, s1, 0
	s_add_u32 s12, s12, 0x100
	s_addc_u32 s13, s13, 0
	s_cmp_ge_u32 s15, s75
	s_mov_b32 s4, s15
	s_waitcnt vmcnt(6)
	s_barrier
	v_mfma_f32_16x16x32_bf16 v[54:57], v[212:215], v[158:161], v[54:57]
	v_mfma_f32_16x16x32_bf16 v[54:57], v[216:219], v[162:165], v[54:57]
	v_mfma_f32_16x16x32_bf16 v[38:41], v[212:215], v[166:169], v[38:41]
	v_mfma_f32_16x16x32_bf16 v[38:41], v[216:219], v[170:173], v[38:41]
	v_mfma_f32_16x16x32_bf16 v[22:25], v[212:215], v[174:177], v[22:25]
	v_mfma_f32_16x16x32_bf16 v[22:25], v[216:219], v[178:181], v[22:25]
	v_mfma_f32_16x16x32_bf16 v[6:9], v[212:215], v[182:185], v[6:9]
	v_mfma_f32_16x16x32_bf16 v[6:9], v[216:219], v[208:211], v[6:9]
	v_mfma_f32_16x16x32_bf16 v[50:53], v[220:223], v[158:161], v[50:53]
	v_mfma_f32_16x16x32_bf16 v[50:53], v[224:227], v[162:165], v[50:53]
	v_mfma_f32_16x16x32_bf16 v[34:37], v[220:223], v[166:169], v[34:37]
	v_mfma_f32_16x16x32_bf16 v[34:37], v[224:227], v[170:173], v[34:37]
	v_mfma_f32_16x16x32_bf16 v[18:21], v[220:223], v[174:177], v[18:21]
	v_mfma_f32_16x16x32_bf16 v[18:21], v[224:227], v[178:181], v[18:21]
	v_mfma_f32_16x16x32_bf16 v[2:5], v[220:223], v[182:185], v[2:5]
	v_mfma_f32_16x16x32_bf16 v[2:5], v[224:227], v[208:211], v[2:5]
	s_barrier
	s_cbranch_scc0 .LBB0_347

.LBB0_663:
	s_add_u32 s0, s0, 0x80
	s_addc_u32 s1, s1, 0
	s_add_u32 s49, s4, 0x100
	s_addc_u32 s65, s5, 0
	s_mov_b32 s4, 0
	s_waitcnt lgkmcnt(0)
	s_waitcnt vmcnt(0)
	s_add_i32 s66, s4, 2
	s_add_u32 s18, s0, 0x80
	s_addc_u32 s5, s1, 0
	s_add_i32 s68, 0, 0x10000
	ds_read_b128 v[142:145], v248
	ds_read_b128 v[146:149], v248 offset:1024
	ds_read_b128 v[156:159], v248 offset:2048
	ds_read_b128 v[160:163], v248 offset:3072
	s_cmp_eq_u32 s43, s4
	s_cselect_b32 s4, s10, s18
	s_cselect_b32 s5, s11, s5
	s_cselect_b32 s19, s13, s65
	s_cselect_b32 s18, s12, s49
	s_add_i32 m0, s28, 0xc000
	ds_read_b128 v[164:167], v154
	ds_read_b128 v[168:171], v154 offset:1024
	ds_read_b128 v[172:175], v154 offset:2048
	ds_read_b128 v[176:179], v154 offset:3072
	ds_read_b128 v[180:183], v154 offset:4096
	ds_read_b128 v[204:207], v154 offset:5120
	ds_read_b128 v[208:211], v154 offset:6144
	ds_read_b128 v[212:215], v154 offset:7168
	global_load_lds_dwordx4 v138, s[0:1]
	s_add_i32 m0, s28, 0xe000
	s_nop 0
	global_load_lds_dwordx4 v140, s[0:1]
	s_waitcnt lgkmcnt(8)
	s_barrier
	s_waitcnt lgkmcnt(0)
	v_mfma_f32_16x16x32_bf16 v[126:129], v[142:145], v[164:167], 0
	v_mfma_f32_16x16x32_bf16 v[126:129], v[146:149], v[168:171], v[126:129]
	v_mfma_f32_16x16x32_bf16 v[110:113], v[142:145], v[172:175], 0
	v_mfma_f32_16x16x32_bf16 v[110:113], v[146:149], v[176:179], v[110:113]
	v_mfma_f32_16x16x32_bf16 v[94:97], v[142:145], v[180:183], 0
	v_mfma_f32_16x16x32_bf16 v[94:97], v[146:149], v[204:207], v[94:97]
	v_mfma_f32_16x16x32_bf16 v[78:81], v[142:145], v[208:211], 0
	v_mfma_f32_16x16x32_bf16 v[78:81], v[146:149], v[212:215], v[78:81]
	v_mfma_f32_16x16x32_bf16 v[122:125], v[156:159], v[164:167], 0
	v_mfma_f32_16x16x32_bf16 v[122:125], v[160:163], v[168:171], v[122:125]
	v_mfma_f32_16x16x32_bf16 v[106:109], v[156:159], v[172:175], 0
	v_mfma_f32_16x16x32_bf16 v[106:109], v[160:163], v[176:179], v[106:109]
	v_mfma_f32_16x16x32_bf16 v[90:93], v[156:159], v[180:183], 0
	v_mfma_f32_16x16x32_bf16 v[90:93], v[160:163], v[204:207], v[90:93]
	v_mfma_f32_16x16x32_bf16 v[74:77], v[156:159], v[208:211], 0
	v_mfma_f32_16x16x32_bf16 v[74:77], v[160:163], v[212:215], v[74:77]
	s_barrier
	s_add_i32 s69, 0, 0x14000
	s_add_i32 s68, s68, s25
	ds_read_b128 v[216:219], v248 offset:16384
	ds_read_b128 v[220:223], v248 offset:17408
	ds_read_b128 v[224:227], v248 offset:18432
	ds_read_b128 v[228:231], v248 offset:19456
	s_add_u32 s70, s18, s6
	s_addc_u32 s71, s19, s7
	s_mov_b32 m0, s68
	s_nop 0
	global_load_lds_dwordx4 v132, s[18:19]
	s_add_i32 m0, s68, 0x2000
	s_nop 0
	global_load_lds_dwordx4 v136, s[18:19]
	s_barrier
	s_waitcnt lgkmcnt(0)
	v_mfma_f32_16x16x32_bf16 v[118:121], v[216:219], v[164:167], 0
	v_mfma_f32_16x16x32_bf16 v[118:121], v[220:223], v[168:171], v[118:121]
	v_mfma_f32_16x16x32_bf16 v[102:105], v[216:219], v[172:175], 0
	v_mfma_f32_16x16x32_bf16 v[102:105], v[220:223], v[176:179], v[102:105]
	v_mfma_f32_16x16x32_bf16 v[86:89], v[216:219], v[180:183], 0
	v_mfma_f32_16x16x32_bf16 v[86:89], v[220:223], v[204:207], v[86:89]
	v_mfma_f32_16x16x32_bf16 v[70:73], v[216:219], v[208:211], 0
	v_mfma_f32_16x16x32_bf16 v[70:73], v[220:223], v[212:215], v[70:73]
	v_mfma_f32_16x16x32_bf16 v[114:117], v[224:227], v[164:167], 0
	v_mfma_f32_16x16x32_bf16 v[114:117], v[228:231], v[168:171], v[114:117]
	v_mfma_f32_16x16x32_bf16 v[98:101], v[224:227], v[172:175], 0
	v_mfma_f32_16x16x32_bf16 v[98:101], v[228:231], v[176:179], v[98:101]
	v_mfma_f32_16x16x32_bf16 v[82:85], v[224:227], v[180:183], 0
	v_mfma_f32_16x16x32_bf16 v[82:85], v[228:231], v[204:207], v[82:85]
	v_mfma_f32_16x16x32_bf16 v[66:69], v[224:227], v[208:211], 0
	v_mfma_f32_16x16x32_bf16 v[66:69], v[228:231], v[212:215], v[66:69]
	s_barrier
	s_mov_b32 m0, s28
	s_add_u32 s72, s4, s6
	s_addc_u32 s73, s5, s7
	ds_read_b128 v[164:167], v154 offset:16384
	ds_read_b128 v[168:171], v154 offset:17408
	ds_read_b128 v[172:175], v154 offset:18432
	ds_read_b128 v[176:179], v154 offset:19456
	ds_read_b128 v[180:183], v154 offset:20480
	ds_read_b128 v[204:207], v154 offset:21504
	ds_read_b128 v[208:211], v154 offset:22528
	ds_read_b128 v[212:215], v154 offset:23552
	global_load_lds_dwordx4 v130, s[4:5]
	s_mov_b32 m0, s29
	s_nop 0
	global_load_lds_dwordx4 v134, s[4:5]
	s_barrier
	s_waitcnt lgkmcnt(0)
	v_mfma_f32_16x16x32_bf16 v[62:65], v[142:145], v[164:167], 0
	v_mfma_f32_16x16x32_bf16 v[62:65], v[146:149], v[168:171], v[62:65]
	v_mfma_f32_16x16x32_bf16 v[46:49], v[142:145], v[172:175], 0
	v_mfma_f32_16x16x32_bf16 v[46:49], v[146:149], v[176:179], v[46:49]
	v_mfma_f32_16x16x32_bf16 v[30:33], v[142:145], v[180:183], 0
	v_mfma_f32_16x16x32_bf16 v[30:33], v[146:149], v[204:207], v[30:33]
	v_mfma_f32_16x16x32_bf16 v[14:17], v[142:145], v[208:211], 0
	v_mfma_f32_16x16x32_bf16 v[14:17], v[146:149], v[212:215], v[14:17]
	v_mfma_f32_16x16x32_bf16 v[58:61], v[156:159], v[164:167], 0
	v_mfma_f32_16x16x32_bf16 v[58:61], v[160:163], v[168:171], v[58:61]
	v_mfma_f32_16x16x32_bf16 v[42:45], v[156:159], v[172:175], 0
	v_mfma_f32_16x16x32_bf16 v[42:45], v[160:163], v[176:179], v[42:45]
	v_mfma_f32_16x16x32_bf16 v[26:29], v[156:159], v[180:183], 0
	v_mfma_f32_16x16x32_bf16 v[26:29], v[160:163], v[204:207], v[26:29]
	v_mfma_f32_16x16x32_bf16 v[10:13], v[156:159], v[208:211], 0
	v_mfma_f32_16x16x32_bf16 v[10:13], v[160:163], v[212:215], v[10:13]
	s_barrier
	s_add_u32 s18, s18, s14
	s_addc_u32 s19, s19, 0
	s_add_i32 s68, s69, s25
	s_add_u32 s76, s18, s6
	s_addc_u32 s77, s19, s7
	s_mov_b32 m0, s68
	s_nop 0
	global_load_lds_dwordx4 v132, s[18:19]
	s_add_i32 m0, s68, 0x2000
	s_nop 0
	global_load_lds_dwordx4 v136, s[18:19]
	s_waitcnt vmcnt(6)
	s_barrier
	v_mfma_f32_16x16x32_bf16 v[54:57], v[216:219], v[164:167], 0
	v_mfma_f32_16x16x32_bf16 v[54:57], v[220:223], v[168:171], v[54:57]
	v_mfma_f32_16x16x32_bf16 v[38:41], v[216:219], v[172:175], 0
	v_mfma_f32_16x16x32_bf16 v[38:41], v[220:223], v[176:179], v[38:41]
	v_mfma_f32_16x16x32_bf16 v[22:25], v[216:219], v[180:183], 0
	v_mfma_f32_16x16x32_bf16 v[22:25], v[220:223], v[204:207], v[22:25]
	v_mfma_f32_16x16x32_bf16 v[6:9], v[216:219], v[208:211], 0
	v_mfma_f32_16x16x32_bf16 v[6:9], v[220:223], v[212:215], v[6:9]
	v_mfma_f32_16x16x32_bf16 v[50:53], v[224:227], v[164:167], 0
	v_mfma_f32_16x16x32_bf16 v[50:53], v[228:231], v[168:171], v[50:53]
	v_mfma_f32_16x16x32_bf16 v[34:37], v[224:227], v[172:175], 0
	v_mfma_f32_16x16x32_bf16 v[34:37], v[228:231], v[176:179], v[34:37]
	v_mfma_f32_16x16x32_bf16 v[18:21], v[224:227], v[180:183], 0
	v_mfma_f32_16x16x32_bf16 v[18:21], v[228:231], v[204:207], v[18:21]
	v_mfma_f32_16x16x32_bf16 v[2:5], v[224:227], v[208:211], 0
	v_mfma_f32_16x16x32_bf16 v[2:5], v[228:231], v[212:215], v[2:5]
	s_barrier
	s_add_i32 s18, 0, 0x18000
	ds_read_b128 v[142:145], v248 offset:32768
	ds_read_b128 v[146:149], v248 offset:33792
	ds_read_b128 v[156:159], v248 offset:34816
	ds_read_b128 v[160:163], v248 offset:35840
	s_add_u32 s4, s4, s14
	s_addc_u32 s5, s5, 0
	s_mov_b32 m0, s31
	ds_read_b128 v[164:167], v154 offset:32768
	ds_read_b128 v[168:171], v154 offset:33792
	ds_read_b128 v[172:175], v154 offset:34816
	ds_read_b128 v[176:179], v154 offset:35840
	ds_read_b128 v[180:183], v154 offset:36864
	ds_read_b128 v[204:207], v154 offset:37888
	ds_read_b128 v[208:211], v154 offset:38912
	ds_read_b128 v[212:215], v154 offset:39936
	global_load_lds_dwordx4 v130, s[4:5]
	s_mov_b32 m0, s34
	s_nop 0
	global_load_lds_dwordx4 v134, s[4:5]
	s_waitcnt lgkmcnt(8)
	s_barrier
	s_waitcnt lgkmcnt(0)
	v_mfma_f32_16x16x32_bf16 v[126:129], v[142:145], v[164:167], v[126:129]
	v_mfma_f32_16x16x32_bf16 v[126:129], v[146:149], v[168:171], v[126:129]
	v_mfma_f32_16x16x32_bf16 v[110:113], v[142:145], v[172:175], v[110:113]
	v_mfma_f32_16x16x32_bf16 v[110:113], v[146:149], v[176:179], v[110:113]
	v_mfma_f32_16x16x32_bf16 v[94:97], v[142:145], v[180:183], v[94:97]
	v_mfma_f32_16x16x32_bf16 v[94:97], v[146:149], v[204:207], v[94:97]
	v_mfma_f32_16x16x32_bf16 v[78:81], v[142:145], v[208:211], v[78:81]
	v_mfma_f32_16x16x32_bf16 v[78:81], v[146:149], v[212:215], v[78:81]
	v_mfma_f32_16x16x32_bf16 v[122:125], v[156:159], v[164:167], v[122:125]
	v_mfma_f32_16x16x32_bf16 v[122:125], v[160:163], v[168:171], v[122:125]
	v_mfma_f32_16x16x32_bf16 v[106:109], v[156:159], v[172:175], v[106:109]
	v_mfma_f32_16x16x32_bf16 v[106:109], v[160:163], v[176:179], v[106:109]
	v_mfma_f32_16x16x32_bf16 v[90:93], v[156:159], v[180:183], v[90:93]
	v_mfma_f32_16x16x32_bf16 v[90:93], v[160:163], v[204:207], v[90:93]
	v_mfma_f32_16x16x32_bf16 v[74:77], v[156:159], v[208:211], v[74:77]
	v_mfma_f32_16x16x32_bf16 v[74:77], v[160:163], v[212:215], v[74:77]
	s_barrier
	s_add_i32 s4, 0, 0x1c000
	s_add_i32 s5, s18, s25
	s_mov_b32 m0, s5
	ds_read_b128 v[216:219], v248 offset:49152
	ds_read_b128 v[220:223], v248 offset:50176
	ds_read_b128 v[224:227], v248 offset:51200
	ds_read_b128 v[228:231], v248 offset:52224
	global_load_lds_dwordx4 v132, s[70:71]
	s_add_i32 m0, s5, 0x2000
	s_nop 0
	global_load_lds_dwordx4 v136, s[70:71]
	s_barrier
	s_waitcnt lgkmcnt(0)
	v_mfma_f32_16x16x32_bf16 v[118:121], v[216:219], v[164:167], v[118:121]
	v_mfma_f32_16x16x32_bf16 v[118:121], v[220:223], v[168:171], v[118:121]
	v_mfma_f32_16x16x32_bf16 v[102:105], v[216:219], v[172:175], v[102:105]
	v_mfma_f32_16x16x32_bf16 v[102:105], v[220:223], v[176:179], v[102:105]
	v_mfma_f32_16x16x32_bf16 v[86:89], v[216:219], v[180:183], v[86:89]
	v_mfma_f32_16x16x32_bf16 v[86:89], v[220:223], v[204:207], v[86:89]
	v_mfma_f32_16x16x32_bf16 v[70:73], v[216:219], v[208:211], v[70:73]
	v_mfma_f32_16x16x32_bf16 v[70:73], v[220:223], v[212:215], v[70:73]
	v_mfma_f32_16x16x32_bf16 v[114:117], v[224:227], v[164:167], v[114:117]
	v_mfma_f32_16x16x32_bf16 v[114:117], v[228:231], v[168:171], v[114:117]
	v_mfma_f32_16x16x32_bf16 v[98:101], v[224:227], v[172:175], v[98:101]
	v_mfma_f32_16x16x32_bf16 v[98:101], v[228:231], v[176:179], v[98:101]
	v_mfma_f32_16x16x32_bf16 v[82:85], v[224:227], v[180:183], v[82:85]
	v_mfma_f32_16x16x32_bf16 v[82:85], v[228:231], v[204:207], v[82:85]
	v_mfma_f32_16x16x32_bf16 v[66:69], v[224:227], v[208:211], v[66:69]
	v_mfma_f32_16x16x32_bf16 v[66:69], v[228:231], v[212:215], v[66:69]
	s_barrier
	s_mov_b32 m0, s41
	ds_read_b128 v[164:167], v154 offset:49152
	ds_read_b128 v[168:171], v154 offset:50176
	ds_read_b128 v[172:175], v154 offset:51200
	ds_read_b128 v[176:179], v154 offset:52224
	ds_read_b128 v[180:183], v154 offset:53248
	ds_read_b128 v[204:207], v154 offset:54272
	ds_read_b128 v[208:211], v154 offset:55296
	ds_read_b128 v[212:215], v154 offset:56320
	global_load_lds_dwordx4 v130, s[72:73]
	s_mov_b32 m0, s42
	s_nop 0
	global_load_lds_dwordx4 v134, s[72:73]
	s_barrier
	s_waitcnt lgkmcnt(0)
	v_mfma_f32_16x16x32_bf16 v[62:65], v[142:145], v[164:167], v[62:65]
	v_mfma_f32_16x16x32_bf16 v[62:65], v[146:149], v[168:171], v[62:65]
	v_mfma_f32_16x16x32_bf16 v[46:49], v[142:145], v[172:175], v[46:49]
	v_mfma_f32_16x16x32_bf16 v[46:49], v[146:149], v[176:179], v[46:49]
	v_mfma_f32_16x16x32_bf16 v[30:33], v[142:145], v[180:183], v[30:33]
	v_mfma_f32_16x16x32_bf16 v[30:33], v[146:149], v[204:207], v[30:33]
	v_mfma_f32_16x16x32_bf16 v[14:17], v[142:145], v[208:211], v[14:17]
	v_mfma_f32_16x16x32_bf16 v[14:17], v[146:149], v[212:215], v[14:17]
	v_mfma_f32_16x16x32_bf16 v[58:61], v[156:159], v[164:167], v[58:61]
	v_mfma_f32_16x16x32_bf16 v[58:61], v[160:163], v[168:171], v[58:61]
	v_mfma_f32_16x16x32_bf16 v[42:45], v[156:159], v[172:175], v[42:45]
	v_mfma_f32_16x16x32_bf16 v[42:45], v[160:163], v[176:179], v[42:45]
	v_mfma_f32_16x16x32_bf16 v[26:29], v[156:159], v[180:183], v[26:29]
	v_mfma_f32_16x16x32_bf16 v[26:29], v[160:163], v[204:207], v[26:29]
	v_mfma_f32_16x16x32_bf16 v[10:13], v[156:159], v[208:211], v[10:13]
	v_mfma_f32_16x16x32_bf16 v[10:13], v[160:163], v[212:215], v[10:13]
	s_barrier
	s_add_i32 s4, s4, s25
	s_mov_b32 m0, s4
	s_nop 0
	global_load_lds_dwordx4 v132, s[76:77]
	s_add_i32 m0, s4, 0x2000
	s_nop 0
	global_load_lds_dwordx4 v136, s[76:77]
	s_add_u32 s0, s0, 0x100
	s_addc_u32 s1, s1, 0
	s_add_u32 s49, s49, 0x100
	s_addc_u32 s65, s65, 0
	s_cmp_ge_u32 s66, s35
	s_mov_b32 s4, s66
	s_waitcnt vmcnt(6)
	s_barrier
	v_mfma_f32_16x16x32_bf16 v[54:57], v[216:219], v[164:167], v[54:57]
	v_mfma_f32_16x16x32_bf16 v[54:57], v[220:223], v[168:171], v[54:57]
	v_mfma_f32_16x16x32_bf16 v[38:41], v[216:219], v[172:175], v[38:41]
	v_mfma_f32_16x16x32_bf16 v[38:41], v[220:223], v[176:179], v[38:41]
	v_mfma_f32_16x16x32_bf16 v[22:25], v[216:219], v[180:183], v[22:25]
	v_mfma_f32_16x16x32_bf16 v[22:25], v[220:223], v[204:207], v[22:25]
	v_mfma_f32_16x16x32_bf16 v[6:9], v[216:219], v[208:211], v[6:9]
	v_mfma_f32_16x16x32_bf16 v[6:9], v[220:223], v[212:215], v[6:9]
	v_mfma_f32_16x16x32_bf16 v[50:53], v[224:227], v[164:167], v[50:53]
	v_mfma_f32_16x16x32_bf16 v[50:53], v[228:231], v[168:171], v[50:53]
	v_mfma_f32_16x16x32_bf16 v[34:37], v[224:227], v[172:175], v[34:37]
	v_mfma_f32_16x16x32_bf16 v[34:37], v[228:231], v[176:179], v[34:37]
	v_mfma_f32_16x16x32_bf16 v[18:21], v[224:227], v[180:183], v[18:21]
	v_mfma_f32_16x16x32_bf16 v[18:21], v[228:231], v[204:207], v[18:21]
	v_mfma_f32_16x16x32_bf16 v[2:5], v[224:227], v[208:211], v[2:5]
	v_mfma_f32_16x16x32_bf16 v[2:5], v[228:231], v[212:215], v[2:5]
	s_barrier
	s_cbranch_scc1 .Lkexit_664
.LBB0_664:
	s_add_i32 s66, s4, 2
	s_add_u32 s18, s0, 0x80
	s_addc_u32 s5, s1, 0
	s_add_i32 s68, 0, 0x10000
	ds_read_b128 v[142:145], v248
	ds_read_b128 v[146:149], v248 offset:1024
	ds_read_b128 v[156:159], v248 offset:2048
	ds_read_b128 v[160:163], v248 offset:3072
	s_cmp_eq_u32 s43, s4
	s_cselect_b32 s4, s10, s18
	s_cselect_b32 s5, s11, s5
	s_cselect_b32 s19, s13, s65
	s_cselect_b32 s18, s12, s49
	s_add_i32 m0, s28, 0xc000
	ds_read_b128 v[164:167], v154
	ds_read_b128 v[168:171], v154 offset:1024
	ds_read_b128 v[172:175], v154 offset:2048
	ds_read_b128 v[176:179], v154 offset:3072
	ds_read_b128 v[180:183], v154 offset:4096
	ds_read_b128 v[204:207], v154 offset:5120
	ds_read_b128 v[208:211], v154 offset:6144
	ds_read_b128 v[212:215], v154 offset:7168
	global_load_lds_dwordx4 v138, s[0:1]
	s_add_i32 m0, s28, 0xe000
	s_nop 0
	global_load_lds_dwordx4 v140, s[0:1]
	s_waitcnt lgkmcnt(8)
	s_barrier
	s_waitcnt lgkmcnt(0)
	v_mfma_f32_16x16x32_bf16 v[126:129], v[142:145], v[164:167], v[126:129]
	v_mfma_f32_16x16x32_bf16 v[126:129], v[146:149], v[168:171], v[126:129]
	v_mfma_f32_16x16x32_bf16 v[110:113], v[142:145], v[172:175], v[110:113]
	v_mfma_f32_16x16x32_bf16 v[110:113], v[146:149], v[176:179], v[110:113]
	v_mfma_f32_16x16x32_bf16 v[94:97], v[142:145], v[180:183], v[94:97]
	v_mfma_f32_16x16x32_bf16 v[94:97], v[146:149], v[204:207], v[94:97]
	v_mfma_f32_16x16x32_bf16 v[78:81], v[142:145], v[208:211], v[78:81]
	v_mfma_f32_16x16x32_bf16 v[78:81], v[146:149], v[212:215], v[78:81]
	v_mfma_f32_16x16x32_bf16 v[122:125], v[156:159], v[164:167], v[122:125]
	v_mfma_f32_16x16x32_bf16 v[122:125], v[160:163], v[168:171], v[122:125]
	v_mfma_f32_16x16x32_bf16 v[106:109], v[156:159], v[172:175], v[106:109]
	v_mfma_f32_16x16x32_bf16 v[106:109], v[160:163], v[176:179], v[106:109]
	v_mfma_f32_16x16x32_bf16 v[90:93], v[156:159], v[180:183], v[90:93]
	v_mfma_f32_16x16x32_bf16 v[90:93], v[160:163], v[204:207], v[90:93]
	v_mfma_f32_16x16x32_bf16 v[74:77], v[156:159], v[208:211], v[74:77]
	v_mfma_f32_16x16x32_bf16 v[74:77], v[160:163], v[212:215], v[74:77]
	s_barrier
	s_add_i32 s69, 0, 0x14000
	s_add_i32 s68, s68, s25
	ds_read_b128 v[216:219], v248 offset:16384
	ds_read_b128 v[220:223], v248 offset:17408
	ds_read_b128 v[224:227], v248 offset:18432
	ds_read_b128 v[228:231], v248 offset:19456
	s_add_u32 s70, s18, s6
	s_addc_u32 s71, s19, s7
	s_mov_b32 m0, s68
	s_nop 0
	global_load_lds_dwordx4 v132, s[18:19]
	s_add_i32 m0, s68, 0x2000
	s_nop 0
	global_load_lds_dwordx4 v136, s[18:19]
	s_barrier
	s_waitcnt lgkmcnt(0)
	v_mfma_f32_16x16x32_bf16 v[118:121], v[216:219], v[164:167], v[118:121]
	v_mfma_f32_16x16x32_bf16 v[118:121], v[220:223], v[168:171], v[118:121]
	v_mfma_f32_16x16x32_bf16 v[102:105], v[216:219], v[172:175], v[102:105]
	v_mfma_f32_16x16x32_bf16 v[102:105], v[220:223], v[176:179], v[102:105]
	v_mfma_f32_16x16x32_bf16 v[86:89], v[216:219], v[180:183], v[86:89]
	v_mfma_f32_16x16x32_bf16 v[86:89], v[220:223], v[204:207], v[86:89]
	v_mfma_f32_16x16x32_bf16 v[70:73], v[216:219], v[208:211], v[70:73]
	v_mfma_f32_16x16x32_bf16 v[70:73], v[220:223], v[212:215], v[70:73]
	v_mfma_f32_16x16x32_bf16 v[114:117], v[224:227], v[164:167], v[114:117]
	v_mfma_f32_16x16x32_bf16 v[114:117], v[228:231], v[168:171], v[114:117]
	v_mfma_f32_16x16x32_bf16 v[98:101], v[224:227], v[172:175], v[98:101]
	v_mfma_f32_16x16x32_bf16 v[98:101], v[228:231], v[176:179], v[98:101]
	v_mfma_f32_16x16x32_bf16 v[82:85], v[224:227], v[180:183], v[82:85]
	v_mfma_f32_16x16x32_bf16 v[82:85], v[228:231], v[204:207], v[82:85]
	v_mfma_f32_16x16x32_bf16 v[66:69], v[224:227], v[208:211], v[66:69]
	v_mfma_f32_16x16x32_bf16 v[66:69], v[228:231], v[212:215], v[66:69]
	s_barrier
	s_mov_b32 m0, s28
	s_add_u32 s72, s4, s6
	s_addc_u32 s73, s5, s7
	ds_read_b128 v[164:167], v154 offset:16384
	ds_read_b128 v[168:171], v154 offset:17408
	ds_read_b128 v[172:175], v154 offset:18432
	ds_read_b128 v[176:179], v154 offset:19456
	ds_read_b128 v[180:183], v154 offset:20480
	ds_read_b128 v[204:207], v154 offset:21504
	ds_read_b128 v[208:211], v154 offset:22528
	ds_read_b128 v[212:215], v154 offset:23552
	global_load_lds_dwordx4 v130, s[4:5]
	s_mov_b32 m0, s29
	s_nop 0
	global_load_lds_dwordx4 v134, s[4:5]
	s_barrier
	s_waitcnt lgkmcnt(0)
	v_mfma_f32_16x16x32_bf16 v[62:65], v[142:145], v[164:167], v[62:65]
	v_mfma_f32_16x16x32_bf16 v[62:65], v[146:149], v[168:171], v[62:65]
	v_mfma_f32_16x16x32_bf16 v[46:49], v[142:145], v[172:175], v[46:49]
	v_mfma_f32_16x16x32_bf16 v[46:49], v[146:149], v[176:179], v[46:49]
	v_mfma_f32_16x16x32_bf16 v[30:33], v[142:145], v[180:183], v[30:33]
	v_mfma_f32_16x16x32_bf16 v[30:33], v[146:149], v[204:207], v[30:33]
	v_mfma_f32_16x16x32_bf16 v[14:17], v[142:145], v[208:211], v[14:17]
	v_mfma_f32_16x16x32_bf16 v[14:17], v[146:149], v[212:215], v[14:17]
	v_mfma_f32_16x16x32_bf16 v[58:61], v[156:159], v[164:167], v[58:61]
	v_mfma_f32_16x16x32_bf16 v[58:61], v[160:163], v[168:171], v[58:61]
	v_mfma_f32_16x16x32_bf16 v[42:45], v[156:159], v[172:175], v[42:45]
	v_mfma_f32_16x16x32_bf16 v[42:45], v[160:163], v[176:179], v[42:45]
	v_mfma_f32_16x16x32_bf16 v[26:29], v[156:159], v[180:183], v[26:29]
	v_mfma_f32_16x16x32_bf16 v[26:29], v[160:163], v[204:207], v[26:29]
	v_mfma_f32_16x16x32_bf16 v[10:13], v[156:159], v[208:211], v[10:13]
	v_mfma_f32_16x16x32_bf16 v[10:13], v[160:163], v[212:215], v[10:13]
	s_barrier
	s_add_u32 s18, s18, s14
	s_addc_u32 s19, s19, 0
	s_add_i32 s68, s69, s25
	s_add_u32 s76, s18, s6
	s_addc_u32 s77, s19, s7
	s_mov_b32 m0, s68
	s_nop 0
	global_load_lds_dwordx4 v132, s[18:19]
	s_add_i32 m0, s68, 0x2000
	s_nop 0
	global_load_lds_dwordx4 v136, s[18:19]
	s_waitcnt vmcnt(6)
	s_barrier
	v_mfma_f32_16x16x32_bf16 v[54:57], v[216:219], v[164:167], v[54:57]
	v_mfma_f32_16x16x32_bf16 v[54:57], v[220:223], v[168:171], v[54:57]
	v_mfma_f32_16x16x32_bf16 v[38:41], v[216:219], v[172:175], v[38:41]
	v_mfma_f32_16x16x32_bf16 v[38:41], v[220:223], v[176:179], v[38:41]
	v_mfma_f32_16x16x32_bf16 v[22:25], v[216:219], v[180:183], v[22:25]
	v_mfma_f32_16x16x32_bf16 v[22:25], v[220:223], v[204:207], v[22:25]
	v_mfma_f32_16x16x32_bf16 v[6:9], v[216:219], v[208:211], v[6:9]
	v_mfma_f32_16x16x32_bf16 v[6:9], v[220:223], v[212:215], v[6:9]
	v_mfma_f32_16x16x32_bf16 v[50:53], v[224:227], v[164:167], v[50:53]
	v_mfma_f32_16x16x32_bf16 v[50:53], v[228:231], v[168:171], v[50:53]
	v_mfma_f32_16x16x32_bf16 v[34:37], v[224:227], v[172:175], v[34:37]
	v_mfma_f32_16x16x32_bf16 v[34:37], v[228:231], v[176:179], v[34:37]
	v_mfma_f32_16x16x32_bf16 v[18:21], v[224:227], v[180:183], v[18:21]
	v_mfma_f32_16x16x32_bf16 v[18:21], v[228:231], v[204:207], v[18:21]
	v_mfma_f32_16x16x32_bf16 v[2:5], v[224:227], v[208:211], v[2:5]
	v_mfma_f32_16x16x32_bf16 v[2:5], v[228:231], v[212:215], v[2:5]
	s_barrier
	s_add_i32 s18, 0, 0x18000
	ds_read_b128 v[142:145], v248 offset:32768
	ds_read_b128 v[146:149], v248 offset:33792
	ds_read_b128 v[156:159], v248 offset:34816
	ds_read_b128 v[160:163], v248 offset:35840
	s_add_u32 s4, s4, s14
	s_addc_u32 s5, s5, 0
	s_mov_b32 m0, s31
	ds_read_b128 v[164:167], v154 offset:32768
	ds_read_b128 v[168:171], v154 offset:33792
	ds_read_b128 v[172:175], v154 offset:34816
	ds_read_b128 v[176:179], v154 offset:35840
	ds_read_b128 v[180:183], v154 offset:36864
	ds_read_b128 v[204:207], v154 offset:37888
	ds_read_b128 v[208:211], v154 offset:38912
	ds_read_b128 v[212:215], v154 offset:39936
	global_load_lds_dwordx4 v130, s[4:5]
	s_mov_b32 m0, s34
	s_nop 0
	global_load_lds_dwordx4 v134, s[4:5]
	s_waitcnt lgkmcnt(8)
	s_barrier
	s_waitcnt lgkmcnt(0)
	v_mfma_f32_16x16x32_bf16 v[126:129], v[142:145], v[164:167], v[126:129]
	v_mfma_f32_16x16x32_bf16 v[126:129], v[146:149], v[168:171], v[126:129]
	v_mfma_f32_16x16x32_bf16 v[110:113], v[142:145], v[172:175], v[110:113]
	v_mfma_f32_16x16x32_bf16 v[110:113], v[146:149], v[176:179], v[110:113]
	v_mfma_f32_16x16x32_bf16 v[94:97], v[142:145], v[180:183], v[94:97]
	v_mfma_f32_16x16x32_bf16 v[94:97], v[146:149], v[204:207], v[94:97]
	v_mfma_f32_16x16x32_bf16 v[78:81], v[142:145], v[208:211], v[78:81]
	v_mfma_f32_16x16x32_bf16 v[78:81], v[146:149], v[212:215], v[78:81]
	v_mfma_f32_16x16x32_bf16 v[122:125], v[156:159], v[164:167], v[122:125]
	v_mfma_f32_16x16x32_bf16 v[122:125], v[160:163], v[168:171], v[122:125]
	v_mfma_f32_16x16x32_bf16 v[106:109], v[156:159], v[172:175], v[106:109]
	v_mfma_f32_16x16x32_bf16 v[106:109], v[160:163], v[176:179], v[106:109]
	v_mfma_f32_16x16x32_bf16 v[90:93], v[156:159], v[180:183], v[90:93]
	v_mfma_f32_16x16x32_bf16 v[90:93], v[160:163], v[204:207], v[90:93]
	v_mfma_f32_16x16x32_bf16 v[74:77], v[156:159], v[208:211], v[74:77]
	v_mfma_f32_16x16x32_bf16 v[74:77], v[160:163], v[212:215], v[74:77]
	s_barrier
	s_add_i32 s4, 0, 0x1c000
	s_add_i32 s5, s18, s25
	s_mov_b32 m0, s5
	ds_read_b128 v[216:219], v248 offset:49152
	ds_read_b128 v[220:223], v248 offset:50176
	ds_read_b128 v[224:227], v248 offset:51200
	ds_read_b128 v[228:231], v248 offset:52224
	global_load_lds_dwordx4 v132, s[70:71]
	s_add_i32 m0, s5, 0x2000
	s_nop 0
	global_load_lds_dwordx4 v136, s[70:71]
	s_barrier
	s_waitcnt lgkmcnt(0)
	v_mfma_f32_16x16x32_bf16 v[118:121], v[216:219], v[164:167], v[118:121]
	v_mfma_f32_16x16x32_bf16 v[118:121], v[220:223], v[168:171], v[118:121]
	v_mfma_f32_16x16x32_bf16 v[102:105], v[216:219], v[172:175], v[102:105]
	v_mfma_f32_16x16x32_bf16 v[102:105], v[220:223], v[176:179], v[102:105]
	v_mfma_f32_16x16x32_bf16 v[86:89], v[216:219], v[180:183], v[86:89]
	v_mfma_f32_16x16x32_bf16 v[86:89], v[220:223], v[204:207], v[86:89]
	v_mfma_f32_16x16x32_bf16 v[70:73], v[216:219], v[208:211], v[70:73]
	v_mfma_f32_16x16x32_bf16 v[70:73], v[220:223], v[212:215], v[70:73]
	v_mfma_f32_16x16x32_bf16 v[114:117], v[224:227], v[164:167], v[114:117]
	v_mfma_f32_16x16x32_bf16 v[114:117], v[228:231], v[168:171], v[114:117]
	v_mfma_f32_16x16x32_bf16 v[98:101], v[224:227], v[172:175], v[98:101]
	v_mfma_f32_16x16x32_bf16 v[98:101], v[228:231], v[176:179], v[98:101]
	v_mfma_f32_16x16x32_bf16 v[82:85], v[224:227], v[180:183], v[82:85]
	v_mfma_f32_16x16x32_bf16 v[82:85], v[228:231], v[204:207], v[82:85]
	v_mfma_f32_16x16x32_bf16 v[66:69], v[224:227], v[208:211], v[66:69]
	v_mfma_f32_16x16x32_bf16 v[66:69], v[228:231], v[212:215], v[66:69]
	s_barrier
	s_mov_b32 m0, s41
	ds_read_b128 v[164:167], v154 offset:49152
	ds_read_b128 v[168:171], v154 offset:50176
	ds_read_b128 v[172:175], v154 offset:51200
	ds_read_b128 v[176:179], v154 offset:52224
	ds_read_b128 v[180:183], v154 offset:53248
	ds_read_b128 v[204:207], v154 offset:54272
	ds_read_b128 v[208:211], v154 offset:55296
	ds_read_b128 v[212:215], v154 offset:56320
	global_load_lds_dwordx4 v130, s[72:73]
	s_mov_b32 m0, s42
	s_nop 0
	global_load_lds_dwordx4 v134, s[72:73]
	s_barrier
	s_waitcnt lgkmcnt(0)
	v_mfma_f32_16x16x32_bf16 v[62:65], v[142:145], v[164:167], v[62:65]
	v_mfma_f32_16x16x32_bf16 v[62:65], v[146:149], v[168:171], v[62:65]
	v_mfma_f32_16x16x32_bf16 v[46:49], v[142:145], v[172:175], v[46:49]
	v_mfma_f32_16x16x32_bf16 v[46:49], v[146:149], v[176:179], v[46:49]
	v_mfma_f32_16x16x32_bf16 v[30:33], v[142:145], v[180:183], v[30:33]
	v_mfma_f32_16x16x32_bf16 v[30:33], v[146:149], v[204:207], v[30:33]
	v_mfma_f32_16x16x32_bf16 v[14:17], v[142:145], v[208:211], v[14:17]
	v_mfma_f32_16x16x32_bf16 v[14:17], v[146:149], v[212:215], v[14:17]
	v_mfma_f32_16x16x32_bf16 v[58:61], v[156:159], v[164:167], v[58:61]
	v_mfma_f32_16x16x32_bf16 v[58:61], v[160:163], v[168:171], v[58:61]
	v_mfma_f32_16x16x32_bf16 v[42:45], v[156:159], v[172:175], v[42:45]
	v_mfma_f32_16x16x32_bf16 v[42:45], v[160:163], v[176:179], v[42:45]
	v_mfma_f32_16x16x32_bf16 v[26:29], v[156:159], v[180:183], v[26:29]
	v_mfma_f32_16x16x32_bf16 v[26:29], v[160:163], v[204:207], v[26:29]
	v_mfma_f32_16x16x32_bf16 v[10:13], v[156:159], v[208:211], v[10:13]
	v_mfma_f32_16x16x32_bf16 v[10:13], v[160:163], v[212:215], v[10:13]
	s_barrier
	s_add_i32 s4, s4, s25
	s_mov_b32 m0, s4
	s_nop 0
	global_load_lds_dwordx4 v132, s[76:77]
	s_add_i32 m0, s4, 0x2000
	s_nop 0
	global_load_lds_dwordx4 v136, s[76:77]
	s_add_u32 s0, s0, 0x100
	s_addc_u32 s1, s1, 0
	s_add_u32 s49, s49, 0x100
	s_addc_u32 s65, s65, 0
	s_cmp_ge_u32 s66, s35
	s_mov_b32 s4, s66
	s_waitcnt vmcnt(6)
	s_barrier
	v_mfma_f32_16x16x32_bf16 v[54:57], v[216:219], v[164:167], v[54:57]
	v_mfma_f32_16x16x32_bf16 v[54:57], v[220:223], v[168:171], v[54:57]
	v_mfma_f32_16x16x32_bf16 v[38:41], v[216:219], v[172:175], v[38:41]
	v_mfma_f32_16x16x32_bf16 v[38:41], v[220:223], v[176:179], v[38:41]
	v_mfma_f32_16x16x32_bf16 v[22:25], v[216:219], v[180:183], v[22:25]
	v_mfma_f32_16x16x32_bf16 v[22:25], v[220:223], v[204:207], v[22:25]
	v_mfma_f32_16x16x32_bf16 v[6:9], v[216:219], v[208:211], v[6:9]
	v_mfma_f32_16x16x32_bf16 v[6:9], v[220:223], v[212:215], v[6:9]
	v_mfma_f32_16x16x32_bf16 v[50:53], v[224:227], v[164:167], v[50:53]
	v_mfma_f32_16x16x32_bf16 v[50:53], v[228:231], v[168:171], v[50:53]
	v_mfma_f32_16x16x32_bf16 v[34:37], v[224:227], v[172:175], v[34:37]
	v_mfma_f32_16x16x32_bf16 v[34:37], v[228:231], v[176:179], v[34:37]
	v_mfma_f32_16x16x32_bf16 v[18:21], v[224:227], v[180:183], v[18:21]
	v_mfma_f32_16x16x32_bf16 v[18:21], v[228:231], v[204:207], v[18:21]
	v_mfma_f32_16x16x32_bf16 v[2:5], v[224:227], v[208:211], v[2:5]
	v_mfma_f32_16x16x32_bf16 v[2:5], v[228:231], v[212:215], v[2:5]
	s_barrier
	s_cbranch_scc0 .LBB0_664

.LBB0_697:
	s_add_u32 s0, s0, 0x80
	s_addc_u32 s1, s1, 0
	s_add_u32 s48, s4, 0x100
	s_addc_u32 s49, s5, 0
	s_mov_b32 s4, 0
	s_waitcnt lgkmcnt(0)
	s_waitcnt vmcnt(0)
	s_add_i32 s65, s4, 2
	s_add_u32 s18, s0, 0x80
	s_addc_u32 s5, s1, 0
	s_add_i32 s66, 0, 0x10000
	ds_read_b128 v[142:145], v248
	ds_read_b128 v[152:155], v248 offset:1024
	ds_read_b128 v[156:159], v248 offset:2048
	ds_read_b128 v[160:163], v248 offset:3072
	s_cmp_eq_u32 s34, s4
	s_cselect_b32 s4, s10, s18
	s_cselect_b32 s5, s11, s5
	s_cselect_b32 s19, s13, s49
	s_cselect_b32 s18, s12, s48
	s_add_i32 m0, s22, 0xc000
	ds_read_b128 v[164:167], v150
	ds_read_b128 v[168:171], v150 offset:1024
	ds_read_b128 v[172:175], v150 offset:2048
	ds_read_b128 v[176:179], v150 offset:3072
	ds_read_b128 v[180:183], v150 offset:4096
	ds_read_b128 v[204:207], v150 offset:5120
	ds_read_b128 v[208:211], v150 offset:6144
	ds_read_b128 v[212:215], v150 offset:7168
	global_load_lds_dwordx4 v138, s[0:1]
	s_add_i32 m0, s22, 0xe000
	s_nop 0
	global_load_lds_dwordx4 v140, s[0:1]
	s_waitcnt lgkmcnt(8)
	s_barrier
	s_waitcnt lgkmcnt(0)
	v_mfma_f32_16x16x32_bf16 v[126:129], v[142:145], v[164:167], 0
	v_mfma_f32_16x16x32_bf16 v[126:129], v[152:155], v[168:171], v[126:129]
	v_mfma_f32_16x16x32_bf16 v[110:113], v[142:145], v[172:175], 0
	v_mfma_f32_16x16x32_bf16 v[110:113], v[152:155], v[176:179], v[110:113]
	v_mfma_f32_16x16x32_bf16 v[94:97], v[142:145], v[180:183], 0
	v_mfma_f32_16x16x32_bf16 v[94:97], v[152:155], v[204:207], v[94:97]
	v_mfma_f32_16x16x32_bf16 v[78:81], v[142:145], v[208:211], 0
	v_mfma_f32_16x16x32_bf16 v[78:81], v[152:155], v[212:215], v[78:81]
	v_mfma_f32_16x16x32_bf16 v[122:125], v[156:159], v[164:167], 0
	v_mfma_f32_16x16x32_bf16 v[122:125], v[160:163], v[168:171], v[122:125]
	v_mfma_f32_16x16x32_bf16 v[106:109], v[156:159], v[172:175], 0
	v_mfma_f32_16x16x32_bf16 v[106:109], v[160:163], v[176:179], v[106:109]
	v_mfma_f32_16x16x32_bf16 v[90:93], v[156:159], v[180:183], 0
	v_mfma_f32_16x16x32_bf16 v[90:93], v[160:163], v[204:207], v[90:93]
	v_mfma_f32_16x16x32_bf16 v[74:77], v[156:159], v[208:211], 0
	v_mfma_f32_16x16x32_bf16 v[74:77], v[160:163], v[212:215], v[74:77]
	s_barrier
	s_add_i32 s67, 0, 0x14000
	s_add_i32 s66, s66, s21
	ds_read_b128 v[216:219], v248 offset:16384
	ds_read_b128 v[220:223], v248 offset:17408
	ds_read_b128 v[224:227], v248 offset:18432
	ds_read_b128 v[228:231], v248 offset:19456
	s_add_u32 s70, s18, s6
	s_addc_u32 s71, s19, s7
	s_mov_b32 m0, s66
	s_nop 0
	global_load_lds_dwordx4 v132, s[18:19]
	s_add_i32 m0, s66, 0x2000
	s_nop 0
	global_load_lds_dwordx4 v136, s[18:19]
	s_barrier
	s_waitcnt lgkmcnt(0)
	v_mfma_f32_16x16x32_bf16 v[118:121], v[216:219], v[164:167], 0
	v_mfma_f32_16x16x32_bf16 v[118:121], v[220:223], v[168:171], v[118:121]
	v_mfma_f32_16x16x32_bf16 v[102:105], v[216:219], v[172:175], 0
	v_mfma_f32_16x16x32_bf16 v[102:105], v[220:223], v[176:179], v[102:105]
	v_mfma_f32_16x16x32_bf16 v[86:89], v[216:219], v[180:183], 0
	v_mfma_f32_16x16x32_bf16 v[86:89], v[220:223], v[204:207], v[86:89]
	v_mfma_f32_16x16x32_bf16 v[70:73], v[216:219], v[208:211], 0
	v_mfma_f32_16x16x32_bf16 v[70:73], v[220:223], v[212:215], v[70:73]
	v_mfma_f32_16x16x32_bf16 v[114:117], v[224:227], v[164:167], 0
	v_mfma_f32_16x16x32_bf16 v[114:117], v[228:231], v[168:171], v[114:117]
	v_mfma_f32_16x16x32_bf16 v[98:101], v[224:227], v[172:175], 0
	v_mfma_f32_16x16x32_bf16 v[98:101], v[228:231], v[176:179], v[98:101]
	v_mfma_f32_16x16x32_bf16 v[82:85], v[224:227], v[180:183], 0
	v_mfma_f32_16x16x32_bf16 v[82:85], v[228:231], v[204:207], v[82:85]
	v_mfma_f32_16x16x32_bf16 v[66:69], v[224:227], v[208:211], 0
	v_mfma_f32_16x16x32_bf16 v[66:69], v[228:231], v[212:215], v[66:69]
	s_barrier
	s_mov_b32 m0, s22
	s_add_u32 s72, s4, s6
	s_addc_u32 s73, s5, s7
	ds_read_b128 v[164:167], v150 offset:16384
	ds_read_b128 v[168:171], v150 offset:17408
	ds_read_b128 v[172:175], v150 offset:18432
	ds_read_b128 v[176:179], v150 offset:19456
	ds_read_b128 v[180:183], v150 offset:20480
	ds_read_b128 v[204:207], v150 offset:21504
	ds_read_b128 v[208:211], v150 offset:22528
	ds_read_b128 v[212:215], v150 offset:23552
	global_load_lds_dwordx4 v130, s[4:5]
	s_mov_b32 m0, s23
	s_nop 0
	global_load_lds_dwordx4 v134, s[4:5]
	s_barrier
	s_waitcnt lgkmcnt(0)
	v_mfma_f32_16x16x32_bf16 v[62:65], v[142:145], v[164:167], 0
	v_mfma_f32_16x16x32_bf16 v[62:65], v[152:155], v[168:171], v[62:65]
	v_mfma_f32_16x16x32_bf16 v[46:49], v[142:145], v[172:175], 0
	v_mfma_f32_16x16x32_bf16 v[46:49], v[152:155], v[176:179], v[46:49]
	v_mfma_f32_16x16x32_bf16 v[30:33], v[142:145], v[180:183], 0
	v_mfma_f32_16x16x32_bf16 v[30:33], v[152:155], v[204:207], v[30:33]
	v_mfma_f32_16x16x32_bf16 v[14:17], v[142:145], v[208:211], 0
	v_mfma_f32_16x16x32_bf16 v[14:17], v[152:155], v[212:215], v[14:17]
	v_mfma_f32_16x16x32_bf16 v[58:61], v[156:159], v[164:167], 0
	v_mfma_f32_16x16x32_bf16 v[58:61], v[160:163], v[168:171], v[58:61]
	v_mfma_f32_16x16x32_bf16 v[42:45], v[156:159], v[172:175], 0
	v_mfma_f32_16x16x32_bf16 v[42:45], v[160:163], v[176:179], v[42:45]
	v_mfma_f32_16x16x32_bf16 v[26:29], v[156:159], v[180:183], 0
	v_mfma_f32_16x16x32_bf16 v[26:29], v[160:163], v[204:207], v[26:29]
	v_mfma_f32_16x16x32_bf16 v[10:13], v[156:159], v[208:211], 0
	v_mfma_f32_16x16x32_bf16 v[10:13], v[160:163], v[212:215], v[10:13]
	s_barrier
	s_add_u32 s18, s18, s2
	s_addc_u32 s19, s19, 0
	s_add_i32 s66, s67, s21
	s_add_u32 s76, s18, s6
	s_addc_u32 s77, s19, s7
	s_mov_b32 m0, s66
	s_nop 0
	global_load_lds_dwordx4 v132, s[18:19]
	s_add_i32 m0, s66, 0x2000
	s_nop 0
	global_load_lds_dwordx4 v136, s[18:19]
	s_waitcnt vmcnt(6)
	s_barrier
	v_mfma_f32_16x16x32_bf16 v[54:57], v[216:219], v[164:167], 0
	v_mfma_f32_16x16x32_bf16 v[54:57], v[220:223], v[168:171], v[54:57]
	v_mfma_f32_16x16x32_bf16 v[38:41], v[216:219], v[172:175], 0
	v_mfma_f32_16x16x32_bf16 v[38:41], v[220:223], v[176:179], v[38:41]
	v_mfma_f32_16x16x32_bf16 v[22:25], v[216:219], v[180:183], 0
	v_mfma_f32_16x16x32_bf16 v[22:25], v[220:223], v[204:207], v[22:25]
	v_mfma_f32_16x16x32_bf16 v[6:9], v[216:219], v[208:211], 0
	v_mfma_f32_16x16x32_bf16 v[6:9], v[220:223], v[212:215], v[6:9]
	v_mfma_f32_16x16x32_bf16 v[50:53], v[224:227], v[164:167], 0
	v_mfma_f32_16x16x32_bf16 v[50:53], v[228:231], v[168:171], v[50:53]
	v_mfma_f32_16x16x32_bf16 v[34:37], v[224:227], v[172:175], 0
	v_mfma_f32_16x16x32_bf16 v[34:37], v[228:231], v[176:179], v[34:37]
	v_mfma_f32_16x16x32_bf16 v[18:21], v[224:227], v[180:183], 0
	v_mfma_f32_16x16x32_bf16 v[18:21], v[228:231], v[204:207], v[18:21]
	v_mfma_f32_16x16x32_bf16 v[2:5], v[224:227], v[208:211], 0
	v_mfma_f32_16x16x32_bf16 v[2:5], v[228:231], v[212:215], v[2:5]
	s_barrier
	s_add_i32 s18, 0, 0x18000
	ds_read_b128 v[142:145], v248 offset:32768
	ds_read_b128 v[152:155], v248 offset:33792
	ds_read_b128 v[156:159], v248 offset:34816
	ds_read_b128 v[160:163], v248 offset:35840
	s_add_u32 s4, s4, s2
	s_addc_u32 s5, s5, 0
	s_mov_b32 m0, s24
	ds_read_b128 v[164:167], v150 offset:32768
	ds_read_b128 v[168:171], v150 offset:33792
	ds_read_b128 v[172:175], v150 offset:34816
	ds_read_b128 v[176:179], v150 offset:35840
	ds_read_b128 v[180:183], v150 offset:36864
	ds_read_b128 v[204:207], v150 offset:37888
	ds_read_b128 v[208:211], v150 offset:38912
	ds_read_b128 v[212:215], v150 offset:39936
	global_load_lds_dwordx4 v130, s[4:5]
	s_mov_b32 m0, s25
	s_nop 0
	global_load_lds_dwordx4 v134, s[4:5]
	s_waitcnt lgkmcnt(8)
	s_barrier
	s_waitcnt lgkmcnt(0)
	v_mfma_f32_16x16x32_bf16 v[126:129], v[142:145], v[164:167], v[126:129]
	v_mfma_f32_16x16x32_bf16 v[126:129], v[152:155], v[168:171], v[126:129]
	v_mfma_f32_16x16x32_bf16 v[110:113], v[142:145], v[172:175], v[110:113]
	v_mfma_f32_16x16x32_bf16 v[110:113], v[152:155], v[176:179], v[110:113]
	v_mfma_f32_16x16x32_bf16 v[94:97], v[142:145], v[180:183], v[94:97]
	v_mfma_f32_16x16x32_bf16 v[94:97], v[152:155], v[204:207], v[94:97]
	v_mfma_f32_16x16x32_bf16 v[78:81], v[142:145], v[208:211], v[78:81]
	v_mfma_f32_16x16x32_bf16 v[78:81], v[152:155], v[212:215], v[78:81]
	v_mfma_f32_16x16x32_bf16 v[122:125], v[156:159], v[164:167], v[122:125]
	v_mfma_f32_16x16x32_bf16 v[122:125], v[160:163], v[168:171], v[122:125]
	v_mfma_f32_16x16x32_bf16 v[106:109], v[156:159], v[172:175], v[106:109]
	v_mfma_f32_16x16x32_bf16 v[106:109], v[160:163], v[176:179], v[106:109]
	v_mfma_f32_16x16x32_bf16 v[90:93], v[156:159], v[180:183], v[90:93]
	v_mfma_f32_16x16x32_bf16 v[90:93], v[160:163], v[204:207], v[90:93]
	v_mfma_f32_16x16x32_bf16 v[74:77], v[156:159], v[208:211], v[74:77]
	v_mfma_f32_16x16x32_bf16 v[74:77], v[160:163], v[212:215], v[74:77]
	s_barrier
	s_add_i32 s4, 0, 0x1c000
	s_add_i32 s5, s18, s21
	s_mov_b32 m0, s5
	ds_read_b128 v[216:219], v248 offset:49152
	ds_read_b128 v[220:223], v248 offset:50176
	ds_read_b128 v[224:227], v248 offset:51200
	ds_read_b128 v[228:231], v248 offset:52224
	global_load_lds_dwordx4 v132, s[70:71]
	s_add_i32 m0, s5, 0x2000
	s_nop 0
	global_load_lds_dwordx4 v136, s[70:71]
	s_barrier
	s_waitcnt lgkmcnt(0)
	v_mfma_f32_16x16x32_bf16 v[118:121], v[216:219], v[164:167], v[118:121]
	v_mfma_f32_16x16x32_bf16 v[118:121], v[220:223], v[168:171], v[118:121]
	v_mfma_f32_16x16x32_bf16 v[102:105], v[216:219], v[172:175], v[102:105]
	v_mfma_f32_16x16x32_bf16 v[102:105], v[220:223], v[176:179], v[102:105]
	v_mfma_f32_16x16x32_bf16 v[86:89], v[216:219], v[180:183], v[86:89]
	v_mfma_f32_16x16x32_bf16 v[86:89], v[220:223], v[204:207], v[86:89]
	v_mfma_f32_16x16x32_bf16 v[70:73], v[216:219], v[208:211], v[70:73]
	v_mfma_f32_16x16x32_bf16 v[70:73], v[220:223], v[212:215], v[70:73]
	v_mfma_f32_16x16x32_bf16 v[114:117], v[224:227], v[164:167], v[114:117]
	v_mfma_f32_16x16x32_bf16 v[114:117], v[228:231], v[168:171], v[114:117]
	v_mfma_f32_16x16x32_bf16 v[98:101], v[224:227], v[172:175], v[98:101]
	v_mfma_f32_16x16x32_bf16 v[98:101], v[228:231], v[176:179], v[98:101]
	v_mfma_f32_16x16x32_bf16 v[82:85], v[224:227], v[180:183], v[82:85]
	v_mfma_f32_16x16x32_bf16 v[82:85], v[228:231], v[204:207], v[82:85]
	v_mfma_f32_16x16x32_bf16 v[66:69], v[224:227], v[208:211], v[66:69]
	v_mfma_f32_16x16x32_bf16 v[66:69], v[228:231], v[212:215], v[66:69]
	s_barrier
	s_mov_b32 m0, s30
	ds_read_b128 v[164:167], v150 offset:49152
	ds_read_b128 v[168:171], v150 offset:50176
	ds_read_b128 v[172:175], v150 offset:51200
	ds_read_b128 v[176:179], v150 offset:52224
	ds_read_b128 v[180:183], v150 offset:53248
	ds_read_b128 v[204:207], v150 offset:54272
	ds_read_b128 v[208:211], v150 offset:55296
	ds_read_b128 v[212:215], v150 offset:56320
	global_load_lds_dwordx4 v130, s[72:73]
	s_mov_b32 m0, s31
	s_nop 0
	global_load_lds_dwordx4 v134, s[72:73]
	s_barrier
	s_waitcnt lgkmcnt(0)
	v_mfma_f32_16x16x32_bf16 v[62:65], v[142:145], v[164:167], v[62:65]
	v_mfma_f32_16x16x32_bf16 v[62:65], v[152:155], v[168:171], v[62:65]
	v_mfma_f32_16x16x32_bf16 v[46:49], v[142:145], v[172:175], v[46:49]
	v_mfma_f32_16x16x32_bf16 v[46:49], v[152:155], v[176:179], v[46:49]
	v_mfma_f32_16x16x32_bf16 v[30:33], v[142:145], v[180:183], v[30:33]
	v_mfma_f32_16x16x32_bf16 v[30:33], v[152:155], v[204:207], v[30:33]
	v_mfma_f32_16x16x32_bf16 v[14:17], v[142:145], v[208:211], v[14:17]
	v_mfma_f32_16x16x32_bf16 v[14:17], v[152:155], v[212:215], v[14:17]
	v_mfma_f32_16x16x32_bf16 v[58:61], v[156:159], v[164:167], v[58:61]
	v_mfma_f32_16x16x32_bf16 v[58:61], v[160:163], v[168:171], v[58:61]
	v_mfma_f32_16x16x32_bf16 v[42:45], v[156:159], v[172:175], v[42:45]
	v_mfma_f32_16x16x32_bf16 v[42:45], v[160:163], v[176:179], v[42:45]
	v_mfma_f32_16x16x32_bf16 v[26:29], v[156:159], v[180:183], v[26:29]
	v_mfma_f32_16x16x32_bf16 v[26:29], v[160:163], v[204:207], v[26:29]
	v_mfma_f32_16x16x32_bf16 v[10:13], v[156:159], v[208:211], v[10:13]
	v_mfma_f32_16x16x32_bf16 v[10:13], v[160:163], v[212:215], v[10:13]
	s_barrier
	s_add_i32 s4, s4, s21
	s_mov_b32 m0, s4
	s_nop 0
	global_load_lds_dwordx4 v132, s[76:77]
	s_add_i32 m0, s4, 0x2000
	s_nop 0
	global_load_lds_dwordx4 v136, s[76:77]
	s_add_u32 s0, s0, 0x100
	s_addc_u32 s1, s1, 0
	s_add_u32 s48, s48, 0x100
	s_addc_u32 s49, s49, 0
	s_cmp_ge_u32 s65, s27
	s_mov_b32 s4, s65
	s_waitcnt vmcnt(6)
	s_barrier
	v_mfma_f32_16x16x32_bf16 v[54:57], v[216:219], v[164:167], v[54:57]
	v_mfma_f32_16x16x32_bf16 v[54:57], v[220:223], v[168:171], v[54:57]
	v_mfma_f32_16x16x32_bf16 v[38:41], v[216:219], v[172:175], v[38:41]
	v_mfma_f32_16x16x32_bf16 v[38:41], v[220:223], v[176:179], v[38:41]
	v_mfma_f32_16x16x32_bf16 v[22:25], v[216:219], v[180:183], v[22:25]
	v_mfma_f32_16x16x32_bf16 v[22:25], v[220:223], v[204:207], v[22:25]
	v_mfma_f32_16x16x32_bf16 v[6:9], v[216:219], v[208:211], v[6:9]
	v_mfma_f32_16x16x32_bf16 v[6:9], v[220:223], v[212:215], v[6:9]
	v_mfma_f32_16x16x32_bf16 v[50:53], v[224:227], v[164:167], v[50:53]
	v_mfma_f32_16x16x32_bf16 v[50:53], v[228:231], v[168:171], v[50:53]
	v_mfma_f32_16x16x32_bf16 v[34:37], v[224:227], v[172:175], v[34:37]
	v_mfma_f32_16x16x32_bf16 v[34:37], v[228:231], v[176:179], v[34:37]
	v_mfma_f32_16x16x32_bf16 v[18:21], v[224:227], v[180:183], v[18:21]
	v_mfma_f32_16x16x32_bf16 v[18:21], v[228:231], v[204:207], v[18:21]
	v_mfma_f32_16x16x32_bf16 v[2:5], v[224:227], v[208:211], v[2:5]
	v_mfma_f32_16x16x32_bf16 v[2:5], v[228:231], v[212:215], v[2:5]
	s_barrier
	s_cbranch_scc1 .Lkexit_698
.LBB0_698:
	s_add_i32 s65, s4, 2
	s_add_u32 s18, s0, 0x80
	s_addc_u32 s5, s1, 0
	s_add_i32 s66, 0, 0x10000
	ds_read_b128 v[142:145], v248
	ds_read_b128 v[152:155], v248 offset:1024
	ds_read_b128 v[156:159], v248 offset:2048
	ds_read_b128 v[160:163], v248 offset:3072
	s_cmp_eq_u32 s34, s4
	s_cselect_b32 s4, s10, s18
	s_cselect_b32 s5, s11, s5
	s_cselect_b32 s19, s13, s49
	s_cselect_b32 s18, s12, s48
	s_add_i32 m0, s22, 0xc000
	ds_read_b128 v[164:167], v150
	ds_read_b128 v[168:171], v150 offset:1024
	ds_read_b128 v[172:175], v150 offset:2048
	ds_read_b128 v[176:179], v150 offset:3072
	ds_read_b128 v[180:183], v150 offset:4096
	ds_read_b128 v[204:207], v150 offset:5120
	ds_read_b128 v[208:211], v150 offset:6144
	ds_read_b128 v[212:215], v150 offset:7168
	global_load_lds_dwordx4 v138, s[0:1]
	s_add_i32 m0, s22, 0xe000
	s_nop 0
	global_load_lds_dwordx4 v140, s[0:1]
	s_waitcnt lgkmcnt(8)
	s_barrier
	s_waitcnt lgkmcnt(0)
	v_mfma_f32_16x16x32_bf16 v[126:129], v[142:145], v[164:167], v[126:129]
	v_mfma_f32_16x16x32_bf16 v[126:129], v[152:155], v[168:171], v[126:129]
	v_mfma_f32_16x16x32_bf16 v[110:113], v[142:145], v[172:175], v[110:113]
	v_mfma_f32_16x16x32_bf16 v[110:113], v[152:155], v[176:179], v[110:113]
	v_mfma_f32_16x16x32_bf16 v[94:97], v[142:145], v[180:183], v[94:97]
	v_mfma_f32_16x16x32_bf16 v[94:97], v[152:155], v[204:207], v[94:97]
	v_mfma_f32_16x16x32_bf16 v[78:81], v[142:145], v[208:211], v[78:81]
	v_mfma_f32_16x16x32_bf16 v[78:81], v[152:155], v[212:215], v[78:81]
	v_mfma_f32_16x16x32_bf16 v[122:125], v[156:159], v[164:167], v[122:125]
	v_mfma_f32_16x16x32_bf16 v[122:125], v[160:163], v[168:171], v[122:125]
	v_mfma_f32_16x16x32_bf16 v[106:109], v[156:159], v[172:175], v[106:109]
	v_mfma_f32_16x16x32_bf16 v[106:109], v[160:163], v[176:179], v[106:109]
	v_mfma_f32_16x16x32_bf16 v[90:93], v[156:159], v[180:183], v[90:93]
	v_mfma_f32_16x16x32_bf16 v[90:93], v[160:163], v[204:207], v[90:93]
	v_mfma_f32_16x16x32_bf16 v[74:77], v[156:159], v[208:211], v[74:77]
	v_mfma_f32_16x16x32_bf16 v[74:77], v[160:163], v[212:215], v[74:77]
	s_barrier
	s_add_i32 s67, 0, 0x14000
	s_add_i32 s66, s66, s21
	ds_read_b128 v[216:219], v248 offset:16384
	ds_read_b128 v[220:223], v248 offset:17408
	ds_read_b128 v[224:227], v248 offset:18432
	ds_read_b128 v[228:231], v248 offset:19456
	s_add_u32 s70, s18, s6
	s_addc_u32 s71, s19, s7
	s_mov_b32 m0, s66
	s_nop 0
	global_load_lds_dwordx4 v132, s[18:19]
	s_add_i32 m0, s66, 0x2000
	s_nop 0
	global_load_lds_dwordx4 v136, s[18:19]
	s_barrier
	s_waitcnt lgkmcnt(0)
	v_mfma_f32_16x16x32_bf16 v[118:121], v[216:219], v[164:167], v[118:121]
	v_mfma_f32_16x16x32_bf16 v[118:121], v[220:223], v[168:171], v[118:121]
	v_mfma_f32_16x16x32_bf16 v[102:105], v[216:219], v[172:175], v[102:105]
	v_mfma_f32_16x16x32_bf16 v[102:105], v[220:223], v[176:179], v[102:105]
	v_mfma_f32_16x16x32_bf16 v[86:89], v[216:219], v[180:183], v[86:89]
	v_mfma_f32_16x16x32_bf16 v[86:89], v[220:223], v[204:207], v[86:89]
	v_mfma_f32_16x16x32_bf16 v[70:73], v[216:219], v[208:211], v[70:73]
	v_mfma_f32_16x16x32_bf16 v[70:73], v[220:223], v[212:215], v[70:73]
	v_mfma_f32_16x16x32_bf16 v[114:117], v[224:227], v[164:167], v[114:117]
	v_mfma_f32_16x16x32_bf16 v[114:117], v[228:231], v[168:171], v[114:117]
	v_mfma_f32_16x16x32_bf16 v[98:101], v[224:227], v[172:175], v[98:101]
	v_mfma_f32_16x16x32_bf16 v[98:101], v[228:231], v[176:179], v[98:101]
	v_mfma_f32_16x16x32_bf16 v[82:85], v[224:227], v[180:183], v[82:85]
	v_mfma_f32_16x16x32_bf16 v[82:85], v[228:231], v[204:207], v[82:85]
	v_mfma_f32_16x16x32_bf16 v[66:69], v[224:227], v[208:211], v[66:69]
	v_mfma_f32_16x16x32_bf16 v[66:69], v[228:231], v[212:215], v[66:69]
	s_barrier
	s_mov_b32 m0, s22
	s_add_u32 s72, s4, s6
	s_addc_u32 s73, s5, s7
	ds_read_b128 v[164:167], v150 offset:16384
	ds_read_b128 v[168:171], v150 offset:17408
	ds_read_b128 v[172:175], v150 offset:18432
	ds_read_b128 v[176:179], v150 offset:19456
	ds_read_b128 v[180:183], v150 offset:20480
	ds_read_b128 v[204:207], v150 offset:21504
	ds_read_b128 v[208:211], v150 offset:22528
	ds_read_b128 v[212:215], v150 offset:23552
	global_load_lds_dwordx4 v130, s[4:5]
	s_mov_b32 m0, s23
	s_nop 0
	global_load_lds_dwordx4 v134, s[4:5]
	s_barrier
	s_waitcnt lgkmcnt(0)
	v_mfma_f32_16x16x32_bf16 v[62:65], v[142:145], v[164:167], v[62:65]
	v_mfma_f32_16x16x32_bf16 v[62:65], v[152:155], v[168:171], v[62:65]
	v_mfma_f32_16x16x32_bf16 v[46:49], v[142:145], v[172:175], v[46:49]
	v_mfma_f32_16x16x32_bf16 v[46:49], v[152:155], v[176:179], v[46:49]
	v_mfma_f32_16x16x32_bf16 v[30:33], v[142:145], v[180:183], v[30:33]
	v_mfma_f32_16x16x32_bf16 v[30:33], v[152:155], v[204:207], v[30:33]
	v_mfma_f32_16x16x32_bf16 v[14:17], v[142:145], v[208:211], v[14:17]
	v_mfma_f32_16x16x32_bf16 v[14:17], v[152:155], v[212:215], v[14:17]
	v_mfma_f32_16x16x32_bf16 v[58:61], v[156:159], v[164:167], v[58:61]
	v_mfma_f32_16x16x32_bf16 v[58:61], v[160:163], v[168:171], v[58:61]
	v_mfma_f32_16x16x32_bf16 v[42:45], v[156:159], v[172:175], v[42:45]
	v_mfma_f32_16x16x32_bf16 v[42:45], v[160:163], v[176:179], v[42:45]
	v_mfma_f32_16x16x32_bf16 v[26:29], v[156:159], v[180:183], v[26:29]
	v_mfma_f32_16x16x32_bf16 v[26:29], v[160:163], v[204:207], v[26:29]
	v_mfma_f32_16x16x32_bf16 v[10:13], v[156:159], v[208:211], v[10:13]
	v_mfma_f32_16x16x32_bf16 v[10:13], v[160:163], v[212:215], v[10:13]
	s_barrier
	s_add_u32 s18, s18, s2
	s_addc_u32 s19, s19, 0
	s_add_i32 s66, s67, s21
	s_add_u32 s76, s18, s6
	s_addc_u32 s77, s19, s7
	s_mov_b32 m0, s66
	s_nop 0
	global_load_lds_dwordx4 v132, s[18:19]
	s_add_i32 m0, s66, 0x2000
	s_nop 0
	global_load_lds_dwordx4 v136, s[18:19]
	s_waitcnt vmcnt(6)
	s_barrier
	v_mfma_f32_16x16x32_bf16 v[54:57], v[216:219], v[164:167], v[54:57]
	v_mfma_f32_16x16x32_bf16 v[54:57], v[220:223], v[168:171], v[54:57]
	v_mfma_f32_16x16x32_bf16 v[38:41], v[216:219], v[172:175], v[38:41]
	v_mfma_f32_16x16x32_bf16 v[38:41], v[220:223], v[176:179], v[38:41]
	v_mfma_f32_16x16x32_bf16 v[22:25], v[216:219], v[180:183], v[22:25]
	v_mfma_f32_16x16x32_bf16 v[22:25], v[220:223], v[204:207], v[22:25]
	v_mfma_f32_16x16x32_bf16 v[6:9], v[216:219], v[208:211], v[6:9]
	v_mfma_f32_16x16x32_bf16 v[6:9], v[220:223], v[212:215], v[6:9]
	v_mfma_f32_16x16x32_bf16 v[50:53], v[224:227], v[164:167], v[50:53]
	v_mfma_f32_16x16x32_bf16 v[50:53], v[228:231], v[168:171], v[50:53]
	v_mfma_f32_16x16x32_bf16 v[34:37], v[224:227], v[172:175], v[34:37]
	v_mfma_f32_16x16x32_bf16 v[34:37], v[228:231], v[176:179], v[34:37]
	v_mfma_f32_16x16x32_bf16 v[18:21], v[224:227], v[180:183], v[18:21]
	v_mfma_f32_16x16x32_bf16 v[18:21], v[228:231], v[204:207], v[18:21]
	v_mfma_f32_16x16x32_bf16 v[2:5], v[224:227], v[208:211], v[2:5]
	v_mfma_f32_16x16x32_bf16 v[2:5], v[228:231], v[212:215], v[2:5]
	s_barrier
	s_add_i32 s18, 0, 0x18000
	ds_read_b128 v[142:145], v248 offset:32768
	ds_read_b128 v[152:155], v248 offset:33792
	ds_read_b128 v[156:159], v248 offset:34816
	ds_read_b128 v[160:163], v248 offset:35840
	s_add_u32 s4, s4, s2
	s_addc_u32 s5, s5, 0
	s_mov_b32 m0, s24
	ds_read_b128 v[164:167], v150 offset:32768
	ds_read_b128 v[168:171], v150 offset:33792
	ds_read_b128 v[172:175], v150 offset:34816
	ds_read_b128 v[176:179], v150 offset:35840
	ds_read_b128 v[180:183], v150 offset:36864
	ds_read_b128 v[204:207], v150 offset:37888
	ds_read_b128 v[208:211], v150 offset:38912
	ds_read_b128 v[212:215], v150 offset:39936
	global_load_lds_dwordx4 v130, s[4:5]
	s_mov_b32 m0, s25
	s_nop 0
	global_load_lds_dwordx4 v134, s[4:5]
	s_waitcnt lgkmcnt(8)
	s_barrier
	s_waitcnt lgkmcnt(0)
	v_mfma_f32_16x16x32_bf16 v[126:129], v[142:145], v[164:167], v[126:129]
	v_mfma_f32_16x16x32_bf16 v[126:129], v[152:155], v[168:171], v[126:129]
	v_mfma_f32_16x16x32_bf16 v[110:113], v[142:145], v[172:175], v[110:113]
	v_mfma_f32_16x16x32_bf16 v[110:113], v[152:155], v[176:179], v[110:113]
	v_mfma_f32_16x16x32_bf16 v[94:97], v[142:145], v[180:183], v[94:97]
	v_mfma_f32_16x16x32_bf16 v[94:97], v[152:155], v[204:207], v[94:97]
	v_mfma_f32_16x16x32_bf16 v[78:81], v[142:145], v[208:211], v[78:81]
	v_mfma_f32_16x16x32_bf16 v[78:81], v[152:155], v[212:215], v[78:81]
	v_mfma_f32_16x16x32_bf16 v[122:125], v[156:159], v[164:167], v[122:125]
	v_mfma_f32_16x16x32_bf16 v[122:125], v[160:163], v[168:171], v[122:125]
	v_mfma_f32_16x16x32_bf16 v[106:109], v[156:159], v[172:175], v[106:109]
	v_mfma_f32_16x16x32_bf16 v[106:109], v[160:163], v[176:179], v[106:109]
	v_mfma_f32_16x16x32_bf16 v[90:93], v[156:159], v[180:183], v[90:93]
	v_mfma_f32_16x16x32_bf16 v[90:93], v[160:163], v[204:207], v[90:93]
	v_mfma_f32_16x16x32_bf16 v[74:77], v[156:159], v[208:211], v[74:77]
	v_mfma_f32_16x16x32_bf16 v[74:77], v[160:163], v[212:215], v[74:77]
	s_barrier
	s_add_i32 s4, 0, 0x1c000
	s_add_i32 s5, s18, s21
	s_mov_b32 m0, s5
	ds_read_b128 v[216:219], v248 offset:49152
	ds_read_b128 v[220:223], v248 offset:50176
	ds_read_b128 v[224:227], v248 offset:51200
	ds_read_b128 v[228:231], v248 offset:52224
	global_load_lds_dwordx4 v132, s[70:71]
	s_add_i32 m0, s5, 0x2000
	s_nop 0
	global_load_lds_dwordx4 v136, s[70:71]
	s_barrier
	s_waitcnt lgkmcnt(0)
	v_mfma_f32_16x16x32_bf16 v[118:121], v[216:219], v[164:167], v[118:121]
	v_mfma_f32_16x16x32_bf16 v[118:121], v[220:223], v[168:171], v[118:121]
	v_mfma_f32_16x16x32_bf16 v[102:105], v[216:219], v[172:175], v[102:105]
	v_mfma_f32_16x16x32_bf16 v[102:105], v[220:223], v[176:179], v[102:105]
	v_mfma_f32_16x16x32_bf16 v[86:89], v[216:219], v[180:183], v[86:89]
	v_mfma_f32_16x16x32_bf16 v[86:89], v[220:223], v[204:207], v[86:89]
	v_mfma_f32_16x16x32_bf16 v[70:73], v[216:219], v[208:211], v[70:73]
	v_mfma_f32_16x16x32_bf16 v[70:73], v[220:223], v[212:215], v[70:73]
	v_mfma_f32_16x16x32_bf16 v[114:117], v[224:227], v[164:167], v[114:117]
	v_mfma_f32_16x16x32_bf16 v[114:117], v[228:231], v[168:171], v[114:117]
	v_mfma_f32_16x16x32_bf16 v[98:101], v[224:227], v[172:175], v[98:101]
	v_mfma_f32_16x16x32_bf16 v[98:101], v[228:231], v[176:179], v[98:101]
	v_mfma_f32_16x16x32_bf16 v[82:85], v[224:227], v[180:183], v[82:85]
	v_mfma_f32_16x16x32_bf16 v[82:85], v[228:231], v[204:207], v[82:85]
	v_mfma_f32_16x16x32_bf16 v[66:69], v[224:227], v[208:211], v[66:69]
	v_mfma_f32_16x16x32_bf16 v[66:69], v[228:231], v[212:215], v[66:69]
	s_barrier
	s_mov_b32 m0, s30
	ds_read_b128 v[164:167], v150 offset:49152
	ds_read_b128 v[168:171], v150 offset:50176
	ds_read_b128 v[172:175], v150 offset:51200
	ds_read_b128 v[176:179], v150 offset:52224
	ds_read_b128 v[180:183], v150 offset:53248
	ds_read_b128 v[204:207], v150 offset:54272
	ds_read_b128 v[208:211], v150 offset:55296
	ds_read_b128 v[212:215], v150 offset:56320
	global_load_lds_dwordx4 v130, s[72:73]
	s_mov_b32 m0, s31
	s_nop 0
	global_load_lds_dwordx4 v134, s[72:73]
	s_barrier
	s_waitcnt lgkmcnt(0)
	v_mfma_f32_16x16x32_bf16 v[62:65], v[142:145], v[164:167], v[62:65]
	v_mfma_f32_16x16x32_bf16 v[62:65], v[152:155], v[168:171], v[62:65]
	v_mfma_f32_16x16x32_bf16 v[46:49], v[142:145], v[172:175], v[46:49]
	v_mfma_f32_16x16x32_bf16 v[46:49], v[152:155], v[176:179], v[46:49]
	v_mfma_f32_16x16x32_bf16 v[30:33], v[142:145], v[180:183], v[30:33]
	v_mfma_f32_16x16x32_bf16 v[30:33], v[152:155], v[204:207], v[30:33]
	v_mfma_f32_16x16x32_bf16 v[14:17], v[142:145], v[208:211], v[14:17]
	v_mfma_f32_16x16x32_bf16 v[14:17], v[152:155], v[212:215], v[14:17]
	v_mfma_f32_16x16x32_bf16 v[58:61], v[156:159], v[164:167], v[58:61]
	v_mfma_f32_16x16x32_bf16 v[58:61], v[160:163], v[168:171], v[58:61]
	v_mfma_f32_16x16x32_bf16 v[42:45], v[156:159], v[172:175], v[42:45]
	v_mfma_f32_16x16x32_bf16 v[42:45], v[160:163], v[176:179], v[42:45]
	v_mfma_f32_16x16x32_bf16 v[26:29], v[156:159], v[180:183], v[26:29]
	v_mfma_f32_16x16x32_bf16 v[26:29], v[160:163], v[204:207], v[26:29]
	v_mfma_f32_16x16x32_bf16 v[10:13], v[156:159], v[208:211], v[10:13]
	v_mfma_f32_16x16x32_bf16 v[10:13], v[160:163], v[212:215], v[10:13]
	s_barrier
	s_add_i32 s4, s4, s21
	s_mov_b32 m0, s4
	s_nop 0
	global_load_lds_dwordx4 v132, s[76:77]
	s_add_i32 m0, s4, 0x2000
	s_nop 0
	global_load_lds_dwordx4 v136, s[76:77]
	s_add_u32 s0, s0, 0x100
	s_addc_u32 s1, s1, 0
	s_add_u32 s48, s48, 0x100
	s_addc_u32 s49, s49, 0
	s_cmp_ge_u32 s65, s27
	s_mov_b32 s4, s65
	s_waitcnt vmcnt(6)
	s_barrier
	v_mfma_f32_16x16x32_bf16 v[54:57], v[216:219], v[164:167], v[54:57]
	v_mfma_f32_16x16x32_bf16 v[54:57], v[220:223], v[168:171], v[54:57]
	v_mfma_f32_16x16x32_bf16 v[38:41], v[216:219], v[172:175], v[38:41]
	v_mfma_f32_16x16x32_bf16 v[38:41], v[220:223], v[176:179], v[38:41]
	v_mfma_f32_16x16x32_bf16 v[22:25], v[216:219], v[180:183], v[22:25]
	v_mfma_f32_16x16x32_bf16 v[22:25], v[220:223], v[204:207], v[22:25]
	v_mfma_f32_16x16x32_bf16 v[6:9], v[216:219], v[208:211], v[6:9]
	v_mfma_f32_16x16x32_bf16 v[6:9], v[220:223], v[212:215], v[6:9]
	v_mfma_f32_16x16x32_bf16 v[50:53], v[224:227], v[164:167], v[50:53]
	v_mfma_f32_16x16x32_bf16 v[50:53], v[228:231], v[168:171], v[50:53]
	v_mfma_f32_16x16x32_bf16 v[34:37], v[224:227], v[172:175], v[34:37]
	v_mfma_f32_16x16x32_bf16 v[34:37], v[228:231], v[176:179], v[34:37]
	v_mfma_f32_16x16x32_bf16 v[18:21], v[224:227], v[180:183], v[18:21]
	v_mfma_f32_16x16x32_bf16 v[18:21], v[228:231], v[204:207], v[18:21]
	v_mfma_f32_16x16x32_bf16 v[2:5], v[224:227], v[208:211], v[2:5]
	v_mfma_f32_16x16x32_bf16 v[2:5], v[228:231], v[212:215], v[2:5]
	s_barrier
	s_cbranch_scc0 .LBB0_698

.LBB0_741:
	s_add_u32 s0, s0, 0x80
	s_addc_u32 s1, s1, 0
	s_add_u32 s65, s4, 0x100
	s_addc_u32 s66, s5, 0
	s_mov_b32 s4, 0
	s_add_i32 s70, s4, 2
	s_add_u32 s10, s0, 0x80
	s_addc_u32 s5, s1, 0
	s_add_i32 s71, 0, 0x10000
	ds_read_b128 v[142:145], v248
	ds_read_b128 v[146:149], v248 offset:1024
	ds_read_b128 v[150:153], v248 offset:2048
	ds_read_b128 v[154:157], v248 offset:3072
	s_cmp_eq_u32 s43, s4
	s_cselect_b32 s4, s22, s10
	s_cselect_b32 s5, s23, s5
	s_cselect_b32 s11, s13, s66
	s_cselect_b32 s10, s12, s65
	s_add_i32 m0, s29, 0xc000
	ds_read_b128 v[158:161], v166
	ds_read_b128 v[168:171], v166 offset:1024
	ds_read_b128 v[172:175], v166 offset:2048
	ds_read_b128 v[176:179], v166 offset:3072
	ds_read_b128 v[180:183], v166 offset:4096
	ds_read_b128 v[204:207], v166 offset:5120
	ds_read_b128 v[208:211], v166 offset:6144
	ds_read_b128 v[212:215], v166 offset:7168
	global_load_lds_dwordx4 v138, s[0:1]
	s_add_i32 m0, s29, 0xe000
	s_nop 0
	global_load_lds_dwordx4 v140, s[0:1]
	s_waitcnt lgkmcnt(8)
	s_barrier
	s_waitcnt lgkmcnt(0)
	v_mfma_f32_16x16x32_bf16 v[126:129], v[142:145], v[158:161], 0
	v_mfma_f32_16x16x32_bf16 v[126:129], v[146:149], v[168:171], v[126:129]
	v_mfma_f32_16x16x32_bf16 v[110:113], v[142:145], v[172:175], 0
	v_mfma_f32_16x16x32_bf16 v[110:113], v[146:149], v[176:179], v[110:113]
	v_mfma_f32_16x16x32_bf16 v[94:97], v[142:145], v[180:183], 0
	v_mfma_f32_16x16x32_bf16 v[94:97], v[146:149], v[204:207], v[94:97]
	v_mfma_f32_16x16x32_bf16 v[78:81], v[142:145], v[208:211], 0
	v_mfma_f32_16x16x32_bf16 v[78:81], v[146:149], v[212:215], v[78:81]
	v_mfma_f32_16x16x32_bf16 v[122:125], v[150:153], v[158:161], 0
	v_mfma_f32_16x16x32_bf16 v[122:125], v[154:157], v[168:171], v[122:125]
	v_mfma_f32_16x16x32_bf16 v[106:109], v[150:153], v[172:175], 0
	v_mfma_f32_16x16x32_bf16 v[106:109], v[154:157], v[176:179], v[106:109]
	v_mfma_f32_16x16x32_bf16 v[90:93], v[150:153], v[180:183], 0
	v_mfma_f32_16x16x32_bf16 v[90:93], v[154:157], v[204:207], v[90:93]
	v_mfma_f32_16x16x32_bf16 v[74:77], v[150:153], v[208:211], 0
	v_mfma_f32_16x16x32_bf16 v[74:77], v[154:157], v[212:215], v[74:77]
	s_barrier
	s_add_i32 s72, 0, 0x14000
	s_add_i32 s71, s71, s28
	ds_read_b128 v[216:219], v248 offset:16384
	ds_read_b128 v[220:223], v248 offset:17408
	ds_read_b128 v[224:227], v248 offset:18432
	ds_read_b128 v[228:231], v248 offset:19456
	s_add_u32 s76, s10, s6
	s_addc_u32 s77, s11, s7
	s_mov_b32 m0, s71
	s_nop 0
	global_load_lds_dwordx4 v132, s[10:11]
	s_add_i32 m0, s71, 0x2000
	s_nop 0
	global_load_lds_dwordx4 v136, s[10:11]
	s_barrier
	s_waitcnt lgkmcnt(0)
	v_mfma_f32_16x16x32_bf16 v[118:121], v[216:219], v[158:161], 0
	v_mfma_f32_16x16x32_bf16 v[118:121], v[220:223], v[168:171], v[118:121]
	v_mfma_f32_16x16x32_bf16 v[102:105], v[216:219], v[172:175], 0
	v_mfma_f32_16x16x32_bf16 v[102:105], v[220:223], v[176:179], v[102:105]
	v_mfma_f32_16x16x32_bf16 v[86:89], v[216:219], v[180:183], 0
	v_mfma_f32_16x16x32_bf16 v[86:89], v[220:223], v[204:207], v[86:89]
	v_mfma_f32_16x16x32_bf16 v[70:73], v[216:219], v[208:211], 0
	v_mfma_f32_16x16x32_bf16 v[70:73], v[220:223], v[212:215], v[70:73]
	v_mfma_f32_16x16x32_bf16 v[114:117], v[224:227], v[158:161], 0
	v_mfma_f32_16x16x32_bf16 v[114:117], v[228:231], v[168:171], v[114:117]
	v_mfma_f32_16x16x32_bf16 v[98:101], v[224:227], v[172:175], 0
	v_mfma_f32_16x16x32_bf16 v[98:101], v[228:231], v[176:179], v[98:101]
	v_mfma_f32_16x16x32_bf16 v[82:85], v[224:227], v[180:183], 0
	v_mfma_f32_16x16x32_bf16 v[82:85], v[228:231], v[204:207], v[82:85]
	v_mfma_f32_16x16x32_bf16 v[66:69], v[224:227], v[208:211], 0
	v_mfma_f32_16x16x32_bf16 v[66:69], v[228:231], v[212:215], v[66:69]
	s_barrier
	s_mov_b32 m0, s29
	s_add_u32 s78, s4, s6
	s_addc_u32 s79, s5, s7
	ds_read_b128 v[158:161], v166 offset:16384
	ds_read_b128 v[168:171], v166 offset:17408
	ds_read_b128 v[172:175], v166 offset:18432
	ds_read_b128 v[176:179], v166 offset:19456
	ds_read_b128 v[180:183], v166 offset:20480
	ds_read_b128 v[204:207], v166 offset:21504
	ds_read_b128 v[208:211], v166 offset:22528
	ds_read_b128 v[212:215], v166 offset:23552
	global_load_lds_dwordx4 v130, s[4:5]
	s_mov_b32 m0, s30
	s_nop 0
	global_load_lds_dwordx4 v134, s[4:5]
	s_barrier
	s_waitcnt lgkmcnt(0)
	v_mfma_f32_16x16x32_bf16 v[62:65], v[142:145], v[158:161], 0
	v_mfma_f32_16x16x32_bf16 v[62:65], v[146:149], v[168:171], v[62:65]
	v_mfma_f32_16x16x32_bf16 v[46:49], v[142:145], v[172:175], 0
	v_mfma_f32_16x16x32_bf16 v[46:49], v[146:149], v[176:179], v[46:49]
	v_mfma_f32_16x16x32_bf16 v[30:33], v[142:145], v[180:183], 0
	v_mfma_f32_16x16x32_bf16 v[30:33], v[146:149], v[204:207], v[30:33]
	v_mfma_f32_16x16x32_bf16 v[14:17], v[142:145], v[208:211], 0
	v_mfma_f32_16x16x32_bf16 v[14:17], v[146:149], v[212:215], v[14:17]
	v_mfma_f32_16x16x32_bf16 v[58:61], v[150:153], v[158:161], 0
	v_mfma_f32_16x16x32_bf16 v[58:61], v[154:157], v[168:171], v[58:61]
	v_mfma_f32_16x16x32_bf16 v[42:45], v[150:153], v[172:175], 0
	v_mfma_f32_16x16x32_bf16 v[42:45], v[154:157], v[176:179], v[42:45]
	v_mfma_f32_16x16x32_bf16 v[26:29], v[150:153], v[180:183], 0
	v_mfma_f32_16x16x32_bf16 v[26:29], v[154:157], v[204:207], v[26:29]
	v_mfma_f32_16x16x32_bf16 v[10:13], v[150:153], v[208:211], 0
	v_mfma_f32_16x16x32_bf16 v[10:13], v[154:157], v[212:215], v[10:13]
	s_barrier
	s_add_u32 s10, s10, s2
	s_addc_u32 s11, s11, 0
	s_add_i32 s71, s72, s28
	s_add_u32 s80, s10, s6
	s_addc_u32 s81, s11, s7
	s_mov_b32 m0, s71
	s_nop 0
	global_load_lds_dwordx4 v132, s[10:11]
	s_add_i32 m0, s71, 0x2000
	s_nop 0
	global_load_lds_dwordx4 v136, s[10:11]
	s_waitcnt vmcnt(6)
	s_barrier
	v_mfma_f32_16x16x32_bf16 v[54:57], v[216:219], v[158:161], 0
	v_mfma_f32_16x16x32_bf16 v[54:57], v[220:223], v[168:171], v[54:57]
	v_mfma_f32_16x16x32_bf16 v[38:41], v[216:219], v[172:175], 0
	v_mfma_f32_16x16x32_bf16 v[38:41], v[220:223], v[176:179], v[38:41]
	v_mfma_f32_16x16x32_bf16 v[22:25], v[216:219], v[180:183], 0
	v_mfma_f32_16x16x32_bf16 v[22:25], v[220:223], v[204:207], v[22:25]
	v_mfma_f32_16x16x32_bf16 v[6:9], v[216:219], v[208:211], 0
	v_mfma_f32_16x16x32_bf16 v[6:9], v[220:223], v[212:215], v[6:9]
	v_mfma_f32_16x16x32_bf16 v[50:53], v[224:227], v[158:161], 0
	v_mfma_f32_16x16x32_bf16 v[50:53], v[228:231], v[168:171], v[50:53]
	v_mfma_f32_16x16x32_bf16 v[34:37], v[224:227], v[172:175], 0
	v_mfma_f32_16x16x32_bf16 v[34:37], v[228:231], v[176:179], v[34:37]
	v_mfma_f32_16x16x32_bf16 v[18:21], v[224:227], v[180:183], 0
	v_mfma_f32_16x16x32_bf16 v[18:21], v[228:231], v[204:207], v[18:21]
	v_mfma_f32_16x16x32_bf16 v[2:5], v[224:227], v[208:211], 0
	v_mfma_f32_16x16x32_bf16 v[2:5], v[228:231], v[212:215], v[2:5]
	s_barrier
	s_add_i32 s10, 0, 0x18000
	ds_read_b128 v[142:145], v248 offset:32768
	ds_read_b128 v[146:149], v248 offset:33792
	ds_read_b128 v[150:153], v248 offset:34816
	ds_read_b128 v[154:157], v248 offset:35840
	s_add_u32 s4, s4, s2
	s_addc_u32 s5, s5, 0
	s_mov_b32 m0, s31
	ds_read_b128 v[158:161], v166 offset:32768
	ds_read_b128 v[168:171], v166 offset:33792
	ds_read_b128 v[172:175], v166 offset:34816
	ds_read_b128 v[176:179], v166 offset:35840
	ds_read_b128 v[180:183], v166 offset:36864
	ds_read_b128 v[204:207], v166 offset:37888
	ds_read_b128 v[208:211], v166 offset:38912
	ds_read_b128 v[212:215], v166 offset:39936
	global_load_lds_dwordx4 v130, s[4:5]
	s_mov_b32 m0, s34
	s_nop 0
	global_load_lds_dwordx4 v134, s[4:5]
	s_waitcnt lgkmcnt(8)
	s_barrier
	s_waitcnt lgkmcnt(0)
	v_mfma_f32_16x16x32_bf16 v[126:129], v[142:145], v[158:161], v[126:129]
	v_mfma_f32_16x16x32_bf16 v[126:129], v[146:149], v[168:171], v[126:129]
	v_mfma_f32_16x16x32_bf16 v[110:113], v[142:145], v[172:175], v[110:113]
	v_mfma_f32_16x16x32_bf16 v[110:113], v[146:149], v[176:179], v[110:113]
	v_mfma_f32_16x16x32_bf16 v[94:97], v[142:145], v[180:183], v[94:97]
	v_mfma_f32_16x16x32_bf16 v[94:97], v[146:149], v[204:207], v[94:97]
	v_mfma_f32_16x16x32_bf16 v[78:81], v[142:145], v[208:211], v[78:81]
	v_mfma_f32_16x16x32_bf16 v[78:81], v[146:149], v[212:215], v[78:81]
	v_mfma_f32_16x16x32_bf16 v[122:125], v[150:153], v[158:161], v[122:125]
	v_mfma_f32_16x16x32_bf16 v[122:125], v[154:157], v[168:171], v[122:125]
	v_mfma_f32_16x16x32_bf16 v[106:109], v[150:153], v[172:175], v[106:109]
	v_mfma_f32_16x16x32_bf16 v[106:109], v[154:157], v[176:179], v[106:109]
	v_mfma_f32_16x16x32_bf16 v[90:93], v[150:153], v[180:183], v[90:93]
	v_mfma_f32_16x16x32_bf16 v[90:93], v[154:157], v[204:207], v[90:93]
	v_mfma_f32_16x16x32_bf16 v[74:77], v[150:153], v[208:211], v[74:77]
	v_mfma_f32_16x16x32_bf16 v[74:77], v[154:157], v[212:215], v[74:77]
	s_barrier
	s_add_i32 s4, 0, 0x1c000
	s_add_i32 s5, s10, s28
	s_mov_b32 m0, s5
	ds_read_b128 v[216:219], v248 offset:49152
	ds_read_b128 v[220:223], v248 offset:50176
	ds_read_b128 v[224:227], v248 offset:51200
	ds_read_b128 v[228:231], v248 offset:52224
	global_load_lds_dwordx4 v132, s[76:77]
	s_add_i32 m0, s5, 0x2000
	s_nop 0
	global_load_lds_dwordx4 v136, s[76:77]
	s_barrier
	s_waitcnt lgkmcnt(0)
	v_mfma_f32_16x16x32_bf16 v[118:121], v[216:219], v[158:161], v[118:121]
	v_mfma_f32_16x16x32_bf16 v[118:121], v[220:223], v[168:171], v[118:121]
	v_mfma_f32_16x16x32_bf16 v[102:105], v[216:219], v[172:175], v[102:105]
	v_mfma_f32_16x16x32_bf16 v[102:105], v[220:223], v[176:179], v[102:105]
	v_mfma_f32_16x16x32_bf16 v[86:89], v[216:219], v[180:183], v[86:89]
	v_mfma_f32_16x16x32_bf16 v[86:89], v[220:223], v[204:207], v[86:89]
	v_mfma_f32_16x16x32_bf16 v[70:73], v[216:219], v[208:211], v[70:73]
	v_mfma_f32_16x16x32_bf16 v[70:73], v[220:223], v[212:215], v[70:73]
	v_mfma_f32_16x16x32_bf16 v[114:117], v[224:227], v[158:161], v[114:117]
	v_mfma_f32_16x16x32_bf16 v[114:117], v[228:231], v[168:171], v[114:117]
	v_mfma_f32_16x16x32_bf16 v[98:101], v[224:227], v[172:175], v[98:101]
	v_mfma_f32_16x16x32_bf16 v[98:101], v[228:231], v[176:179], v[98:101]
	v_mfma_f32_16x16x32_bf16 v[82:85], v[224:227], v[180:183], v[82:85]
	v_mfma_f32_16x16x32_bf16 v[82:85], v[228:231], v[204:207], v[82:85]
	v_mfma_f32_16x16x32_bf16 v[66:69], v[224:227], v[208:211], v[66:69]
	v_mfma_f32_16x16x32_bf16 v[66:69], v[228:231], v[212:215], v[66:69]
	s_barrier
	s_mov_b32 m0, s41
	ds_read_b128 v[158:161], v166 offset:49152
	ds_read_b128 v[168:171], v166 offset:50176
	ds_read_b128 v[172:175], v166 offset:51200
	ds_read_b128 v[176:179], v166 offset:52224
	ds_read_b128 v[180:183], v166 offset:53248
	ds_read_b128 v[204:207], v166 offset:54272
	ds_read_b128 v[208:211], v166 offset:55296
	ds_read_b128 v[212:215], v166 offset:56320
	global_load_lds_dwordx4 v130, s[78:79]
	s_mov_b32 m0, s42
	s_nop 0
	global_load_lds_dwordx4 v134, s[78:79]
	s_barrier
	s_waitcnt lgkmcnt(0)
	v_mfma_f32_16x16x32_bf16 v[62:65], v[142:145], v[158:161], v[62:65]
	v_mfma_f32_16x16x32_bf16 v[62:65], v[146:149], v[168:171], v[62:65]
	v_mfma_f32_16x16x32_bf16 v[46:49], v[142:145], v[172:175], v[46:49]
	v_mfma_f32_16x16x32_bf16 v[46:49], v[146:149], v[176:179], v[46:49]
	v_mfma_f32_16x16x32_bf16 v[30:33], v[142:145], v[180:183], v[30:33]
	v_mfma_f32_16x16x32_bf16 v[30:33], v[146:149], v[204:207], v[30:33]
	v_mfma_f32_16x16x32_bf16 v[14:17], v[142:145], v[208:211], v[14:17]
	v_mfma_f32_16x16x32_bf16 v[14:17], v[146:149], v[212:215], v[14:17]
	v_mfma_f32_16x16x32_bf16 v[58:61], v[150:153], v[158:161], v[58:61]
	v_mfma_f32_16x16x32_bf16 v[58:61], v[154:157], v[168:171], v[58:61]
	v_mfma_f32_16x16x32_bf16 v[42:45], v[150:153], v[172:175], v[42:45]
	v_mfma_f32_16x16x32_bf16 v[42:45], v[154:157], v[176:179], v[42:45]
	v_mfma_f32_16x16x32_bf16 v[26:29], v[150:153], v[180:183], v[26:29]
	v_mfma_f32_16x16x32_bf16 v[26:29], v[154:157], v[204:207], v[26:29]
	v_mfma_f32_16x16x32_bf16 v[10:13], v[150:153], v[208:211], v[10:13]
	v_mfma_f32_16x16x32_bf16 v[10:13], v[154:157], v[212:215], v[10:13]
	s_barrier
	s_add_i32 s4, s4, s28
	s_mov_b32 m0, s4
	s_nop 0
	global_load_lds_dwordx4 v132, s[80:81]
	s_add_i32 m0, s4, 0x2000
	s_nop 0
	global_load_lds_dwordx4 v136, s[80:81]
	s_add_u32 s0, s0, 0x100
	s_addc_u32 s1, s1, 0
	s_add_u32 s65, s65, 0x100
	s_addc_u32 s66, s66, 0
	s_cmp_ge_u32 s70, s35
	s_mov_b32 s4, s70
	s_waitcnt vmcnt(6)
	s_barrier
	v_mfma_f32_16x16x32_bf16 v[54:57], v[216:219], v[158:161], v[54:57]
	v_mfma_f32_16x16x32_bf16 v[54:57], v[220:223], v[168:171], v[54:57]
	v_mfma_f32_16x16x32_bf16 v[38:41], v[216:219], v[172:175], v[38:41]
	v_mfma_f32_16x16x32_bf16 v[38:41], v[220:223], v[176:179], v[38:41]
	v_mfma_f32_16x16x32_bf16 v[22:25], v[216:219], v[180:183], v[22:25]
	v_mfma_f32_16x16x32_bf16 v[22:25], v[220:223], v[204:207], v[22:25]
	v_mfma_f32_16x16x32_bf16 v[6:9], v[216:219], v[208:211], v[6:9]
	v_mfma_f32_16x16x32_bf16 v[6:9], v[220:223], v[212:215], v[6:9]
	v_mfma_f32_16x16x32_bf16 v[50:53], v[224:227], v[158:161], v[50:53]
	v_mfma_f32_16x16x32_bf16 v[50:53], v[228:231], v[168:171], v[50:53]
	v_mfma_f32_16x16x32_bf16 v[34:37], v[224:227], v[172:175], v[34:37]
	v_mfma_f32_16x16x32_bf16 v[34:37], v[228:231], v[176:179], v[34:37]
	v_mfma_f32_16x16x32_bf16 v[18:21], v[224:227], v[180:183], v[18:21]
	v_mfma_f32_16x16x32_bf16 v[18:21], v[228:231], v[204:207], v[18:21]
	v_mfma_f32_16x16x32_bf16 v[2:5], v[224:227], v[208:211], v[2:5]
	v_mfma_f32_16x16x32_bf16 v[2:5], v[228:231], v[212:215], v[2:5]
	s_barrier
	s_cbranch_scc1 .Lkexit_742
.LBB0_742:
	s_add_i32 s70, s4, 2
	s_add_u32 s10, s0, 0x80
	s_addc_u32 s5, s1, 0
	s_add_i32 s71, 0, 0x10000
	ds_read_b128 v[142:145], v248
	ds_read_b128 v[146:149], v248 offset:1024
	ds_read_b128 v[150:153], v248 offset:2048
	ds_read_b128 v[154:157], v248 offset:3072
	s_cmp_eq_u32 s43, s4
	s_cselect_b32 s4, s22, s10
	s_cselect_b32 s5, s23, s5
	s_cselect_b32 s11, s13, s66
	s_cselect_b32 s10, s12, s65
	s_add_i32 m0, s29, 0xc000
	ds_read_b128 v[158:161], v166
	ds_read_b128 v[168:171], v166 offset:1024
	ds_read_b128 v[172:175], v166 offset:2048
	ds_read_b128 v[176:179], v166 offset:3072
	ds_read_b128 v[180:183], v166 offset:4096
	ds_read_b128 v[204:207], v166 offset:5120
	ds_read_b128 v[208:211], v166 offset:6144
	ds_read_b128 v[212:215], v166 offset:7168
	global_load_lds_dwordx4 v138, s[0:1]
	s_add_i32 m0, s29, 0xe000
	s_nop 0
	global_load_lds_dwordx4 v140, s[0:1]
	s_waitcnt lgkmcnt(8)
	s_barrier
	s_waitcnt lgkmcnt(0)
	v_mfma_f32_16x16x32_bf16 v[126:129], v[142:145], v[158:161], v[126:129]
	v_mfma_f32_16x16x32_bf16 v[126:129], v[146:149], v[168:171], v[126:129]
	v_mfma_f32_16x16x32_bf16 v[110:113], v[142:145], v[172:175], v[110:113]
	v_mfma_f32_16x16x32_bf16 v[110:113], v[146:149], v[176:179], v[110:113]
	v_mfma_f32_16x16x32_bf16 v[94:97], v[142:145], v[180:183], v[94:97]
	v_mfma_f32_16x16x32_bf16 v[94:97], v[146:149], v[204:207], v[94:97]
	v_mfma_f32_16x16x32_bf16 v[78:81], v[142:145], v[208:211], v[78:81]
	v_mfma_f32_16x16x32_bf16 v[78:81], v[146:149], v[212:215], v[78:81]
	v_mfma_f32_16x16x32_bf16 v[122:125], v[150:153], v[158:161], v[122:125]
	v_mfma_f32_16x16x32_bf16 v[122:125], v[154:157], v[168:171], v[122:125]
	v_mfma_f32_16x16x32_bf16 v[106:109], v[150:153], v[172:175], v[106:109]
	v_mfma_f32_16x16x32_bf16 v[106:109], v[154:157], v[176:179], v[106:109]
	v_mfma_f32_16x16x32_bf16 v[90:93], v[150:153], v[180:183], v[90:93]
	v_mfma_f32_16x16x32_bf16 v[90:93], v[154:157], v[204:207], v[90:93]
	v_mfma_f32_16x16x32_bf16 v[74:77], v[150:153], v[208:211], v[74:77]
	v_mfma_f32_16x16x32_bf16 v[74:77], v[154:157], v[212:215], v[74:77]
	s_barrier
	s_add_i32 s72, 0, 0x14000
	s_add_i32 s71, s71, s28
	ds_read_b128 v[216:219], v248 offset:16384
	ds_read_b128 v[220:223], v248 offset:17408
	ds_read_b128 v[224:227], v248 offset:18432
	ds_read_b128 v[228:231], v248 offset:19456
	s_add_u32 s76, s10, s6
	s_addc_u32 s77, s11, s7
	s_mov_b32 m0, s71
	s_nop 0
	global_load_lds_dwordx4 v132, s[10:11]
	s_add_i32 m0, s71, 0x2000
	s_nop 0
	global_load_lds_dwordx4 v136, s[10:11]
	s_barrier
	s_waitcnt lgkmcnt(0)
	v_mfma_f32_16x16x32_bf16 v[118:121], v[216:219], v[158:161], v[118:121]
	v_mfma_f32_16x16x32_bf16 v[118:121], v[220:223], v[168:171], v[118:121]
	v_mfma_f32_16x16x32_bf16 v[102:105], v[216:219], v[172:175], v[102:105]
	v_mfma_f32_16x16x32_bf16 v[102:105], v[220:223], v[176:179], v[102:105]
	v_mfma_f32_16x16x32_bf16 v[86:89], v[216:219], v[180:183], v[86:89]
	v_mfma_f32_16x16x32_bf16 v[86:89], v[220:223], v[204:207], v[86:89]
	v_mfma_f32_16x16x32_bf16 v[70:73], v[216:219], v[208:211], v[70:73]
	v_mfma_f32_16x16x32_bf16 v[70:73], v[220:223], v[212:215], v[70:73]
	v_mfma_f32_16x16x32_bf16 v[114:117], v[224:227], v[158:161], v[114:117]
	v_mfma_f32_16x16x32_bf16 v[114:117], v[228:231], v[168:171], v[114:117]
	v_mfma_f32_16x16x32_bf16 v[98:101], v[224:227], v[172:175], v[98:101]
	v_mfma_f32_16x16x32_bf16 v[98:101], v[228:231], v[176:179], v[98:101]
	v_mfma_f32_16x16x32_bf16 v[82:85], v[224:227], v[180:183], v[82:85]
	v_mfma_f32_16x16x32_bf16 v[82:85], v[228:231], v[204:207], v[82:85]
	v_mfma_f32_16x16x32_bf16 v[66:69], v[224:227], v[208:211], v[66:69]
	v_mfma_f32_16x16x32_bf16 v[66:69], v[228:231], v[212:215], v[66:69]
	s_barrier
	s_mov_b32 m0, s29
	s_add_u32 s78, s4, s6
	s_addc_u32 s79, s5, s7
	ds_read_b128 v[158:161], v166 offset:16384
	ds_read_b128 v[168:171], v166 offset:17408
	ds_read_b128 v[172:175], v166 offset:18432
	ds_read_b128 v[176:179], v166 offset:19456
	ds_read_b128 v[180:183], v166 offset:20480
	ds_read_b128 v[204:207], v166 offset:21504
	ds_read_b128 v[208:211], v166 offset:22528
	ds_read_b128 v[212:215], v166 offset:23552
	global_load_lds_dwordx4 v130, s[4:5]
	s_mov_b32 m0, s30
	s_nop 0
	global_load_lds_dwordx4 v134, s[4:5]
	s_barrier
	s_waitcnt lgkmcnt(0)
	v_mfma_f32_16x16x32_bf16 v[62:65], v[142:145], v[158:161], v[62:65]
	v_mfma_f32_16x16x32_bf16 v[62:65], v[146:149], v[168:171], v[62:65]
	v_mfma_f32_16x16x32_bf16 v[46:49], v[142:145], v[172:175], v[46:49]
	v_mfma_f32_16x16x32_bf16 v[46:49], v[146:149], v[176:179], v[46:49]
	v_mfma_f32_16x16x32_bf16 v[30:33], v[142:145], v[180:183], v[30:33]
	v_mfma_f32_16x16x32_bf16 v[30:33], v[146:149], v[204:207], v[30:33]
	v_mfma_f32_16x16x32_bf16 v[14:17], v[142:145], v[208:211], v[14:17]
	v_mfma_f32_16x16x32_bf16 v[14:17], v[146:149], v[212:215], v[14:17]
	v_mfma_f32_16x16x32_bf16 v[58:61], v[150:153], v[158:161], v[58:61]
	v_mfma_f32_16x16x32_bf16 v[58:61], v[154:157], v[168:171], v[58:61]
	v_mfma_f32_16x16x32_bf16 v[42:45], v[150:153], v[172:175], v[42:45]
	v_mfma_f32_16x16x32_bf16 v[42:45], v[154:157], v[176:179], v[42:45]
	v_mfma_f32_16x16x32_bf16 v[26:29], v[150:153], v[180:183], v[26:29]
	v_mfma_f32_16x16x32_bf16 v[26:29], v[154:157], v[204:207], v[26:29]
	v_mfma_f32_16x16x32_bf16 v[10:13], v[150:153], v[208:211], v[10:13]
	v_mfma_f32_16x16x32_bf16 v[10:13], v[154:157], v[212:215], v[10:13]
	s_barrier
	s_add_u32 s10, s10, s2
	s_addc_u32 s11, s11, 0
	s_add_i32 s71, s72, s28
	s_add_u32 s80, s10, s6
	s_addc_u32 s81, s11, s7
	s_mov_b32 m0, s71
	s_nop 0
	global_load_lds_dwordx4 v132, s[10:11]
	s_add_i32 m0, s71, 0x2000
	s_nop 0
	global_load_lds_dwordx4 v136, s[10:11]
	s_waitcnt vmcnt(6)
	s_barrier
	v_mfma_f32_16x16x32_bf16 v[54:57], v[216:219], v[158:161], v[54:57]
	v_mfma_f32_16x16x32_bf16 v[54:57], v[220:223], v[168:171], v[54:57]
	v_mfma_f32_16x16x32_bf16 v[38:41], v[216:219], v[172:175], v[38:41]
	v_mfma_f32_16x16x32_bf16 v[38:41], v[220:223], v[176:179], v[38:41]
	v_mfma_f32_16x16x32_bf16 v[22:25], v[216:219], v[180:183], v[22:25]
	v_mfma_f32_16x16x32_bf16 v[22:25], v[220:223], v[204:207], v[22:25]
	v_mfma_f32_16x16x32_bf16 v[6:9], v[216:219], v[208:211], v[6:9]
	v_mfma_f32_16x16x32_bf16 v[6:9], v[220:223], v[212:215], v[6:9]
	v_mfma_f32_16x16x32_bf16 v[50:53], v[224:227], v[158:161], v[50:53]
	v_mfma_f32_16x16x32_bf16 v[50:53], v[228:231], v[168:171], v[50:53]
	v_mfma_f32_16x16x32_bf16 v[34:37], v[224:227], v[172:175], v[34:37]
	v_mfma_f32_16x16x32_bf16 v[34:37], v[228:231], v[176:179], v[34:37]
	v_mfma_f32_16x16x32_bf16 v[18:21], v[224:227], v[180:183], v[18:21]
	v_mfma_f32_16x16x32_bf16 v[18:21], v[228:231], v[204:207], v[18:21]
	v_mfma_f32_16x16x32_bf16 v[2:5], v[224:227], v[208:211], v[2:5]
	v_mfma_f32_16x16x32_bf16 v[2:5], v[228:231], v[212:215], v[2:5]
	s_barrier
	s_add_i32 s10, 0, 0x18000
	ds_read_b128 v[142:145], v248 offset:32768
	ds_read_b128 v[146:149], v248 offset:33792
	ds_read_b128 v[150:153], v248 offset:34816
	ds_read_b128 v[154:157], v248 offset:35840
	s_add_u32 s4, s4, s2
	s_addc_u32 s5, s5, 0
	s_mov_b32 m0, s31
	ds_read_b128 v[158:161], v166 offset:32768
	ds_read_b128 v[168:171], v166 offset:33792
	ds_read_b128 v[172:175], v166 offset:34816
	ds_read_b128 v[176:179], v166 offset:35840
	ds_read_b128 v[180:183], v166 offset:36864
	ds_read_b128 v[204:207], v166 offset:37888
	ds_read_b128 v[208:211], v166 offset:38912
	ds_read_b128 v[212:215], v166 offset:39936
	global_load_lds_dwordx4 v130, s[4:5]
	s_mov_b32 m0, s34
	s_nop 0
	global_load_lds_dwordx4 v134, s[4:5]
	s_waitcnt lgkmcnt(8)
	s_barrier
	s_waitcnt lgkmcnt(0)
	v_mfma_f32_16x16x32_bf16 v[126:129], v[142:145], v[158:161], v[126:129]
	v_mfma_f32_16x16x32_bf16 v[126:129], v[146:149], v[168:171], v[126:129]
	v_mfma_f32_16x16x32_bf16 v[110:113], v[142:145], v[172:175], v[110:113]
	v_mfma_f32_16x16x32_bf16 v[110:113], v[146:149], v[176:179], v[110:113]
	v_mfma_f32_16x16x32_bf16 v[94:97], v[142:145], v[180:183], v[94:97]
	v_mfma_f32_16x16x32_bf16 v[94:97], v[146:149], v[204:207], v[94:97]
	v_mfma_f32_16x16x32_bf16 v[78:81], v[142:145], v[208:211], v[78:81]
	v_mfma_f32_16x16x32_bf16 v[78:81], v[146:149], v[212:215], v[78:81]
	v_mfma_f32_16x16x32_bf16 v[122:125], v[150:153], v[158:161], v[122:125]
	v_mfma_f32_16x16x32_bf16 v[122:125], v[154:157], v[168:171], v[122:125]
	v_mfma_f32_16x16x32_bf16 v[106:109], v[150:153], v[172:175], v[106:109]
	v_mfma_f32_16x16x32_bf16 v[106:109], v[154:157], v[176:179], v[106:109]
	v_mfma_f32_16x16x32_bf16 v[90:93], v[150:153], v[180:183], v[90:93]
	v_mfma_f32_16x16x32_bf16 v[90:93], v[154:157], v[204:207], v[90:93]
	v_mfma_f32_16x16x32_bf16 v[74:77], v[150:153], v[208:211], v[74:77]
	v_mfma_f32_16x16x32_bf16 v[74:77], v[154:157], v[212:215], v[74:77]
	s_barrier
	s_add_i32 s4, 0, 0x1c000
	s_add_i32 s5, s10, s28
	s_mov_b32 m0, s5
	ds_read_b128 v[216:219], v248 offset:49152
	ds_read_b128 v[220:223], v248 offset:50176
	ds_read_b128 v[224:227], v248 offset:51200
	ds_read_b128 v[228:231], v248 offset:52224
	global_load_lds_dwordx4 v132, s[76:77]
	s_add_i32 m0, s5, 0x2000
	s_nop 0
	global_load_lds_dwordx4 v136, s[76:77]
	s_barrier
	s_waitcnt lgkmcnt(0)
	v_mfma_f32_16x16x32_bf16 v[118:121], v[216:219], v[158:161], v[118:121]
	v_mfma_f32_16x16x32_bf16 v[118:121], v[220:223], v[168:171], v[118:121]
	v_mfma_f32_16x16x32_bf16 v[102:105], v[216:219], v[172:175], v[102:105]
	v_mfma_f32_16x16x32_bf16 v[102:105], v[220:223], v[176:179], v[102:105]
	v_mfma_f32_16x16x32_bf16 v[86:89], v[216:219], v[180:183], v[86:89]
	v_mfma_f32_16x16x32_bf16 v[86:89], v[220:223], v[204:207], v[86:89]
	v_mfma_f32_16x16x32_bf16 v[70:73], v[216:219], v[208:211], v[70:73]
	v_mfma_f32_16x16x32_bf16 v[70:73], v[220:223], v[212:215], v[70:73]
	v_mfma_f32_16x16x32_bf16 v[114:117], v[224:227], v[158:161], v[114:117]
	v_mfma_f32_16x16x32_bf16 v[114:117], v[228:231], v[168:171], v[114:117]
	v_mfma_f32_16x16x32_bf16 v[98:101], v[224:227], v[172:175], v[98:101]
	v_mfma_f32_16x16x32_bf16 v[98:101], v[228:231], v[176:179], v[98:101]
	v_mfma_f32_16x16x32_bf16 v[82:85], v[224:227], v[180:183], v[82:85]
	v_mfma_f32_16x16x32_bf16 v[82:85], v[228:231], v[204:207], v[82:85]
	v_mfma_f32_16x16x32_bf16 v[66:69], v[224:227], v[208:211], v[66:69]
	v_mfma_f32_16x16x32_bf16 v[66:69], v[228:231], v[212:215], v[66:69]
	s_barrier
	s_mov_b32 m0, s41
	ds_read_b128 v[158:161], v166 offset:49152
	ds_read_b128 v[168:171], v166 offset:50176
	ds_read_b128 v[172:175], v166 offset:51200
	ds_read_b128 v[176:179], v166 offset:52224
	ds_read_b128 v[180:183], v166 offset:53248
	ds_read_b128 v[204:207], v166 offset:54272
	ds_read_b128 v[208:211], v166 offset:55296
	ds_read_b128 v[212:215], v166 offset:56320
	global_load_lds_dwordx4 v130, s[78:79]
	s_mov_b32 m0, s42
	s_nop 0
	global_load_lds_dwordx4 v134, s[78:79]
	s_barrier
	s_waitcnt lgkmcnt(0)
	v_mfma_f32_16x16x32_bf16 v[62:65], v[142:145], v[158:161], v[62:65]
	v_mfma_f32_16x16x32_bf16 v[62:65], v[146:149], v[168:171], v[62:65]
	v_mfma_f32_16x16x32_bf16 v[46:49], v[142:145], v[172:175], v[46:49]
	v_mfma_f32_16x16x32_bf16 v[46:49], v[146:149], v[176:179], v[46:49]
	v_mfma_f32_16x16x32_bf16 v[30:33], v[142:145], v[180:183], v[30:33]
	v_mfma_f32_16x16x32_bf16 v[30:33], v[146:149], v[204:207], v[30:33]
	v_mfma_f32_16x16x32_bf16 v[14:17], v[142:145], v[208:211], v[14:17]
	v_mfma_f32_16x16x32_bf16 v[14:17], v[146:149], v[212:215], v[14:17]
	v_mfma_f32_16x16x32_bf16 v[58:61], v[150:153], v[158:161], v[58:61]
	v_mfma_f32_16x16x32_bf16 v[58:61], v[154:157], v[168:171], v[58:61]
	v_mfma_f32_16x16x32_bf16 v[42:45], v[150:153], v[172:175], v[42:45]
	v_mfma_f32_16x16x32_bf16 v[42:45], v[154:157], v[176:179], v[42:45]
	v_mfma_f32_16x16x32_bf16 v[26:29], v[150:153], v[180:183], v[26:29]
	v_mfma_f32_16x16x32_bf16 v[26:29], v[154:157], v[204:207], v[26:29]
	v_mfma_f32_16x16x32_bf16 v[10:13], v[150:153], v[208:211], v[10:13]
	v_mfma_f32_16x16x32_bf16 v[10:13], v[154:157], v[212:215], v[10:13]
	s_barrier
	s_add_i32 s4, s4, s28
	s_mov_b32 m0, s4
	s_nop 0
	global_load_lds_dwordx4 v132, s[80:81]
	s_add_i32 m0, s4, 0x2000
	s_nop 0
	global_load_lds_dwordx4 v136, s[80:81]
	s_add_u32 s0, s0, 0x100
	s_addc_u32 s1, s1, 0
	s_add_u32 s65, s65, 0x100
	s_addc_u32 s66, s66, 0
	s_cmp_ge_u32 s70, s35
	s_mov_b32 s4, s70
	s_waitcnt vmcnt(6)
	s_barrier
	v_mfma_f32_16x16x32_bf16 v[54:57], v[216:219], v[158:161], v[54:57]
	v_mfma_f32_16x16x32_bf16 v[54:57], v[220:223], v[168:171], v[54:57]
	v_mfma_f32_16x16x32_bf16 v[38:41], v[216:219], v[172:175], v[38:41]
	v_mfma_f32_16x16x32_bf16 v[38:41], v[220:223], v[176:179], v[38:41]
	v_mfma_f32_16x16x32_bf16 v[22:25], v[216:219], v[180:183], v[22:25]
	v_mfma_f32_16x16x32_bf16 v[22:25], v[220:223], v[204:207], v[22:25]
	v_mfma_f32_16x16x32_bf16 v[6:9], v[216:219], v[208:211], v[6:9]
	v_mfma_f32_16x16x32_bf16 v[6:9], v[220:223], v[212:215], v[6:9]
	v_mfma_f32_16x16x32_bf16 v[50:53], v[224:227], v[158:161], v[50:53]
	v_mfma_f32_16x16x32_bf16 v[50:53], v[228:231], v[168:171], v[50:53]
	v_mfma_f32_16x16x32_bf16 v[34:37], v[224:227], v[172:175], v[34:37]
	v_mfma_f32_16x16x32_bf16 v[34:37], v[228:231], v[176:179], v[34:37]
	v_mfma_f32_16x16x32_bf16 v[18:21], v[224:227], v[180:183], v[18:21]
	v_mfma_f32_16x16x32_bf16 v[18:21], v[228:231], v[204:207], v[18:21]
	v_mfma_f32_16x16x32_bf16 v[2:5], v[224:227], v[208:211], v[2:5]
	v_mfma_f32_16x16x32_bf16 v[2:5], v[228:231], v[212:215], v[2:5]
	s_barrier
	s_cbranch_scc0 .LBB0_742

.LBB0_805:
	s_add_u32 s0, s0, 0x80
	s_addc_u32 s1, s1, 0
	s_add_u32 s12, s4, 0x100
	s_addc_u32 s13, s5, 0
	s_mov_b32 s4, 0
	s_waitcnt vmcnt(0)
	s_add_i32 s27, s4, 2
	s_add_u32 s10, s0, 0x80
	s_addc_u32 s5, s1, 0
	s_add_i32 s28, 0, 0x10000
	ds_read_b128 v[142:145], v248
	ds_read_b128 v[146:149], v248 offset:1024
	ds_read_b128 v[150:153], v248 offset:2048
	ds_read_b128 v[154:157], v248 offset:3072
	s_cmp_eq_u32 s48, s4
	s_cselect_b32 s4, s22, s10
	s_cselect_b32 s5, s23, s5
	s_cselect_b32 s11, s25, s13
	s_cselect_b32 s10, s24, s12
	s_add_i32 m0, s35, 0xc000
	ds_read_b128 v[158:161], v172
	ds_read_b128 v[162:165], v172 offset:1024
	ds_read_b128 v[166:169], v172 offset:2048
	ds_read_b128 v[174:177], v172 offset:3072
	ds_read_b128 v[178:181], v172 offset:4096
	ds_read_b128 v[182:185], v172 offset:5120
	ds_read_b128 v[204:207], v172 offset:6144
	ds_read_b128 v[208:211], v172 offset:7168
	global_load_lds_dwordx4 v138, s[0:1]
	s_add_i32 m0, s35, 0xe000
	s_nop 0
	global_load_lds_dwordx4 v140, s[0:1]
	s_waitcnt lgkmcnt(8)
	s_barrier
	s_waitcnt lgkmcnt(0)
	v_mfma_f32_16x16x32_bf16 v[126:129], v[142:145], v[158:161], 0
	v_mfma_f32_16x16x32_bf16 v[126:129], v[146:149], v[162:165], v[126:129]
	v_mfma_f32_16x16x32_bf16 v[110:113], v[142:145], v[166:169], 0
	v_mfma_f32_16x16x32_bf16 v[110:113], v[146:149], v[174:177], v[110:113]
	v_mfma_f32_16x16x32_bf16 v[94:97], v[142:145], v[178:181], 0
	v_mfma_f32_16x16x32_bf16 v[94:97], v[146:149], v[182:185], v[94:97]
	v_mfma_f32_16x16x32_bf16 v[78:81], v[142:145], v[204:207], 0
	v_mfma_f32_16x16x32_bf16 v[78:81], v[146:149], v[208:211], v[78:81]
	v_mfma_f32_16x16x32_bf16 v[122:125], v[150:153], v[158:161], 0
	v_mfma_f32_16x16x32_bf16 v[122:125], v[154:157], v[162:165], v[122:125]
	v_mfma_f32_16x16x32_bf16 v[106:109], v[150:153], v[166:169], 0
	v_mfma_f32_16x16x32_bf16 v[106:109], v[154:157], v[174:177], v[106:109]
	v_mfma_f32_16x16x32_bf16 v[90:93], v[150:153], v[178:181], 0
	v_mfma_f32_16x16x32_bf16 v[90:93], v[154:157], v[182:185], v[90:93]
	v_mfma_f32_16x16x32_bf16 v[74:77], v[150:153], v[204:207], 0
	v_mfma_f32_16x16x32_bf16 v[74:77], v[154:157], v[208:211], v[74:77]
	s_barrier
	s_add_i32 s29, 0, 0x14000
	s_add_i32 s28, s28, s34
	s_add_u32 s78, s10, s6
	s_addc_u32 s79, s11, s7
	s_mov_b32 m0, s28
	ds_read_b128 v[212:215], v248 offset:16384
	ds_read_b128 v[216:219], v248 offset:17408
	ds_read_b128 v[220:223], v248 offset:18432
	ds_read_b128 v[224:227], v248 offset:19456
	global_load_lds_dwordx4 v132, s[10:11]
	s_add_i32 m0, s28, 0x2000
	s_nop 0
	global_load_lds_dwordx4 v136, s[10:11]
	s_barrier
	s_waitcnt lgkmcnt(0)
	v_mfma_f32_16x16x32_bf16 v[118:121], v[212:215], v[158:161], 0
	v_mfma_f32_16x16x32_bf16 v[118:121], v[216:219], v[162:165], v[118:121]
	v_mfma_f32_16x16x32_bf16 v[102:105], v[212:215], v[166:169], 0
	v_mfma_f32_16x16x32_bf16 v[102:105], v[216:219], v[174:177], v[102:105]
	v_mfma_f32_16x16x32_bf16 v[86:89], v[212:215], v[178:181], 0
	v_mfma_f32_16x16x32_bf16 v[86:89], v[216:219], v[182:185], v[86:89]
	v_mfma_f32_16x16x32_bf16 v[70:73], v[212:215], v[204:207], 0
	v_mfma_f32_16x16x32_bf16 v[70:73], v[216:219], v[208:211], v[70:73]
	v_mfma_f32_16x16x32_bf16 v[114:117], v[220:223], v[158:161], 0
	v_mfma_f32_16x16x32_bf16 v[114:117], v[224:227], v[162:165], v[114:117]
	v_mfma_f32_16x16x32_bf16 v[98:101], v[220:223], v[166:169], 0
	v_mfma_f32_16x16x32_bf16 v[98:101], v[224:227], v[174:177], v[98:101]
	v_mfma_f32_16x16x32_bf16 v[82:85], v[220:223], v[178:181], 0
	v_mfma_f32_16x16x32_bf16 v[82:85], v[224:227], v[182:185], v[82:85]
	v_mfma_f32_16x16x32_bf16 v[66:69], v[220:223], v[204:207], 0
	v_mfma_f32_16x16x32_bf16 v[66:69], v[224:227], v[208:211], v[66:69]
	s_barrier
	s_mov_b32 m0, s35
	s_add_u32 s80, s4, s6
	s_addc_u32 s81, s5, s7
	ds_read_b128 v[158:161], v172 offset:16384
	ds_read_b128 v[162:165], v172 offset:17408
	ds_read_b128 v[166:169], v172 offset:18432
	ds_read_b128 v[174:177], v172 offset:19456
	ds_read_b128 v[178:181], v172 offset:20480
	ds_read_b128 v[182:185], v172 offset:21504
	ds_read_b128 v[204:207], v172 offset:22528
	ds_read_b128 v[208:211], v172 offset:23552
	global_load_lds_dwordx4 v130, s[4:5]
	s_mov_b32 m0, s40
	s_nop 0
	global_load_lds_dwordx4 v134, s[4:5]
	s_barrier
	s_waitcnt lgkmcnt(0)
	v_mfma_f32_16x16x32_bf16 v[62:65], v[142:145], v[158:161], 0
	v_mfma_f32_16x16x32_bf16 v[62:65], v[146:149], v[162:165], v[62:65]
	v_mfma_f32_16x16x32_bf16 v[46:49], v[142:145], v[166:169], 0
	v_mfma_f32_16x16x32_bf16 v[46:49], v[146:149], v[174:177], v[46:49]
	v_mfma_f32_16x16x32_bf16 v[30:33], v[142:145], v[178:181], 0
	v_mfma_f32_16x16x32_bf16 v[30:33], v[146:149], v[182:185], v[30:33]
	v_mfma_f32_16x16x32_bf16 v[14:17], v[142:145], v[204:207], 0
	v_mfma_f32_16x16x32_bf16 v[14:17], v[146:149], v[208:211], v[14:17]
	v_mfma_f32_16x16x32_bf16 v[58:61], v[150:153], v[158:161], 0
	v_mfma_f32_16x16x32_bf16 v[58:61], v[154:157], v[162:165], v[58:61]
	v_mfma_f32_16x16x32_bf16 v[42:45], v[150:153], v[166:169], 0
	v_mfma_f32_16x16x32_bf16 v[42:45], v[154:157], v[174:177], v[42:45]
	v_mfma_f32_16x16x32_bf16 v[26:29], v[150:153], v[178:181], 0
	v_mfma_f32_16x16x32_bf16 v[26:29], v[154:157], v[182:185], v[26:29]
	v_mfma_f32_16x16x32_bf16 v[10:13], v[150:153], v[204:207], 0
	v_mfma_f32_16x16x32_bf16 v[10:13], v[154:157], v[208:211], v[10:13]
	s_barrier
	s_add_u32 s10, s10, s92
	s_addc_u32 s11, s11, 0
	s_add_i32 s28, s29, s34
	s_add_u32 s58, s10, s6
	s_addc_u32 s59, s11, s7
	s_mov_b32 m0, s28
	s_nop 0
	global_load_lds_dwordx4 v132, s[10:11]
	s_add_i32 m0, s28, 0x2000
	s_nop 0
	global_load_lds_dwordx4 v136, s[10:11]
	s_waitcnt vmcnt(6)
	s_barrier
	v_mfma_f32_16x16x32_bf16 v[54:57], v[212:215], v[158:161], 0
	v_mfma_f32_16x16x32_bf16 v[54:57], v[216:219], v[162:165], v[54:57]
	v_mfma_f32_16x16x32_bf16 v[38:41], v[212:215], v[166:169], 0
	v_mfma_f32_16x16x32_bf16 v[38:41], v[216:219], v[174:177], v[38:41]
	v_mfma_f32_16x16x32_bf16 v[22:25], v[212:215], v[178:181], 0
	v_mfma_f32_16x16x32_bf16 v[22:25], v[216:219], v[182:185], v[22:25]
	v_mfma_f32_16x16x32_bf16 v[6:9], v[212:215], v[204:207], 0
	v_mfma_f32_16x16x32_bf16 v[6:9], v[216:219], v[208:211], v[6:9]
	v_mfma_f32_16x16x32_bf16 v[50:53], v[220:223], v[158:161], 0
	v_mfma_f32_16x16x32_bf16 v[50:53], v[224:227], v[162:165], v[50:53]
	v_mfma_f32_16x16x32_bf16 v[34:37], v[220:223], v[166:169], 0
	v_mfma_f32_16x16x32_bf16 v[34:37], v[224:227], v[174:177], v[34:37]
	v_mfma_f32_16x16x32_bf16 v[18:21], v[220:223], v[178:181], 0
	v_mfma_f32_16x16x32_bf16 v[18:21], v[224:227], v[182:185], v[18:21]
	v_mfma_f32_16x16x32_bf16 v[2:5], v[220:223], v[204:207], 0
	v_mfma_f32_16x16x32_bf16 v[2:5], v[224:227], v[208:211], v[2:5]
	s_barrier
	s_add_i32 s10, 0, 0x18000
	ds_read_b128 v[142:145], v248 offset:32768
	ds_read_b128 v[146:149], v248 offset:33792
	ds_read_b128 v[150:153], v248 offset:34816
	ds_read_b128 v[154:157], v248 offset:35840
	s_add_u32 s4, s4, s92
	s_addc_u32 s5, s5, 0
	s_mov_b32 m0, s41
	ds_read_b128 v[158:161], v172 offset:32768
	ds_read_b128 v[162:165], v172 offset:33792
	ds_read_b128 v[166:169], v172 offset:34816
	ds_read_b128 v[174:177], v172 offset:35840
	ds_read_b128 v[178:181], v172 offset:36864
	ds_read_b128 v[182:185], v172 offset:37888
	ds_read_b128 v[204:207], v172 offset:38912
	ds_read_b128 v[208:211], v172 offset:39936
	global_load_lds_dwordx4 v130, s[4:5]
	s_mov_b32 m0, s42
	s_nop 0
	global_load_lds_dwordx4 v134, s[4:5]
	s_waitcnt lgkmcnt(8)
	s_barrier
	s_waitcnt lgkmcnt(0)
	v_mfma_f32_16x16x32_bf16 v[126:129], v[142:145], v[158:161], v[126:129]
	v_mfma_f32_16x16x32_bf16 v[126:129], v[146:149], v[162:165], v[126:129]
	v_mfma_f32_16x16x32_bf16 v[110:113], v[142:145], v[166:169], v[110:113]
	v_mfma_f32_16x16x32_bf16 v[110:113], v[146:149], v[174:177], v[110:113]
	v_mfma_f32_16x16x32_bf16 v[94:97], v[142:145], v[178:181], v[94:97]
	v_mfma_f32_16x16x32_bf16 v[94:97], v[146:149], v[182:185], v[94:97]
	v_mfma_f32_16x16x32_bf16 v[78:81], v[142:145], v[204:207], v[78:81]
	v_mfma_f32_16x16x32_bf16 v[78:81], v[146:149], v[208:211], v[78:81]
	v_mfma_f32_16x16x32_bf16 v[122:125], v[150:153], v[158:161], v[122:125]
	v_mfma_f32_16x16x32_bf16 v[122:125], v[154:157], v[162:165], v[122:125]
	v_mfma_f32_16x16x32_bf16 v[106:109], v[150:153], v[166:169], v[106:109]
	v_mfma_f32_16x16x32_bf16 v[106:109], v[154:157], v[174:177], v[106:109]
	v_mfma_f32_16x16x32_bf16 v[90:93], v[150:153], v[178:181], v[90:93]
	v_mfma_f32_16x16x32_bf16 v[90:93], v[154:157], v[182:185], v[90:93]
	v_mfma_f32_16x16x32_bf16 v[74:77], v[150:153], v[204:207], v[74:77]
	v_mfma_f32_16x16x32_bf16 v[74:77], v[154:157], v[208:211], v[74:77]
	s_barrier
	s_add_i32 s4, 0, 0x1c000
	s_add_i32 s5, s10, s34
	s_mov_b32 m0, s5
	ds_read_b128 v[212:215], v248 offset:49152
	ds_read_b128 v[216:219], v248 offset:50176
	ds_read_b128 v[220:223], v248 offset:51200
	ds_read_b128 v[224:227], v248 offset:52224
	global_load_lds_dwordx4 v132, s[78:79]
	s_add_i32 m0, s5, 0x2000
	s_nop 0
	global_load_lds_dwordx4 v136, s[78:79]
	s_barrier
	s_waitcnt lgkmcnt(0)
	v_mfma_f32_16x16x32_bf16 v[118:121], v[212:215], v[158:161], v[118:121]
	v_mfma_f32_16x16x32_bf16 v[118:121], v[216:219], v[162:165], v[118:121]
	v_mfma_f32_16x16x32_bf16 v[102:105], v[212:215], v[166:169], v[102:105]
	v_mfma_f32_16x16x32_bf16 v[102:105], v[216:219], v[174:177], v[102:105]
	v_mfma_f32_16x16x32_bf16 v[86:89], v[212:215], v[178:181], v[86:89]
	v_mfma_f32_16x16x32_bf16 v[86:89], v[216:219], v[182:185], v[86:89]
	v_mfma_f32_16x16x32_bf16 v[70:73], v[212:215], v[204:207], v[70:73]
	v_mfma_f32_16x16x32_bf16 v[70:73], v[216:219], v[208:211], v[70:73]
	v_mfma_f32_16x16x32_bf16 v[114:117], v[220:223], v[158:161], v[114:117]
	v_mfma_f32_16x16x32_bf16 v[114:117], v[224:227], v[162:165], v[114:117]
	v_mfma_f32_16x16x32_bf16 v[98:101], v[220:223], v[166:169], v[98:101]
	v_mfma_f32_16x16x32_bf16 v[98:101], v[224:227], v[174:177], v[98:101]
	v_mfma_f32_16x16x32_bf16 v[82:85], v[220:223], v[178:181], v[82:85]
	v_mfma_f32_16x16x32_bf16 v[82:85], v[224:227], v[182:185], v[82:85]
	v_mfma_f32_16x16x32_bf16 v[66:69], v[220:223], v[204:207], v[66:69]
	v_mfma_f32_16x16x32_bf16 v[66:69], v[224:227], v[208:211], v[66:69]
	s_barrier
	s_mov_b32 m0, s46
	ds_read_b128 v[158:161], v172 offset:49152
	ds_read_b128 v[162:165], v172 offset:50176
	ds_read_b128 v[166:169], v172 offset:51200
	ds_read_b128 v[174:177], v172 offset:52224
	ds_read_b128 v[178:181], v172 offset:53248
	ds_read_b128 v[182:185], v172 offset:54272
	ds_read_b128 v[204:207], v172 offset:55296
	ds_read_b128 v[208:211], v172 offset:56320
	global_load_lds_dwordx4 v130, s[80:81]
	s_mov_b32 m0, s47
	s_nop 0
	global_load_lds_dwordx4 v134, s[80:81]
	s_barrier
	s_waitcnt lgkmcnt(0)
	v_mfma_f32_16x16x32_bf16 v[62:65], v[142:145], v[158:161], v[62:65]
	v_mfma_f32_16x16x32_bf16 v[62:65], v[146:149], v[162:165], v[62:65]
	v_mfma_f32_16x16x32_bf16 v[46:49], v[142:145], v[166:169], v[46:49]
	v_mfma_f32_16x16x32_bf16 v[46:49], v[146:149], v[174:177], v[46:49]
	v_mfma_f32_16x16x32_bf16 v[30:33], v[142:145], v[178:181], v[30:33]
	v_mfma_f32_16x16x32_bf16 v[30:33], v[146:149], v[182:185], v[30:33]
	v_mfma_f32_16x16x32_bf16 v[14:17], v[142:145], v[204:207], v[14:17]
	v_mfma_f32_16x16x32_bf16 v[14:17], v[146:149], v[208:211], v[14:17]
	v_mfma_f32_16x16x32_bf16 v[58:61], v[150:153], v[158:161], v[58:61]
	v_mfma_f32_16x16x32_bf16 v[58:61], v[154:157], v[162:165], v[58:61]
	v_mfma_f32_16x16x32_bf16 v[42:45], v[150:153], v[166:169], v[42:45]
	v_mfma_f32_16x16x32_bf16 v[42:45], v[154:157], v[174:177], v[42:45]
	v_mfma_f32_16x16x32_bf16 v[26:29], v[150:153], v[178:181], v[26:29]
	v_mfma_f32_16x16x32_bf16 v[26:29], v[154:157], v[182:185], v[26:29]
	v_mfma_f32_16x16x32_bf16 v[10:13], v[150:153], v[204:207], v[10:13]
	v_mfma_f32_16x16x32_bf16 v[10:13], v[154:157], v[208:211], v[10:13]
	s_barrier
	s_add_i32 s4, s4, s34
	s_mov_b32 m0, s4
	s_nop 0
	global_load_lds_dwordx4 v132, s[58:59]
	s_add_i32 m0, s4, 0x2000
	s_nop 0
	global_load_lds_dwordx4 v136, s[58:59]
	s_add_u32 s0, s0, 0x100
	s_addc_u32 s1, s1, 0
	s_add_u32 s12, s12, 0x100
	s_addc_u32 s13, s13, 0
	s_cmp_ge_u32 s27, s43
	s_mov_b32 s4, s27
	s_waitcnt vmcnt(6)
	s_barrier
	v_mfma_f32_16x16x32_bf16 v[54:57], v[212:215], v[158:161], v[54:57]
	v_mfma_f32_16x16x32_bf16 v[54:57], v[216:219], v[162:165], v[54:57]
	v_mfma_f32_16x16x32_bf16 v[38:41], v[212:215], v[166:169], v[38:41]
	v_mfma_f32_16x16x32_bf16 v[38:41], v[216:219], v[174:177], v[38:41]
	v_mfma_f32_16x16x32_bf16 v[22:25], v[212:215], v[178:181], v[22:25]
	v_mfma_f32_16x16x32_bf16 v[22:25], v[216:219], v[182:185], v[22:25]
	v_mfma_f32_16x16x32_bf16 v[6:9], v[212:215], v[204:207], v[6:9]
	v_mfma_f32_16x16x32_bf16 v[6:9], v[216:219], v[208:211], v[6:9]
	v_mfma_f32_16x16x32_bf16 v[50:53], v[220:223], v[158:161], v[50:53]
	v_mfma_f32_16x16x32_bf16 v[50:53], v[224:227], v[162:165], v[50:53]
	v_mfma_f32_16x16x32_bf16 v[34:37], v[220:223], v[166:169], v[34:37]
	v_mfma_f32_16x16x32_bf16 v[34:37], v[224:227], v[174:177], v[34:37]
	v_mfma_f32_16x16x32_bf16 v[18:21], v[220:223], v[178:181], v[18:21]
	v_mfma_f32_16x16x32_bf16 v[18:21], v[224:227], v[182:185], v[18:21]
	v_mfma_f32_16x16x32_bf16 v[2:5], v[220:223], v[204:207], v[2:5]
	v_mfma_f32_16x16x32_bf16 v[2:5], v[224:227], v[208:211], v[2:5]
	s_barrier
	s_cbranch_scc1 .Lkexit_806
.LBB0_806:
	s_add_i32 s27, s4, 2
	s_add_u32 s10, s0, 0x80
	s_addc_u32 s5, s1, 0
	s_add_i32 s28, 0, 0x10000
	ds_read_b128 v[142:145], v248
	ds_read_b128 v[146:149], v248 offset:1024
	ds_read_b128 v[150:153], v248 offset:2048
	ds_read_b128 v[154:157], v248 offset:3072
	s_cmp_eq_u32 s48, s4
	s_cselect_b32 s4, s22, s10
	s_cselect_b32 s5, s23, s5
	s_cselect_b32 s11, s25, s13
	s_cselect_b32 s10, s24, s12
	s_add_i32 m0, s35, 0xc000
	ds_read_b128 v[158:161], v172
	ds_read_b128 v[162:165], v172 offset:1024
	ds_read_b128 v[166:169], v172 offset:2048
	ds_read_b128 v[174:177], v172 offset:3072
	ds_read_b128 v[178:181], v172 offset:4096
	ds_read_b128 v[182:185], v172 offset:5120
	ds_read_b128 v[204:207], v172 offset:6144
	ds_read_b128 v[208:211], v172 offset:7168
	global_load_lds_dwordx4 v138, s[0:1]
	s_add_i32 m0, s35, 0xe000
	s_nop 0
	global_load_lds_dwordx4 v140, s[0:1]
	s_waitcnt lgkmcnt(8)
	s_barrier
	s_waitcnt lgkmcnt(0)
	v_mfma_f32_16x16x32_bf16 v[126:129], v[142:145], v[158:161], v[126:129]
	v_mfma_f32_16x16x32_bf16 v[126:129], v[146:149], v[162:165], v[126:129]
	v_mfma_f32_16x16x32_bf16 v[110:113], v[142:145], v[166:169], v[110:113]
	v_mfma_f32_16x16x32_bf16 v[110:113], v[146:149], v[174:177], v[110:113]
	v_mfma_f32_16x16x32_bf16 v[94:97], v[142:145], v[178:181], v[94:97]
	v_mfma_f32_16x16x32_bf16 v[94:97], v[146:149], v[182:185], v[94:97]
	v_mfma_f32_16x16x32_bf16 v[78:81], v[142:145], v[204:207], v[78:81]
	v_mfma_f32_16x16x32_bf16 v[78:81], v[146:149], v[208:211], v[78:81]
	v_mfma_f32_16x16x32_bf16 v[122:125], v[150:153], v[158:161], v[122:125]
	v_mfma_f32_16x16x32_bf16 v[122:125], v[154:157], v[162:165], v[122:125]
	v_mfma_f32_16x16x32_bf16 v[106:109], v[150:153], v[166:169], v[106:109]
	v_mfma_f32_16x16x32_bf16 v[106:109], v[154:157], v[174:177], v[106:109]
	v_mfma_f32_16x16x32_bf16 v[90:93], v[150:153], v[178:181], v[90:93]
	v_mfma_f32_16x16x32_bf16 v[90:93], v[154:157], v[182:185], v[90:93]
	v_mfma_f32_16x16x32_bf16 v[74:77], v[150:153], v[204:207], v[74:77]
	v_mfma_f32_16x16x32_bf16 v[74:77], v[154:157], v[208:211], v[74:77]
	s_barrier
	s_add_i32 s29, 0, 0x14000
	s_add_i32 s28, s28, s34
	s_add_u32 s78, s10, s6
	s_addc_u32 s79, s11, s7
	s_mov_b32 m0, s28
	ds_read_b128 v[212:215], v248 offset:16384
	ds_read_b128 v[216:219], v248 offset:17408
	ds_read_b128 v[220:223], v248 offset:18432
	ds_read_b128 v[224:227], v248 offset:19456
	global_load_lds_dwordx4 v132, s[10:11]
	s_add_i32 m0, s28, 0x2000
	s_nop 0
	global_load_lds_dwordx4 v136, s[10:11]
	s_barrier
	s_waitcnt lgkmcnt(0)
	v_mfma_f32_16x16x32_bf16 v[118:121], v[212:215], v[158:161], v[118:121]
	v_mfma_f32_16x16x32_bf16 v[118:121], v[216:219], v[162:165], v[118:121]
	v_mfma_f32_16x16x32_bf16 v[102:105], v[212:215], v[166:169], v[102:105]
	v_mfma_f32_16x16x32_bf16 v[102:105], v[216:219], v[174:177], v[102:105]
	v_mfma_f32_16x16x32_bf16 v[86:89], v[212:215], v[178:181], v[86:89]
	v_mfma_f32_16x16x32_bf16 v[86:89], v[216:219], v[182:185], v[86:89]
	v_mfma_f32_16x16x32_bf16 v[70:73], v[212:215], v[204:207], v[70:73]
	v_mfma_f32_16x16x32_bf16 v[70:73], v[216:219], v[208:211], v[70:73]
	v_mfma_f32_16x16x32_bf16 v[114:117], v[220:223], v[158:161], v[114:117]
	v_mfma_f32_16x16x32_bf16 v[114:117], v[224:227], v[162:165], v[114:117]
	v_mfma_f32_16x16x32_bf16 v[98:101], v[220:223], v[166:169], v[98:101]
	v_mfma_f32_16x16x32_bf16 v[98:101], v[224:227], v[174:177], v[98:101]
	v_mfma_f32_16x16x32_bf16 v[82:85], v[220:223], v[178:181], v[82:85]
	v_mfma_f32_16x16x32_bf16 v[82:85], v[224:227], v[182:185], v[82:85]
	v_mfma_f32_16x16x32_bf16 v[66:69], v[220:223], v[204:207], v[66:69]
	v_mfma_f32_16x16x32_bf16 v[66:69], v[224:227], v[208:211], v[66:69]
	s_barrier
	s_mov_b32 m0, s35
	s_add_u32 s80, s4, s6
	s_addc_u32 s81, s5, s7
	ds_read_b128 v[158:161], v172 offset:16384
	ds_read_b128 v[162:165], v172 offset:17408
	ds_read_b128 v[166:169], v172 offset:18432
	ds_read_b128 v[174:177], v172 offset:19456
	ds_read_b128 v[178:181], v172 offset:20480
	ds_read_b128 v[182:185], v172 offset:21504
	ds_read_b128 v[204:207], v172 offset:22528
	ds_read_b128 v[208:211], v172 offset:23552
	global_load_lds_dwordx4 v130, s[4:5]
	s_mov_b32 m0, s40
	s_nop 0
	global_load_lds_dwordx4 v134, s[4:5]
	s_barrier
	s_waitcnt lgkmcnt(0)
	v_mfma_f32_16x16x32_bf16 v[62:65], v[142:145], v[158:161], v[62:65]
	v_mfma_f32_16x16x32_bf16 v[62:65], v[146:149], v[162:165], v[62:65]
	v_mfma_f32_16x16x32_bf16 v[46:49], v[142:145], v[166:169], v[46:49]
	v_mfma_f32_16x16x32_bf16 v[46:49], v[146:149], v[174:177], v[46:49]
	v_mfma_f32_16x16x32_bf16 v[30:33], v[142:145], v[178:181], v[30:33]
	v_mfma_f32_16x16x32_bf16 v[30:33], v[146:149], v[182:185], v[30:33]
	v_mfma_f32_16x16x32_bf16 v[14:17], v[142:145], v[204:207], v[14:17]
	v_mfma_f32_16x16x32_bf16 v[14:17], v[146:149], v[208:211], v[14:17]
	v_mfma_f32_16x16x32_bf16 v[58:61], v[150:153], v[158:161], v[58:61]
	v_mfma_f32_16x16x32_bf16 v[58:61], v[154:157], v[162:165], v[58:61]
	v_mfma_f32_16x16x32_bf16 v[42:45], v[150:153], v[166:169], v[42:45]
	v_mfma_f32_16x16x32_bf16 v[42:45], v[154:157], v[174:177], v[42:45]
	v_mfma_f32_16x16x32_bf16 v[26:29], v[150:153], v[178:181], v[26:29]
	v_mfma_f32_16x16x32_bf16 v[26:29], v[154:157], v[182:185], v[26:29]
	v_mfma_f32_16x16x32_bf16 v[10:13], v[150:153], v[204:207], v[10:13]
	v_mfma_f32_16x16x32_bf16 v[10:13], v[154:157], v[208:211], v[10:13]
	s_barrier
	s_add_u32 s10, s10, s92
	s_addc_u32 s11, s11, 0
	s_add_i32 s28, s29, s34
	s_add_u32 s58, s10, s6
	s_addc_u32 s59, s11, s7
	s_mov_b32 m0, s28
	s_nop 0
	global_load_lds_dwordx4 v132, s[10:11]
	s_add_i32 m0, s28, 0x2000
	s_nop 0
	global_load_lds_dwordx4 v136, s[10:11]
	s_waitcnt vmcnt(6)
	s_barrier
	v_mfma_f32_16x16x32_bf16 v[54:57], v[212:215], v[158:161], v[54:57]
	v_mfma_f32_16x16x32_bf16 v[54:57], v[216:219], v[162:165], v[54:57]
	v_mfma_f32_16x16x32_bf16 v[38:41], v[212:215], v[166:169], v[38:41]
	v_mfma_f32_16x16x32_bf16 v[38:41], v[216:219], v[174:177], v[38:41]
	v_mfma_f32_16x16x32_bf16 v[22:25], v[212:215], v[178:181], v[22:25]
	v_mfma_f32_16x16x32_bf16 v[22:25], v[216:219], v[182:185], v[22:25]
	v_mfma_f32_16x16x32_bf16 v[6:9], v[212:215], v[204:207], v[6:9]
	v_mfma_f32_16x16x32_bf16 v[6:9], v[216:219], v[208:211], v[6:9]
	v_mfma_f32_16x16x32_bf16 v[50:53], v[220:223], v[158:161], v[50:53]
	v_mfma_f32_16x16x32_bf16 v[50:53], v[224:227], v[162:165], v[50:53]
	v_mfma_f32_16x16x32_bf16 v[34:37], v[220:223], v[166:169], v[34:37]
	v_mfma_f32_16x16x32_bf16 v[34:37], v[224:227], v[174:177], v[34:37]
	v_mfma_f32_16x16x32_bf16 v[18:21], v[220:223], v[178:181], v[18:21]
	v_mfma_f32_16x16x32_bf16 v[18:21], v[224:227], v[182:185], v[18:21]
	v_mfma_f32_16x16x32_bf16 v[2:5], v[220:223], v[204:207], v[2:5]
	v_mfma_f32_16x16x32_bf16 v[2:5], v[224:227], v[208:211], v[2:5]
	s_barrier
	s_add_i32 s10, 0, 0x18000
	ds_read_b128 v[142:145], v248 offset:32768
	ds_read_b128 v[146:149], v248 offset:33792
	ds_read_b128 v[150:153], v248 offset:34816
	ds_read_b128 v[154:157], v248 offset:35840
	s_add_u32 s4, s4, s92
	s_addc_u32 s5, s5, 0
	s_mov_b32 m0, s41
	ds_read_b128 v[158:161], v172 offset:32768
	ds_read_b128 v[162:165], v172 offset:33792
	ds_read_b128 v[166:169], v172 offset:34816
	ds_read_b128 v[174:177], v172 offset:35840
	ds_read_b128 v[178:181], v172 offset:36864
	ds_read_b128 v[182:185], v172 offset:37888
	ds_read_b128 v[204:207], v172 offset:38912
	ds_read_b128 v[208:211], v172 offset:39936
	global_load_lds_dwordx4 v130, s[4:5]
	s_mov_b32 m0, s42
	s_nop 0
	global_load_lds_dwordx4 v134, s[4:5]
	s_waitcnt lgkmcnt(8)
	s_barrier
	s_waitcnt lgkmcnt(0)
	v_mfma_f32_16x16x32_bf16 v[126:129], v[142:145], v[158:161], v[126:129]
	v_mfma_f32_16x16x32_bf16 v[126:129], v[146:149], v[162:165], v[126:129]
	v_mfma_f32_16x16x32_bf16 v[110:113], v[142:145], v[166:169], v[110:113]
	v_mfma_f32_16x16x32_bf16 v[110:113], v[146:149], v[174:177], v[110:113]
	v_mfma_f32_16x16x32_bf16 v[94:97], v[142:145], v[178:181], v[94:97]
	v_mfma_f32_16x16x32_bf16 v[94:97], v[146:149], v[182:185], v[94:97]
	v_mfma_f32_16x16x32_bf16 v[78:81], v[142:145], v[204:207], v[78:81]
	v_mfma_f32_16x16x32_bf16 v[78:81], v[146:149], v[208:211], v[78:81]
	v_mfma_f32_16x16x32_bf16 v[122:125], v[150:153], v[158:161], v[122:125]
	v_mfma_f32_16x16x32_bf16 v[122:125], v[154:157], v[162:165], v[122:125]
	v_mfma_f32_16x16x32_bf16 v[106:109], v[150:153], v[166:169], v[106:109]
	v_mfma_f32_16x16x32_bf16 v[106:109], v[154:157], v[174:177], v[106:109]
	v_mfma_f32_16x16x32_bf16 v[90:93], v[150:153], v[178:181], v[90:93]
	v_mfma_f32_16x16x32_bf16 v[90:93], v[154:157], v[182:185], v[90:93]
	v_mfma_f32_16x16x32_bf16 v[74:77], v[150:153], v[204:207], v[74:77]
	v_mfma_f32_16x16x32_bf16 v[74:77], v[154:157], v[208:211], v[74:77]
	s_barrier
	s_add_i32 s4, 0, 0x1c000
	s_add_i32 s5, s10, s34
	s_mov_b32 m0, s5
	ds_read_b128 v[212:215], v248 offset:49152
	ds_read_b128 v[216:219], v248 offset:50176
	ds_read_b128 v[220:223], v248 offset:51200
	ds_read_b128 v[224:227], v248 offset:52224
	global_load_lds_dwordx4 v132, s[78:79]
	s_add_i32 m0, s5, 0x2000
	s_nop 0
	global_load_lds_dwordx4 v136, s[78:79]
	s_barrier
	s_waitcnt lgkmcnt(0)
	v_mfma_f32_16x16x32_bf16 v[118:121], v[212:215], v[158:161], v[118:121]
	v_mfma_f32_16x16x32_bf16 v[118:121], v[216:219], v[162:165], v[118:121]
	v_mfma_f32_16x16x32_bf16 v[102:105], v[212:215], v[166:169], v[102:105]
	v_mfma_f32_16x16x32_bf16 v[102:105], v[216:219], v[174:177], v[102:105]
	v_mfma_f32_16x16x32_bf16 v[86:89], v[212:215], v[178:181], v[86:89]
	v_mfma_f32_16x16x32_bf16 v[86:89], v[216:219], v[182:185], v[86:89]
	v_mfma_f32_16x16x32_bf16 v[70:73], v[212:215], v[204:207], v[70:73]
	v_mfma_f32_16x16x32_bf16 v[70:73], v[216:219], v[208:211], v[70:73]
	v_mfma_f32_16x16x32_bf16 v[114:117], v[220:223], v[158:161], v[114:117]
	v_mfma_f32_16x16x32_bf16 v[114:117], v[224:227], v[162:165], v[114:117]
	v_mfma_f32_16x16x32_bf16 v[98:101], v[220:223], v[166:169], v[98:101]
	v_mfma_f32_16x16x32_bf16 v[98:101], v[224:227], v[174:177], v[98:101]
	v_mfma_f32_16x16x32_bf16 v[82:85], v[220:223], v[178:181], v[82:85]
	v_mfma_f32_16x16x32_bf16 v[82:85], v[224:227], v[182:185], v[82:85]
	v_mfma_f32_16x16x32_bf16 v[66:69], v[220:223], v[204:207], v[66:69]
	v_mfma_f32_16x16x32_bf16 v[66:69], v[224:227], v[208:211], v[66:69]
	s_barrier
	s_mov_b32 m0, s46
	ds_read_b128 v[158:161], v172 offset:49152
	ds_read_b128 v[162:165], v172 offset:50176
	ds_read_b128 v[166:169], v172 offset:51200
	ds_read_b128 v[174:177], v172 offset:52224
	ds_read_b128 v[178:181], v172 offset:53248
	ds_read_b128 v[182:185], v172 offset:54272
	ds_read_b128 v[204:207], v172 offset:55296
	ds_read_b128 v[208:211], v172 offset:56320
	global_load_lds_dwordx4 v130, s[80:81]
	s_mov_b32 m0, s47
	s_nop 0
	global_load_lds_dwordx4 v134, s[80:81]
	s_barrier
	s_waitcnt lgkmcnt(0)
	v_mfma_f32_16x16x32_bf16 v[62:65], v[142:145], v[158:161], v[62:65]
	v_mfma_f32_16x16x32_bf16 v[62:65], v[146:149], v[162:165], v[62:65]
	v_mfma_f32_16x16x32_bf16 v[46:49], v[142:145], v[166:169], v[46:49]
	v_mfma_f32_16x16x32_bf16 v[46:49], v[146:149], v[174:177], v[46:49]
	v_mfma_f32_16x16x32_bf16 v[30:33], v[142:145], v[178:181], v[30:33]
	v_mfma_f32_16x16x32_bf16 v[30:33], v[146:149], v[182:185], v[30:33]
	v_mfma_f32_16x16x32_bf16 v[14:17], v[142:145], v[204:207], v[14:17]
	v_mfma_f32_16x16x32_bf16 v[14:17], v[146:149], v[208:211], v[14:17]
	v_mfma_f32_16x16x32_bf16 v[58:61], v[150:153], v[158:161], v[58:61]
	v_mfma_f32_16x16x32_bf16 v[58:61], v[154:157], v[162:165], v[58:61]
	v_mfma_f32_16x16x32_bf16 v[42:45], v[150:153], v[166:169], v[42:45]
	v_mfma_f32_16x16x32_bf16 v[42:45], v[154:157], v[174:177], v[42:45]
	v_mfma_f32_16x16x32_bf16 v[26:29], v[150:153], v[178:181], v[26:29]
	v_mfma_f32_16x16x32_bf16 v[26:29], v[154:157], v[182:185], v[26:29]
	v_mfma_f32_16x16x32_bf16 v[10:13], v[150:153], v[204:207], v[10:13]
	v_mfma_f32_16x16x32_bf16 v[10:13], v[154:157], v[208:211], v[10:13]
	s_barrier
	s_add_i32 s4, s4, s34
	s_mov_b32 m0, s4
	s_nop 0
	global_load_lds_dwordx4 v132, s[58:59]
	s_add_i32 m0, s4, 0x2000
	s_nop 0
	global_load_lds_dwordx4 v136, s[58:59]
	s_add_u32 s0, s0, 0x100
	s_addc_u32 s1, s1, 0
	s_add_u32 s12, s12, 0x100
	s_addc_u32 s13, s13, 0
	s_cmp_ge_u32 s27, s43
	s_mov_b32 s4, s27
	s_waitcnt vmcnt(6)
	s_barrier
	v_mfma_f32_16x16x32_bf16 v[54:57], v[212:215], v[158:161], v[54:57]
	v_mfma_f32_16x16x32_bf16 v[54:57], v[216:219], v[162:165], v[54:57]
	v_mfma_f32_16x16x32_bf16 v[38:41], v[212:215], v[166:169], v[38:41]
	v_mfma_f32_16x16x32_bf16 v[38:41], v[216:219], v[174:177], v[38:41]
	v_mfma_f32_16x16x32_bf16 v[22:25], v[212:215], v[178:181], v[22:25]
	v_mfma_f32_16x16x32_bf16 v[22:25], v[216:219], v[182:185], v[22:25]
	v_mfma_f32_16x16x32_bf16 v[6:9], v[212:215], v[204:207], v[6:9]
	v_mfma_f32_16x16x32_bf16 v[6:9], v[216:219], v[208:211], v[6:9]
	v_mfma_f32_16x16x32_bf16 v[50:53], v[220:223], v[158:161], v[50:53]
	v_mfma_f32_16x16x32_bf16 v[50:53], v[224:227], v[162:165], v[50:53]
	v_mfma_f32_16x16x32_bf16 v[34:37], v[220:223], v[166:169], v[34:37]
	v_mfma_f32_16x16x32_bf16 v[34:37], v[224:227], v[174:177], v[34:37]
	v_mfma_f32_16x16x32_bf16 v[18:21], v[220:223], v[178:181], v[18:21]
	v_mfma_f32_16x16x32_bf16 v[18:21], v[224:227], v[182:185], v[18:21]
	v_mfma_f32_16x16x32_bf16 v[2:5], v[220:223], v[204:207], v[2:5]
	v_mfma_f32_16x16x32_bf16 v[2:5], v[224:227], v[208:211], v[2:5]
	s_barrier
	s_cbranch_scc0 .LBB0_806
